# v7 + LDS-DMA loads hoisted ahead of the ds_read burst in every load segment; loop heads at baseline alignment
# baseline (speedup 1.0000x reference)
; #define PG8_STAGE(bufoff, gbase, voff) do { _Pragma("unroll") for (int _i = 0; _i < 2; ++_i) \
;         __builtin_amdgcn_global_load_lds((const unsigned*)((const char*)(gbase) + (voff)[_i]), (LAS unsigned*)(lds + (bufoff) + ldsw + _i * 8192), 16, 0, 0); } while (0)
; #define PG8_LDA(dst, b, h) do { _Pragma("unroll") for (int m = 0; m < 4; ++m) _Pragma("unroll") for (int k = 0; k < 2; ++k) dst[m][k] = *(const LAS bf16x8*)(lds + PG8_SA(b, h) + aoff + m * 2048 + k * 1024); } while (0)
; #define PG8_LDB(dst, b, h) do { _Pragma("unroll") for (int n = 0; n < 2; ++n) _Pragma("unroll") for (int k = 0; k < 2; ++k) dst[n][k] = *(const LAS bf16x8*)(lds + PG8_SB(b, h) + boff + n * 2048 + k * 1024); } while (0)
; #define PG8_MMA(ai, bj, At, Bt) do { __builtin_amdgcn_s_setprio(1); _Pragma("unroll") for (int m = 0; m < 4; ++m) _Pragma("unroll") for (int n = 0; n < 2; ++n) _Pragma("unroll") for (int k = 0; k < 2; ++k) \
;         acc[ai][bj][m][n] = __builtin_amdgcn_mfma_f32_16x16x32_bf16(Bt[n][k], At[m][k], acc[ai][bj][m][n], 0, 0, 0); __builtin_amdgcn_s_setprio(0); } while (0)
; #define PG8_WAIT_L(n) asm volatile("s_waitcnt lgkmcnt(" #n ")" ::: "memory")
; #define PG8_BAR __builtin_amdgcn_s_barrier()
; #define PG8_SCHED __builtin_amdgcn_sched_barrier(0)
; template <class Epi, class Ptrs>
; __device__ __forceinline__ void gemm_phase(LAS unsigned char* lds, const int K, const StaticOrder& S, const Ptrs& P, const Epi& E) {
;     ...
;         for (int t = 0; t < nt; t += 2) {
;             const bool last = (t == nt - 2);
;             const char* a1 = cA + (size_t)(t + 1) * kstep;
;             const char* a2 = last ? nA : cA + (size_t)(t + 2) * kstep; const char* b2 = last ? nB : cB + (size_t)(t + 2) * kstep;
;             const char* a3 = a2 + kstep; const char* b3 = b2 + kstep;
;             PG8_LDB(B0, 0, 0); PG8_SCHED; PG8_LDA(At, 0, 0); PG8_STAGE(PG8_SA(1, 1), a1 + hstep, voffA);
;             PG8_WAIT_L(8); PG8_BAR; PG8_WAIT_L(0); PG8_MMA(0, 0, At, B0); PG8_BAR; PG8_SCHED;
;     ...
; #pragma unroll
;         for (int a = 0; a < 2; ++a)
; #pragma unroll
;             for (int b = 0; b < 2; ++b)
; #pragma unroll
;                 for (int m = 0; m < 4; ++m)
; #pragma unroll
;                     for (int n = 0; n < 2; ++n) acc[a][b][m][n] = (f32x4){0.f, 0.f, 0.f, 0.f};
.LBB0_126:
	s_add_u32 s6, s6, 0x40080
	s_nop 0
	s_nop 0
	s_nop 0
	s_nop 0
	s_nop 0
	s_nop 0
	s_nop 0
	s_nop 0
	s_nop 0
	s_nop 0
	s_nop 0
	s_nop 0
	s_nop 0
	s_nop 0
	s_nop 0
	s_nop 0
	s_nop 0
	s_nop 0
	s_nop 0
	s_nop 0
	s_nop 0
	s_nop 0
	s_nop 0
	s_nop 0
	s_nop 0
	s_nop 0
	s_nop 0
	s_nop 0
	s_nop 0
	s_nop 0
	s_nop 0
	s_nop 0
	s_nop 0
	s_nop 0
	s_nop 0
	s_nop 0
	s_nop 0
	s_nop 0
	s_nop 0
	s_nop 0
	s_nop 0
	s_nop 0
	s_nop 0
	s_nop 0
	s_nop 0
	s_nop 0
	s_nop 0
	s_nop 0
	s_nop 0
	s_nop 0
	s_nop 0
	s_nop 0
	s_nop 0
	s_nop 0
	s_nop 0
	s_nop 0
	s_nop 0
	s_nop 0
	s_nop 0
	s_nop 0
	s_addc_u32 s7, s7, 0
	s_add_u32 s20, s78, 0x100
	v_mov_b32_e32 v0, 0
	s_addc_u32 s25, s79, 0
	s_mov_b32 s63, -2
	v_mov_b32_e32 v1, v0
	v_mov_b32_e32 v2, v0
	v_mov_b32_e32 v3, v0
	v_mov_b32_e32 v12, v0
	v_mov_b32_e32 v13, v0
	v_mov_b32_e32 v14, v0
	v_mov_b32_e32 v15, v0
	v_mov_b32_e32 v16, v0
	v_mov_b32_e32 v17, v0
	v_mov_b32_e32 v18, v0
	v_mov_b32_e32 v19, v0
	v_mov_b32_e32 v28, v0
	v_mov_b32_e32 v29, v0
	v_mov_b32_e32 v30, v0
	v_mov_b32_e32 v31, v0
	v_mov_b32_e32 v32, v0
	v_mov_b32_e32 v33, v0
	v_mov_b32_e32 v34, v0
	v_mov_b32_e32 v35, v0
	v_mov_b32_e32 v44, v0
	v_mov_b32_e32 v45, v0
	v_mov_b32_e32 v46, v0
	v_mov_b32_e32 v47, v0
	v_mov_b32_e32 v48, v0
	v_mov_b32_e32 v49, v0
	v_mov_b32_e32 v50, v0
	v_mov_b32_e32 v51, v0
	v_mov_b32_e32 v60, v0
	v_mov_b32_e32 v61, v0
	v_mov_b32_e32 v62, v0
	v_mov_b32_e32 v63, v0
	v_mov_b32_e32 v4, v0
	v_mov_b32_e32 v5, v0
	v_mov_b32_e32 v6, v0
	v_mov_b32_e32 v7, v0
	v_mov_b32_e32 v8, v0
	v_mov_b32_e32 v9, v0
	v_mov_b32_e32 v10, v0
	v_mov_b32_e32 v11, v0
	v_mov_b32_e32 v20, v0
	v_mov_b32_e32 v21, v0
	v_mov_b32_e32 v22, v0
	v_mov_b32_e32 v23, v0
	v_mov_b32_e32 v24, v0
	v_mov_b32_e32 v25, v0
	v_mov_b32_e32 v26, v0
	v_mov_b32_e32 v27, v0
	v_mov_b32_e32 v36, v0
	v_mov_b32_e32 v37, v0
	v_mov_b32_e32 v38, v0
	v_mov_b32_e32 v39, v0
	v_mov_b32_e32 v40, v0
	v_mov_b32_e32 v41, v0
	v_mov_b32_e32 v42, v0
	v_mov_b32_e32 v43, v0
	v_mov_b32_e32 v52, v0
	v_mov_b32_e32 v53, v0
	v_mov_b32_e32 v54, v0
	v_mov_b32_e32 v55, v0
	v_mov_b32_e32 v56, v0
	v_mov_b32_e32 v57, v0
	v_mov_b32_e32 v58, v0
	v_mov_b32_e32 v59, v0
	v_mov_b32_e32 v64, v0
	v_mov_b32_e32 v65, v0
	v_mov_b32_e32 v66, v0
	v_mov_b32_e32 v67, v0
	v_mov_b32_e32 v76, v0
	v_mov_b32_e32 v77, v0
	v_mov_b32_e32 v78, v0
	v_mov_b32_e32 v79, v0
	v_mov_b32_e32 v80, v0
	v_mov_b32_e32 v81, v0
	v_mov_b32_e32 v82, v0
	v_mov_b32_e32 v83, v0
	v_mov_b32_e32 v92, v0
	v_mov_b32_e32 v93, v0
	v_mov_b32_e32 v94, v0
	v_mov_b32_e32 v95, v0
	v_mov_b32_e32 v96, v0
	v_mov_b32_e32 v97, v0
	v_mov_b32_e32 v98, v0
	v_mov_b32_e32 v99, v0
	v_mov_b32_e32 v108, v0
	v_mov_b32_e32 v109, v0
	v_mov_b32_e32 v110, v0
	v_mov_b32_e32 v111, v0
	v_mov_b32_e32 v112, v0
	v_mov_b32_e32 v113, v0
	v_mov_b32_e32 v114, v0
	v_mov_b32_e32 v115, v0
	v_mov_b32_e32 v124, v0
	v_mov_b32_e32 v125, v0
	v_mov_b32_e32 v126, v0
	v_mov_b32_e32 v127, v0
	v_mov_b32_e32 v68, v0
	v_mov_b32_e32 v69, v0
	v_mov_b32_e32 v70, v0
	v_mov_b32_e32 v71, v0
	v_mov_b32_e32 v72, v0
	v_mov_b32_e32 v73, v0
	v_mov_b32_e32 v74, v0
	v_mov_b32_e32 v75, v0
	v_mov_b32_e32 v84, v0
	v_mov_b32_e32 v85, v0
	v_mov_b32_e32 v86, v0
	v_mov_b32_e32 v87, v0
	v_mov_b32_e32 v88, v0
	v_mov_b32_e32 v89, v0
	v_mov_b32_e32 v90, v0
	v_mov_b32_e32 v91, v0
	v_mov_b32_e32 v100, v0
	v_mov_b32_e32 v101, v0
	v_mov_b32_e32 v102, v0
	v_mov_b32_e32 v103, v0
	v_mov_b32_e32 v104, v0
	v_mov_b32_e32 v105, v0
	v_mov_b32_e32 v106, v0
	v_mov_b32_e32 v107, v0
	v_mov_b32_e32 v116, v0
	v_mov_b32_e32 v117, v0
	v_mov_b32_e32 v118, v0
	v_mov_b32_e32 v119, v0
	v_mov_b32_e32 v120, v0
	v_mov_b32_e32 v121, v0
	v_mov_b32_e32 v122, v0
	v_add_u32_e32 v252, 0x18000, v131
	v_add_u32_e32 v253, 0x1c000, v131
	v_mov_b32_e32 v123, v0
.LBB0_127:
	s_add_u32 s69, s6, 0xfffc0080
	s_addc_u32 s71, s7, -1
	s_cmp_eq_u32 s63, 12
	s_cselect_b32 s81, s1, s71
	s_cselect_b32 s80, s0, s69
	s_cselect_b32 s79, s73, s25
	s_cselect_b32 s78, s72, s20
	s_add_i32 m0, s67, 0xc000
	s_nop 0
	global_load_lds_dwordx4 v142, s[6:7]
	s_add_i32 m0, s67, 0xe000
	s_nop 0
	global_load_lds_dwordx4 v144, s[6:7]
	ds_read_b128 v[150:153], v205
	ds_read_b128 v[154:157], v205 offset:1024
	ds_read_b128 v[158:161], v205 offset:2048
	ds_read_b128 v[162:165], v205 offset:3072
	ds_read_b128 v[166:169], v206
	ds_read_b128 v[170:173], v206 offset:1024
	ds_read_b128 v[174:177], v206 offset:2048
	ds_read_b128 v[178:181], v206 offset:3072
	ds_read_b128 v[182:185], v206 offset:4096
	ds_read_b128 v[186:189], v206 offset:5120
	ds_read_b128 v[190:193], v206 offset:6144
	ds_read_b128 v[194:197], v206 offset:7168
	s_waitcnt lgkmcnt(8)
	s_barrier
	s_waitcnt lgkmcnt(0)
	s_setprio 1
	s_waitcnt lgkmcnt(0)
	v_mfma_f32_16x16x32_bf16 v[120:123], v[150:153], v[166:169], v[120:123]
	v_mfma_f32_16x16x32_bf16 v[120:123], v[154:157], v[170:173], v[120:123]
	v_mfma_f32_16x16x32_bf16 v[116:119], v[162:165], v[170:173], v[116:119]
	v_mfma_f32_16x16x32_bf16 v[116:119], v[158:161], v[166:169], v[116:119]
	v_mfma_f32_16x16x32_bf16 v[100:103], v[158:161], v[174:177], v[100:103]
	v_mfma_f32_16x16x32_bf16 v[100:103], v[162:165], v[178:181], v[100:103]
	v_mfma_f32_16x16x32_bf16 v[104:107], v[154:157], v[178:181], v[104:107]
	v_mfma_f32_16x16x32_bf16 v[104:107], v[150:153], v[174:177], v[104:107]
	v_mfma_f32_16x16x32_bf16 v[88:91], v[150:153], v[182:185], v[88:91]
	v_mfma_f32_16x16x32_bf16 v[88:91], v[154:157], v[186:189], v[88:91]
	v_mfma_f32_16x16x32_bf16 v[84:87], v[162:165], v[186:189], v[84:87]
	v_mfma_f32_16x16x32_bf16 v[84:87], v[158:161], v[182:185], v[84:87]
	v_mfma_f32_16x16x32_bf16 v[68:71], v[158:161], v[190:193], v[68:71]
	v_mfma_f32_16x16x32_bf16 v[68:71], v[162:165], v[194:197], v[68:71]
	v_mfma_f32_16x16x32_bf16 v[72:75], v[154:157], v[194:197], v[72:75]
	v_mfma_f32_16x16x32_bf16 v[72:75], v[150:153], v[190:193], v[72:75]
	s_setprio 0
	s_barrier
; #define PG8_STAGE(bufoff, gbase, voff) do { _Pragma("unroll") for (int _i = 0; _i < 2; ++_i) \
;         __builtin_amdgcn_global_load_lds((const unsigned*)((const char*)(gbase) + (voff)[_i]), (LAS unsigned*)(lds + (bufoff) + ldsw + _i * 8192), 16, 0, 0); } while (0)
; #define PG8_LDA(dst, b, h) do { _Pragma("unroll") for (int m = 0; m < 4; ++m) _Pragma("unroll") for (int k = 0; k < 2; ++k) dst[m][k] = *(const LAS bf16x8*)(lds + PG8_SA(b, h) + aoff + m * 2048 + k * 1024); } while (0)
; #define PG8_LDB(dst, b, h) do { _Pragma("unroll") for (int n = 0; n < 2; ++n) _Pragma("unroll") for (int k = 0; k < 2; ++k) dst[n][k] = *(const LAS bf16x8*)(lds + PG8_SB(b, h) + boff + n * 2048 + k * 1024); } while (0)
; #define PG8_MMA(ai, bj, At, Bt) do { __builtin_amdgcn_s_setprio(1); _Pragma("unroll") for (int m = 0; m < 4; ++m) _Pragma("unroll") for (int n = 0; n < 2; ++n) _Pragma("unroll") for (int k = 0; k < 2; ++k) \
;         acc[ai][bj][m][n] = __builtin_amdgcn_mfma_f32_16x16x32_bf16(Bt[n][k], At[m][k], acc[ai][bj][m][n], 0, 0, 0); __builtin_amdgcn_s_setprio(0); } while (0)
; #define PG8_WAIT_V(n) asm volatile("s_waitcnt vmcnt(" #n ")" ::: "memory")
; #define PG8_WAIT_L(n) asm volatile("s_waitcnt lgkmcnt(" #n ")" ::: "memory")
; #define PG8_BAR __builtin_amdgcn_s_barrier()
; #define PG8_SCHED __builtin_amdgcn_sched_barrier(0)
; template <class Epi, class Ptrs>
; __device__ __forceinline__ void gemm_phase(LAS unsigned char* lds, const int K, const StaticOrder& S, const Ptrs& P, const Epi& E) {
;     ...
;             PG8_LDB(B1, 0, 1); PG8_STAGE(PG8_SB(0, 0), b2, voffB);
;             PG8_BAR; PG8_WAIT_L(0); PG8_MMA(0, 1, At, B1); PG8_BAR;
;             PG8_LDA(At, 0, 1); PG8_STAGE(PG8_SA(0, 0), a2, voffA);
;             PG8_BAR; PG8_WAIT_L(0); PG8_MMA(1, 0, At, B0); PG8_BAR; PG8_SCHED;
;             PG8_STAGE(PG8_SB(0, 1), b2 + hstep, voffB);
;             PG8_WAIT_V(6); PG8_BAR; PG8_MMA(1, 1, At, B1); PG8_BAR;
;             PG8_LDB(B0, 1, 0); PG8_SCHED; PG8_LDA(At, 1, 0); PG8_STAGE(PG8_SA(0, 1), a2 + hstep, voffA);
	s_add_i32 s69, s91, s65
	s_add_u32 s100, s78, 0x80
	s_addc_u32 s101, s79, 0
	s_mov_b32 m0, s69
	s_nop 0
	global_load_lds_dwordx4 v134, s[78:79]
	s_add_i32 m0, s69, 0x2000
	s_nop 0
	global_load_lds_dwordx4 v138, s[78:79]
	ds_read_b128 v[198:201], v207
	ds_read_b128 v[210:213], v207 offset:1024
	ds_read_b128 v[214:217], v207 offset:2048
	ds_read_b128 v[218:221], v207 offset:3072
	s_barrier
	s_waitcnt lgkmcnt(0)
	s_setprio 1
	s_waitcnt lgkmcnt(0)
	v_mfma_f32_16x16x32_bf16 v[124:127], v[198:201], v[166:169], v[124:127]
	v_mfma_f32_16x16x32_bf16 v[124:127], v[210:213], v[170:173], v[124:127]
	v_mfma_f32_16x16x32_bf16 v[112:115], v[218:221], v[170:173], v[112:115]
	v_mfma_f32_16x16x32_bf16 v[112:115], v[214:217], v[166:169], v[112:115]
	v_mfma_f32_16x16x32_bf16 v[96:99], v[214:217], v[174:177], v[96:99]
	v_mfma_f32_16x16x32_bf16 v[96:99], v[218:221], v[178:181], v[96:99]
	v_mfma_f32_16x16x32_bf16 v[108:111], v[210:213], v[178:181], v[108:111]
	v_mfma_f32_16x16x32_bf16 v[108:111], v[198:201], v[174:177], v[108:111]
	v_mfma_f32_16x16x32_bf16 v[92:95], v[198:201], v[182:185], v[92:95]
	v_mfma_f32_16x16x32_bf16 v[92:95], v[210:213], v[186:189], v[92:95]
	v_mfma_f32_16x16x32_bf16 v[80:83], v[218:221], v[186:189], v[80:83]
	v_mfma_f32_16x16x32_bf16 v[80:83], v[214:217], v[182:185], v[80:83]
	v_mfma_f32_16x16x32_bf16 v[64:67], v[214:217], v[190:193], v[64:67]
	v_mfma_f32_16x16x32_bf16 v[64:67], v[218:221], v[194:197], v[64:67]
	v_mfma_f32_16x16x32_bf16 v[76:79], v[210:213], v[194:197], v[76:79]
	v_mfma_f32_16x16x32_bf16 v[76:79], v[198:201], v[190:193], v[76:79]
	s_setprio 0
	s_mov_b32 m0, s67
	s_barrier
	global_load_lds_dwordx4 v132, s[80:81]
	s_mov_b32 m0, s75
	s_nop 0
	global_load_lds_dwordx4 v136, s[80:81]
	ds_read_b128 v[166:169], v206 offset:16384
	ds_read_b128 v[170:173], v206 offset:17408
	ds_read_b128 v[174:177], v206 offset:18432
	ds_read_b128 v[178:181], v206 offset:19456
	ds_read_b128 v[182:185], v206 offset:20480
	ds_read_b128 v[186:189], v206 offset:21504
	ds_read_b128 v[190:193], v206 offset:22528
	ds_read_b128 v[194:197], v206 offset:23552
	s_barrier
	s_waitcnt lgkmcnt(0)
	s_setprio 1
	s_waitcnt lgkmcnt(0)
	v_mfma_f32_16x16x32_bf16 v[56:59], v[150:153], v[166:169], v[56:59]
	v_mfma_f32_16x16x32_bf16 v[56:59], v[154:157], v[170:173], v[56:59]
	v_mfma_f32_16x16x32_bf16 v[52:55], v[162:165], v[170:173], v[52:55]
	v_mfma_f32_16x16x32_bf16 v[52:55], v[158:161], v[166:169], v[52:55]
	v_mfma_f32_16x16x32_bf16 v[36:39], v[158:161], v[174:177], v[36:39]
	v_mfma_f32_16x16x32_bf16 v[36:39], v[162:165], v[178:181], v[36:39]
	v_mfma_f32_16x16x32_bf16 v[40:43], v[154:157], v[178:181], v[40:43]
	v_mfma_f32_16x16x32_bf16 v[40:43], v[150:153], v[174:177], v[40:43]
	v_mfma_f32_16x16x32_bf16 v[24:27], v[150:153], v[182:185], v[24:27]
	v_mfma_f32_16x16x32_bf16 v[24:27], v[154:157], v[186:189], v[24:27]
	v_mfma_f32_16x16x32_bf16 v[20:23], v[162:165], v[186:189], v[20:23]
	v_mfma_f32_16x16x32_bf16 v[20:23], v[158:161], v[182:185], v[20:23]
	v_mfma_f32_16x16x32_bf16 v[4:7], v[158:161], v[190:193], v[4:7]
	v_mfma_f32_16x16x32_bf16 v[4:7], v[162:165], v[194:197], v[4:7]
	v_mfma_f32_16x16x32_bf16 v[8:11], v[154:157], v[194:197], v[8:11]
	v_mfma_f32_16x16x32_bf16 v[8:11], v[150:153], v[190:193], v[8:11]
	s_setprio 0
	s_barrier
	s_add_u32 s82, s78, 0x40000
	s_addc_u32 s83, s79, 0
	s_add_i32 s69, s92, s65
	s_mov_b32 m0, s69
	s_nop 0
	global_load_lds_dwordx4 v134, s[82:83]
	s_add_i32 m0, s69, 0x2000
	s_nop 0
	global_load_lds_dwordx4 v138, s[82:83]
	s_waitcnt vmcnt(6)
	s_barrier
	s_setprio 1
	v_mfma_f32_16x16x32_bf16 v[60:63], v[198:201], v[166:169], v[60:63]
	v_mfma_f32_16x16x32_bf16 v[60:63], v[210:213], v[170:173], v[60:63]
	v_mfma_f32_16x16x32_bf16 v[48:51], v[218:221], v[170:173], v[48:51]
	v_mfma_f32_16x16x32_bf16 v[48:51], v[214:217], v[166:169], v[48:51]
	v_mfma_f32_16x16x32_bf16 v[32:35], v[214:217], v[174:177], v[32:35]
	v_mfma_f32_16x16x32_bf16 v[32:35], v[218:221], v[178:181], v[32:35]
	v_mfma_f32_16x16x32_bf16 v[44:47], v[210:213], v[178:181], v[44:47]
	v_mfma_f32_16x16x32_bf16 v[44:47], v[198:201], v[174:177], v[44:47]
	v_mfma_f32_16x16x32_bf16 v[28:31], v[198:201], v[182:185], v[28:31]
	v_mfma_f32_16x16x32_bf16 v[28:31], v[210:213], v[186:189], v[28:31]
	v_mfma_f32_16x16x32_bf16 v[16:19], v[218:221], v[186:189], v[16:19]
	v_mfma_f32_16x16x32_bf16 v[16:19], v[214:217], v[182:185], v[16:19]
	v_mfma_f32_16x16x32_bf16 v[0:3], v[214:217], v[190:193], v[0:3]
	v_mfma_f32_16x16x32_bf16 v[0:3], v[218:221], v[194:197], v[0:3]
	v_mfma_f32_16x16x32_bf16 v[12:15], v[210:213], v[194:197], v[12:15]
	v_mfma_f32_16x16x32_bf16 v[12:15], v[198:201], v[190:193], v[12:15]
	s_setprio 0
	s_add_i32 s69, 0, 0x18000
	s_barrier
	s_add_u32 s80, s80, 0x40000
	s_addc_u32 s81, s81, 0
	s_mov_b32 m0, s77
	s_nop 0
	global_load_lds_dwordx4 v132, s[80:81]
	s_mov_b32 m0, s85
	s_nop 0
	global_load_lds_dwordx4 v136, s[80:81]
	ds_read_b128 v[150:153], v252
	ds_read_b128 v[154:157], v252 offset:1024
	ds_read_b128 v[158:161], v252 offset:2048
	ds_read_b128 v[162:165], v252 offset:3072
	ds_read_b128 v[166:169], v206 offset:32768
	ds_read_b128 v[170:173], v206 offset:33792
	ds_read_b128 v[174:177], v206 offset:34816
	ds_read_b128 v[178:181], v206 offset:35840
	ds_read_b128 v[182:185], v206 offset:36864
	ds_read_b128 v[186:189], v206 offset:37888
	ds_read_b128 v[190:193], v206 offset:38912
	ds_read_b128 v[194:197], v206 offset:39936
	s_waitcnt lgkmcnt(8)
	s_barrier
; template <class Epi, class Ptrs>
; __device__ __forceinline__ void gemm_phase(LAS unsigned char* lds, const int K, const StaticOrder& S, const Ptrs& P, const Epi& E) {
;     ...
;             PG8_WAIT_L(8); PG8_BAR; PG8_WAIT_L(0); PG8_MMA(0, 0, At, B0); PG8_BAR; PG8_SCHED;
;             PG8_LDB(B1, 1, 1); PG8_STAGE(PG8_SB(1, 0), b3, voffB);
;             PG8_BAR; PG8_WAIT_L(0); PG8_MMA(0, 1, At, B1); PG8_BAR;
;             PG8_LDA(At, 1, 1); PG8_STAGE(PG8_SA(1, 0), a3, voffA);
;             PG8_BAR; PG8_WAIT_L(0); PG8_MMA(1, 0, At, B0); PG8_BAR; PG8_SCHED;
;             PG8_STAGE(PG8_SB(1, 1), b3 + hstep, voffB);
;             PG8_WAIT_V(6); PG8_BAR; PG8_MMA(1, 1, At, B1); PG8_BAR;
;     __device__ __forceinline__ void operator()(const f32x4 (&acc)[2][2][4][2], const Unit& u, int ui, int wr, int wc, int fr, int fq) const {
;         const int pn = u.pn;
;         if (pn < 8) {
;             bf16_t* base = (bf16_t*)(ws + WS_U) + (size_t)(u.pm * 256 + wr * 64 + fr) * DM + pn * 128 + wc * 32 + 8 * fq;
; #pragma unroll
;             for (int ai = 0; ai < 2; ++ai)
; #pragma unroll
;                 for (int m = 0; m < 4; ++m) {
;                     const f32x4 g0 = g1_4(acc[ai][0][m][0], acc[ai][1][m][0]), g1 = g1_4(acc[ai][0][m][1], acc[ai][1][m][1]);
;                     *(u32x4*)(base + (size_t)(ai * 128 + m * 16) * DM) = pack8(g0, g1); }
;             return; }
;         if (pn >= 17 && pn < 21) {
;             bf16_t* base = (bf16_t*)(dout + DO_GVT) + (size_t)((pn - 17) * 256 + wr * 64 + fr) * MTOK + u.pm * 256 + wc * 32 + 8 * fq;
;             float* pp = (float*)(ws + WS_PART) + (size_t)(u.pm * 256 + wc * 32 + 8 * fq) * 8 + (pn - 17) * 2 + wr;
; #pragma unroll
;             for (int bj = 0; bj < 2; ++bj) { f32x4 sq0 = {0.f, 0.f, 0.f, 0.f}, sq1 = {0.f, 0.f, 0.f, 0.f};
; #pragma unroll
;                 for (int ai = 0; ai < 2; ++ai)
; #pragma unroll
;                     for (int m = 0; m < 4; ++m) { const f32x4 g0 = gelu4(acc[ai][bj][m][0]), g1 = gelu4(acc[ai][bj][m][1]);
;                         sq0 += g0 * g0; sq1 += g1 * g1;
;                         *(u32x4*)(base + (size_t)(ai * 128 + m * 16) * MTOK + bj * 128) = pack8(g0, g1); }
; #pragma unroll
;                 for (int j = 0; j < 4; ++j) { const float t0 = row16_sum(sq0[j]), t1 = row16_sum(sq1[j]); if (fr == 0) { pp[(size_t)(bj * 128 + j) * 8] = t0; pp[(size_t)(bj * 128 + 4 + j) * 8] = t1; } } }
	s_waitcnt lgkmcnt(0)
	s_setprio 1
	s_waitcnt lgkmcnt(0)
	v_mfma_f32_16x16x32_bf16 v[120:123], v[150:153], v[166:169], v[120:123]
	v_mfma_f32_16x16x32_bf16 v[120:123], v[154:157], v[170:173], v[120:123]
	v_mfma_f32_16x16x32_bf16 v[116:119], v[162:165], v[170:173], v[116:119]
	v_mfma_f32_16x16x32_bf16 v[116:119], v[158:161], v[166:169], v[116:119]
	v_mfma_f32_16x16x32_bf16 v[100:103], v[158:161], v[174:177], v[100:103]
	v_mfma_f32_16x16x32_bf16 v[100:103], v[162:165], v[178:181], v[100:103]
	v_mfma_f32_16x16x32_bf16 v[104:107], v[154:157], v[178:181], v[104:107]
	v_mfma_f32_16x16x32_bf16 v[104:107], v[150:153], v[174:177], v[104:107]
	v_mfma_f32_16x16x32_bf16 v[88:91], v[150:153], v[182:185], v[88:91]
	v_mfma_f32_16x16x32_bf16 v[88:91], v[154:157], v[186:189], v[88:91]
	v_mfma_f32_16x16x32_bf16 v[84:87], v[162:165], v[186:189], v[84:87]
	v_mfma_f32_16x16x32_bf16 v[84:87], v[158:161], v[182:185], v[84:87]
	v_mfma_f32_16x16x32_bf16 v[68:71], v[158:161], v[190:193], v[68:71]
	v_mfma_f32_16x16x32_bf16 v[68:71], v[162:165], v[194:197], v[68:71]
	v_mfma_f32_16x16x32_bf16 v[72:75], v[154:157], v[194:197], v[72:75]
	v_mfma_f32_16x16x32_bf16 v[72:75], v[150:153], v[190:193], v[72:75]
	s_setprio 0
	s_barrier
	s_add_i32 s71, 0, 0x1c000
	s_add_i32 s69, s69, s65
	s_mov_b32 m0, s69
	s_nop 0
	global_load_lds_dwordx4 v134, s[100:101]
	s_add_i32 m0, s69, 0x2000
	s_nop 0
	global_load_lds_dwordx4 v138, s[100:101]
	ds_read_b128 v[198:201], v253
	ds_read_b128 v[210:213], v253 offset:1024
	ds_read_b128 v[214:217], v253 offset:2048
	ds_read_b128 v[218:221], v253 offset:3072
	s_barrier
	s_waitcnt lgkmcnt(0)
	s_setprio 1
	s_waitcnt lgkmcnt(0)
	v_mfma_f32_16x16x32_bf16 v[124:127], v[198:201], v[166:169], v[124:127]
	v_mfma_f32_16x16x32_bf16 v[124:127], v[210:213], v[170:173], v[124:127]
	v_mfma_f32_16x16x32_bf16 v[112:115], v[218:221], v[170:173], v[112:115]
	v_mfma_f32_16x16x32_bf16 v[112:115], v[214:217], v[166:169], v[112:115]
	v_mfma_f32_16x16x32_bf16 v[96:99], v[214:217], v[174:177], v[96:99]
	v_mfma_f32_16x16x32_bf16 v[96:99], v[218:221], v[178:181], v[96:99]
	v_mfma_f32_16x16x32_bf16 v[108:111], v[210:213], v[178:181], v[108:111]
	v_mfma_f32_16x16x32_bf16 v[108:111], v[198:201], v[174:177], v[108:111]
	v_mfma_f32_16x16x32_bf16 v[92:95], v[198:201], v[182:185], v[92:95]
	v_mfma_f32_16x16x32_bf16 v[92:95], v[210:213], v[186:189], v[92:95]
	v_mfma_f32_16x16x32_bf16 v[80:83], v[218:221], v[186:189], v[80:83]
	v_mfma_f32_16x16x32_bf16 v[80:83], v[214:217], v[182:185], v[80:83]
	v_mfma_f32_16x16x32_bf16 v[64:67], v[214:217], v[190:193], v[64:67]
	v_mfma_f32_16x16x32_bf16 v[64:67], v[218:221], v[194:197], v[64:67]
	v_mfma_f32_16x16x32_bf16 v[76:79], v[210:213], v[194:197], v[76:79]
	v_mfma_f32_16x16x32_bf16 v[76:79], v[198:201], v[190:193], v[76:79]
	s_setprio 0
	s_mov_b32 m0, s89
	s_add_u32 s100, s80, 0xfffc0080
	s_addc_u32 s101, s81, -1
	s_barrier
	global_load_lds_dwordx4 v132, s[100:101]
	s_mov_b32 m0, s90
	s_nop 0
	global_load_lds_dwordx4 v136, s[100:101]
	ds_read_b128 v[166:169], v206 offset:49152
	ds_read_b128 v[170:173], v206 offset:50176
	ds_read_b128 v[174:177], v206 offset:51200
	ds_read_b128 v[178:181], v206 offset:52224
	ds_read_b128 v[182:185], v206 offset:53248
	ds_read_b128 v[186:189], v206 offset:54272
	ds_read_b128 v[190:193], v206 offset:55296
	ds_read_b128 v[194:197], v206 offset:56320
	s_barrier
	s_waitcnt lgkmcnt(0)
	s_setprio 1
	s_waitcnt lgkmcnt(0)
	v_mfma_f32_16x16x32_bf16 v[56:59], v[150:153], v[166:169], v[56:59]
	v_mfma_f32_16x16x32_bf16 v[56:59], v[154:157], v[170:173], v[56:59]
	v_mfma_f32_16x16x32_bf16 v[52:55], v[162:165], v[170:173], v[52:55]
	v_mfma_f32_16x16x32_bf16 v[52:55], v[158:161], v[166:169], v[52:55]
	v_mfma_f32_16x16x32_bf16 v[36:39], v[158:161], v[174:177], v[36:39]
	v_mfma_f32_16x16x32_bf16 v[36:39], v[162:165], v[178:181], v[36:39]
	v_mfma_f32_16x16x32_bf16 v[40:43], v[154:157], v[178:181], v[40:43]
	v_mfma_f32_16x16x32_bf16 v[40:43], v[150:153], v[174:177], v[40:43]
	v_mfma_f32_16x16x32_bf16 v[24:27], v[150:153], v[182:185], v[24:27]
	v_mfma_f32_16x16x32_bf16 v[24:27], v[154:157], v[186:189], v[24:27]
	v_mfma_f32_16x16x32_bf16 v[20:23], v[162:165], v[186:189], v[20:23]
	v_mfma_f32_16x16x32_bf16 v[20:23], v[158:161], v[182:185], v[20:23]
	v_mfma_f32_16x16x32_bf16 v[4:7], v[158:161], v[190:193], v[4:7]
	v_mfma_f32_16x16x32_bf16 v[4:7], v[162:165], v[194:197], v[4:7]
	v_mfma_f32_16x16x32_bf16 v[8:11], v[154:157], v[194:197], v[8:11]
	v_mfma_f32_16x16x32_bf16 v[8:11], v[150:153], v[190:193], v[8:11]
	s_setprio 0
	s_barrier
	s_add_u32 s78, s78, 0x40080
	s_addc_u32 s79, s79, 0
	s_add_i32 s69, s71, s65
	s_mov_b32 m0, s69
	s_nop 0
	global_load_lds_dwordx4 v134, s[78:79]
	s_add_i32 m0, s69, 0x2000
	s_nop 0
	global_load_lds_dwordx4 v138, s[78:79]
	s_waitcnt vmcnt(6)
	s_barrier
	s_setprio 1
	v_mfma_f32_16x16x32_bf16 v[60:63], v[198:201], v[166:169], v[60:63]
	v_mfma_f32_16x16x32_bf16 v[60:63], v[210:213], v[170:173], v[60:63]
	v_mfma_f32_16x16x32_bf16 v[48:51], v[218:221], v[170:173], v[48:51]
	v_mfma_f32_16x16x32_bf16 v[48:51], v[214:217], v[166:169], v[48:51]
	v_mfma_f32_16x16x32_bf16 v[32:35], v[214:217], v[174:177], v[32:35]
	v_mfma_f32_16x16x32_bf16 v[32:35], v[218:221], v[178:181], v[32:35]
	v_mfma_f32_16x16x32_bf16 v[44:47], v[210:213], v[178:181], v[44:47]
	v_mfma_f32_16x16x32_bf16 v[44:47], v[198:201], v[174:177], v[44:47]
	v_mfma_f32_16x16x32_bf16 v[28:31], v[198:201], v[182:185], v[28:31]
	v_mfma_f32_16x16x32_bf16 v[28:31], v[210:213], v[186:189], v[28:31]
	v_mfma_f32_16x16x32_bf16 v[16:19], v[218:221], v[186:189], v[16:19]
	v_mfma_f32_16x16x32_bf16 v[16:19], v[214:217], v[182:185], v[16:19]
	v_mfma_f32_16x16x32_bf16 v[0:3], v[214:217], v[190:193], v[0:3]
	v_mfma_f32_16x16x32_bf16 v[0:3], v[218:221], v[194:197], v[0:3]
	v_mfma_f32_16x16x32_bf16 v[12:15], v[210:213], v[194:197], v[12:15]
	v_mfma_f32_16x16x32_bf16 v[12:15], v[198:201], v[190:193], v[12:15]
	s_setprio 0
	s_add_i32 s63, s63, 2
	s_add_u32 s6, s6, 0x100
	s_addc_u32 s7, s7, 0
	s_add_u32 s20, s20, 0x100
	s_addc_u32 s25, s25, 0
	s_cmp_gt_u32 s63, 13
	s_barrier
	s_cbranch_scc0 .LBB0_127
	s_nop 0
	s_nop 0
	s_nop 0
	s_nop 0
	s_nop 0
	s_nop 0
	s_nop 0
	s_nop 0
	s_nop 0
	s_nop 0
	s_nop 0
	s_nop 0
	s_nop 0
	s_nop 0
	s_nop 0
	s_nop 0
	s_nop 0
	s_nop 0
	s_nop 0
	s_nop 0
	s_nop 0
	s_nop 0
	s_nop 0
	s_nop 0
	s_cmp_gt_i32 s74, 7
	s_mov_b64 s[6:7], -1
	s_cbranch_scc0 .LBB0_188
	s_sub_i32 s25, s74, 17
	s_cmp_gt_u32 s25, 3
	s_cbranch_scc0 .LBB0_170
	s_lshl_b32 s69, s76, 8
	s_cmp_gt_u32 s74, 11
	s_cbranch_scc0 .LBB0_135
	s_cmp_eq_u32 s74, 12
	s_mov_b64 s[6:7], 0
	s_cbranch_scc1 .LBB0_134
	s_cmp_gt_u32 s74, 16
	s_cbranch_scc1 .LBB0_191
	s_lshl_b32 s20, s74, 8
	v_readlane_b32 s80, v254, 2
	s_addk_i32 s20, 0xf300
	s_mov_b64 s[78:79], 0x400
	s_mov_b64 s[82:83], -1
	s_mov_b32 s63, s69
	v_readlane_b32 s81, v254, 3
	s_andn2_b64 vcc, exec, s[6:7]
	s_cbranch_vccz .LBB0_136
	s_branch .LBB0_137

; #define PG8_STAGE(bufoff, gbase, voff) do { _Pragma("unroll") for (int _i = 0; _i < 2; ++_i) \
;         __builtin_amdgcn_global_load_lds((const unsigned*)((const char*)(gbase) + (voff)[_i]), (LAS unsigned*)(lds + (bufoff) + ldsw + _i * 8192), 16, 0, 0); } while (0)
; #define PG8_LDA(dst, b, h) do { _Pragma("unroll") for (int m = 0; m < 4; ++m) _Pragma("unroll") for (int k = 0; k < 2; ++k) dst[m][k] = *(const LAS bf16x8*)(lds + PG8_SA(b, h) + aoff + m * 2048 + k * 1024); } while (0)
; #define PG8_LDB(dst, b, h) do { _Pragma("unroll") for (int n = 0; n < 2; ++n) _Pragma("unroll") for (int k = 0; k < 2; ++k) dst[n][k] = *(const LAS bf16x8*)(lds + PG8_SB(b, h) + boff + n * 2048 + k * 1024); } while (0)
; #define PG8_MMA(ai, bj, At, Bt) do { __builtin_amdgcn_s_setprio(1); _Pragma("unroll") for (int m = 0; m < 4; ++m) _Pragma("unroll") for (int n = 0; n < 2; ++n) _Pragma("unroll") for (int k = 0; k < 2; ++k) \
;         acc[ai][bj][m][n] = __builtin_amdgcn_mfma_f32_16x16x32_bf16(Bt[n][k], At[m][k], acc[ai][bj][m][n], 0, 0, 0); __builtin_amdgcn_s_setprio(0); } while (0)
; #define PG8_WAIT_L(n) asm volatile("s_waitcnt lgkmcnt(" #n ")" ::: "memory")
; #define PG8_BAR __builtin_amdgcn_s_barrier()
; #define PG8_SCHED __builtin_amdgcn_sched_barrier(0)
; template <class Epi, class Ptrs>
; __device__ __forceinline__ void gemm_phase(LAS unsigned char* lds, const int K, const StaticOrder& S, const Ptrs& P, const Epi& E) {
;     ...
;         for (int t = 0; t < nt; t += 2) {
;             const bool last = (t == nt - 2);
;             const char* a1 = cA + (size_t)(t + 1) * kstep;
;             const char* a2 = last ? nA : cA + (size_t)(t + 2) * kstep; const char* b2 = last ? nB : cB + (size_t)(t + 2) * kstep;
;             const char* a3 = a2 + kstep; const char* b3 = b2 + kstep;
;             PG8_LDB(B0, 0, 0); PG8_SCHED; PG8_LDA(At, 0, 0); PG8_STAGE(PG8_SA(1, 1), a1 + hstep, voffA);
;             PG8_WAIT_L(8); PG8_BAR; PG8_WAIT_L(0); PG8_MMA(0, 0, At, B0); PG8_BAR; PG8_SCHED;
;     ...
; #pragma unroll
;         for (int a = 0; a < 2; ++a)
; #pragma unroll
;             for (int b = 0; b < 2; ++b)
; #pragma unroll
;                 for (int m = 0; m < 4; ++m)
; #pragma unroll
;                     for (int n = 0; n < 2; ++n) acc[a][b][m][n] = (f32x4){0.f, 0.f, 0.f, 0.f};
.LBB0_352:
	s_add_u32 s38, s44, 0x40080
	s_nop 0
	s_nop 0
	s_nop 0
	s_nop 0
	s_nop 0
	s_nop 0
	s_nop 0
	s_nop 0
	s_nop 0
	s_nop 0
	s_nop 0
	s_nop 0
	s_nop 0
	s_nop 0
	s_nop 0
	s_nop 0
	s_nop 0
	s_nop 0
	s_nop 0
	s_nop 0
	s_nop 0
	s_nop 0
	s_nop 0
	s_nop 0
	s_nop 0
	s_nop 0
	s_nop 0
	s_nop 0
	s_nop 0
	s_nop 0
	s_nop 0
	s_nop 0
	s_nop 0
	s_nop 0
	s_nop 0
	s_nop 0
	s_nop 0
	s_nop 0
	s_nop 0
	s_nop 0
	s_nop 0
	s_nop 0
	s_nop 0
	s_nop 0
	s_nop 0
	s_nop 0
	s_nop 0
	s_nop 0
	s_nop 0
	s_nop 0
	s_nop 0
	s_nop 0
	s_nop 0
	s_nop 0
	s_nop 0
	s_nop 0
	s_nop 0
	s_nop 0
	s_nop 0
	s_nop 0
	s_addc_u32 s39, s45, 0
	s_add_u32 s21, s42, 0x100
	v_mov_b32_e32 v0, 0
	s_addc_u32 s23, s43, 0
	s_mov_b32 s41, -2
	v_mov_b32_e32 v1, v0
	v_mov_b32_e32 v2, v0
	v_mov_b32_e32 v3, v0
	v_mov_b32_e32 v4, v0
	v_mov_b32_e32 v5, v0
	v_mov_b32_e32 v6, v0
	v_mov_b32_e32 v7, v0
	v_mov_b32_e32 v16, v0
	v_mov_b32_e32 v17, v0
	v_mov_b32_e32 v18, v0
	v_mov_b32_e32 v19, v0
	v_mov_b32_e32 v20, v0
	v_mov_b32_e32 v21, v0
	v_mov_b32_e32 v22, v0
	v_mov_b32_e32 v23, v0
	v_mov_b32_e32 v32, v0
	v_mov_b32_e32 v33, v0
	v_mov_b32_e32 v34, v0
	v_mov_b32_e32 v35, v0
	v_mov_b32_e32 v36, v0
	v_mov_b32_e32 v37, v0
	v_mov_b32_e32 v38, v0
	v_mov_b32_e32 v39, v0
	v_mov_b32_e32 v48, v0
	v_mov_b32_e32 v49, v0
	v_mov_b32_e32 v50, v0
	v_mov_b32_e32 v51, v0
	v_mov_b32_e32 v52, v0
	v_mov_b32_e32 v53, v0
	v_mov_b32_e32 v54, v0
	v_mov_b32_e32 v55, v0
	v_mov_b32_e32 v8, v0
	v_mov_b32_e32 v9, v0
	v_mov_b32_e32 v10, v0
	v_mov_b32_e32 v11, v0
	v_mov_b32_e32 v12, v0
	v_mov_b32_e32 v13, v0
	v_mov_b32_e32 v14, v0
	v_mov_b32_e32 v15, v0
	v_mov_b32_e32 v24, v0
	v_mov_b32_e32 v25, v0
	v_mov_b32_e32 v26, v0
	v_mov_b32_e32 v27, v0
	v_mov_b32_e32 v28, v0
	v_mov_b32_e32 v29, v0
	v_mov_b32_e32 v30, v0
	v_mov_b32_e32 v31, v0
	v_mov_b32_e32 v40, v0
	v_mov_b32_e32 v41, v0
	v_mov_b32_e32 v42, v0
	v_mov_b32_e32 v43, v0
	v_mov_b32_e32 v44, v0
	v_mov_b32_e32 v45, v0
	v_mov_b32_e32 v46, v0
	v_mov_b32_e32 v47, v0
	v_mov_b32_e32 v56, v0
	v_mov_b32_e32 v57, v0
	v_mov_b32_e32 v58, v0
	v_mov_b32_e32 v59, v0
	v_mov_b32_e32 v60, v0
	v_mov_b32_e32 v61, v0
	v_mov_b32_e32 v62, v0
	v_mov_b32_e32 v63, v0
	v_mov_b32_e32 v64, v0
	v_mov_b32_e32 v65, v0
	v_mov_b32_e32 v66, v0
	v_mov_b32_e32 v67, v0
	v_mov_b32_e32 v68, v0
	v_mov_b32_e32 v69, v0
	v_mov_b32_e32 v70, v0
	v_mov_b32_e32 v71, v0
	v_mov_b32_e32 v80, v0
	v_mov_b32_e32 v81, v0
	v_mov_b32_e32 v82, v0
	v_mov_b32_e32 v83, v0
	v_mov_b32_e32 v84, v0
	v_mov_b32_e32 v85, v0
	v_mov_b32_e32 v86, v0
	v_mov_b32_e32 v87, v0
	v_mov_b32_e32 v96, v0
	v_mov_b32_e32 v97, v0
	v_mov_b32_e32 v98, v0
	v_mov_b32_e32 v99, v0
	v_mov_b32_e32 v100, v0
	v_mov_b32_e32 v101, v0
	v_mov_b32_e32 v102, v0
	v_mov_b32_e32 v103, v0
	v_mov_b32_e32 v112, v0
	v_mov_b32_e32 v113, v0
	v_mov_b32_e32 v114, v0
	v_mov_b32_e32 v115, v0
	v_mov_b32_e32 v116, v0
	v_mov_b32_e32 v117, v0
	v_mov_b32_e32 v118, v0
	v_mov_b32_e32 v119, v0
	v_mov_b32_e32 v72, v0
	v_mov_b32_e32 v73, v0
	v_mov_b32_e32 v74, v0
	v_mov_b32_e32 v75, v0
	v_mov_b32_e32 v76, v0
	v_mov_b32_e32 v77, v0
	v_mov_b32_e32 v78, v0
	v_mov_b32_e32 v79, v0
	v_mov_b32_e32 v88, v0
	v_mov_b32_e32 v89, v0
	v_mov_b32_e32 v90, v0
	v_mov_b32_e32 v91, v0
	v_mov_b32_e32 v92, v0
	v_mov_b32_e32 v93, v0
	v_mov_b32_e32 v94, v0
	v_mov_b32_e32 v95, v0
	v_mov_b32_e32 v104, v0
	v_mov_b32_e32 v105, v0
	v_mov_b32_e32 v106, v0
	v_mov_b32_e32 v107, v0
	v_mov_b32_e32 v108, v0
	v_mov_b32_e32 v109, v0
	v_mov_b32_e32 v110, v0
	v_mov_b32_e32 v111, v0
	v_mov_b32_e32 v120, v0
	v_mov_b32_e32 v121, v0
	v_mov_b32_e32 v122, v0
	v_mov_b32_e32 v123, v0
	v_mov_b32_e32 v124, v0
	v_mov_b32_e32 v125, v0
	v_mov_b32_e32 v126, v0
	v_add_u32_e32 v252, 0x18000, v205
	v_add_u32_e32 v253, 0x1c000, v205
	v_mov_b32_e32 v127, v0
.LBB0_353:
	s_add_u32 s42, s38, 0xfffc0080
	s_addc_u32 s43, s39, -1
	s_cmp_eq_u32 s41, 12
	s_cselect_b32 s45, s1, s43
	s_cselect_b32 s44, s0, s42
	s_cselect_b32 s43, s25, s23
	s_cselect_b32 s42, s24, s21
	s_add_i32 m0, s54, 0xc000
	s_nop 0
	global_load_lds_dwordx4 v184, s[38:39]
	s_add_i32 m0, s54, 0xe000
	s_nop 0
	global_load_lds_dwordx4 v186, s[38:39]
	ds_read_b128 v[128:131], v207
	ds_read_b128 v[132:135], v207 offset:1024
	ds_read_b128 v[136:139], v207 offset:2048
	ds_read_b128 v[140:143], v207 offset:3072
	ds_read_b128 v[144:147], v209
	ds_read_b128 v[148:151], v209 offset:1024
	ds_read_b128 v[152:155], v209 offset:2048
	ds_read_b128 v[156:159], v209 offset:3072
	ds_read_b128 v[160:163], v209 offset:4096
	ds_read_b128 v[164:167], v209 offset:5120
	ds_read_b128 v[168:171], v209 offset:6144
	ds_read_b128 v[172:175], v209 offset:7168
	s_waitcnt lgkmcnt(8)
	s_barrier
	s_waitcnt lgkmcnt(0)
	s_setprio 1
	s_waitcnt lgkmcnt(0)
	v_mfma_f32_16x16x32_bf16 v[124:127], v[128:131], v[144:147], v[124:127]
	v_mfma_f32_16x16x32_bf16 v[124:127], v[132:135], v[148:151], v[124:127]
	v_mfma_f32_16x16x32_bf16 v[120:123], v[140:143], v[148:151], v[120:123]
	v_mfma_f32_16x16x32_bf16 v[120:123], v[136:139], v[144:147], v[120:123]
	v_mfma_f32_16x16x32_bf16 v[104:107], v[136:139], v[152:155], v[104:107]
	v_mfma_f32_16x16x32_bf16 v[104:107], v[140:143], v[156:159], v[104:107]
	v_mfma_f32_16x16x32_bf16 v[108:111], v[132:135], v[156:159], v[108:111]
	v_mfma_f32_16x16x32_bf16 v[108:111], v[128:131], v[152:155], v[108:111]
	v_mfma_f32_16x16x32_bf16 v[92:95], v[128:131], v[160:163], v[92:95]
	v_mfma_f32_16x16x32_bf16 v[92:95], v[132:135], v[164:167], v[92:95]
	v_mfma_f32_16x16x32_bf16 v[88:91], v[140:143], v[164:167], v[88:91]
	v_mfma_f32_16x16x32_bf16 v[88:91], v[136:139], v[160:163], v[88:91]
	v_mfma_f32_16x16x32_bf16 v[72:75], v[136:139], v[168:171], v[72:75]
	v_mfma_f32_16x16x32_bf16 v[72:75], v[140:143], v[172:175], v[72:75]
	v_mfma_f32_16x16x32_bf16 v[76:79], v[132:135], v[172:175], v[76:79]
	v_mfma_f32_16x16x32_bf16 v[76:79], v[128:131], v[168:171], v[76:79]
	s_setprio 0
	s_barrier
; #define PG8_STAGE(bufoff, gbase, voff) do { _Pragma("unroll") for (int _i = 0; _i < 2; ++_i) \
;         __builtin_amdgcn_global_load_lds((const unsigned*)((const char*)(gbase) + (voff)[_i]), (LAS unsigned*)(lds + (bufoff) + ldsw + _i * 8192), 16, 0, 0); } while (0)
; #define PG8_LDA(dst, b, h) do { _Pragma("unroll") for (int m = 0; m < 4; ++m) _Pragma("unroll") for (int k = 0; k < 2; ++k) dst[m][k] = *(const LAS bf16x8*)(lds + PG8_SA(b, h) + aoff + m * 2048 + k * 1024); } while (0)
; #define PG8_LDB(dst, b, h) do { _Pragma("unroll") for (int n = 0; n < 2; ++n) _Pragma("unroll") for (int k = 0; k < 2; ++k) dst[n][k] = *(const LAS bf16x8*)(lds + PG8_SB(b, h) + boff + n * 2048 + k * 1024); } while (0)
; #define PG8_MMA(ai, bj, At, Bt) do { __builtin_amdgcn_s_setprio(1); _Pragma("unroll") for (int m = 0; m < 4; ++m) _Pragma("unroll") for (int n = 0; n < 2; ++n) _Pragma("unroll") for (int k = 0; k < 2; ++k) \
;         acc[ai][bj][m][n] = __builtin_amdgcn_mfma_f32_16x16x32_bf16(Bt[n][k], At[m][k], acc[ai][bj][m][n], 0, 0, 0); __builtin_amdgcn_s_setprio(0); } while (0)
; #define PG8_WAIT_V(n) asm volatile("s_waitcnt vmcnt(" #n ")" ::: "memory")
; #define PG8_WAIT_L(n) asm volatile("s_waitcnt lgkmcnt(" #n ")" ::: "memory")
; #define PG8_BAR __builtin_amdgcn_s_barrier()
; #define PG8_SCHED __builtin_amdgcn_sched_barrier(0)
; template <class Epi, class Ptrs>
; __device__ __forceinline__ void gemm_phase(LAS unsigned char* lds, const int K, const StaticOrder& S, const Ptrs& P, const Epi& E) {
;     ...
;             PG8_LDB(B1, 0, 1); PG8_STAGE(PG8_SB(0, 0), b2, voffB);
;             PG8_BAR; PG8_WAIT_L(0); PG8_MMA(0, 1, At, B1); PG8_BAR;
;             PG8_LDA(At, 0, 1); PG8_STAGE(PG8_SA(0, 0), a2, voffA);
;             PG8_BAR; PG8_WAIT_L(0); PG8_MMA(1, 0, At, B0); PG8_BAR; PG8_SCHED;
;             PG8_STAGE(PG8_SB(0, 1), b2 + hstep, voffB);
;             PG8_WAIT_V(6); PG8_BAR; PG8_MMA(1, 1, At, B1); PG8_BAR;
;             PG8_LDB(B0, 1, 0); PG8_SCHED; PG8_LDA(At, 1, 0); PG8_STAGE(PG8_SA(0, 1), a2 + hstep, voffA);
	s_add_i32 s69, s66, s51
	s_add_u32 s90, s42, 0x80
	s_addc_u32 s91, s43, 0
	s_mov_b32 m0, s69
	s_nop 0
	global_load_lds_dwordx4 v178, s[42:43]
	s_add_i32 m0, s69, 0x2000
	s_nop 0
	global_load_lds_dwordx4 v182, s[42:43]
	ds_read_b128 v[192:195], v210
	ds_read_b128 v[196:199], v210 offset:1024
	ds_read_b128 v[200:203], v210 offset:2048
	ds_read_b128 v[212:215], v210 offset:3072
	s_barrier
	s_waitcnt lgkmcnt(0)
	s_setprio 1
	s_waitcnt lgkmcnt(0)
	v_mfma_f32_16x16x32_bf16 v[116:119], v[192:195], v[144:147], v[116:119]
	v_mfma_f32_16x16x32_bf16 v[116:119], v[196:199], v[148:151], v[116:119]
	v_mfma_f32_16x16x32_bf16 v[112:115], v[212:215], v[148:151], v[112:115]
	v_mfma_f32_16x16x32_bf16 v[112:115], v[200:203], v[144:147], v[112:115]
	v_mfma_f32_16x16x32_bf16 v[96:99], v[200:203], v[152:155], v[96:99]
	v_mfma_f32_16x16x32_bf16 v[96:99], v[212:215], v[156:159], v[96:99]
	v_mfma_f32_16x16x32_bf16 v[100:103], v[196:199], v[156:159], v[100:103]
	v_mfma_f32_16x16x32_bf16 v[100:103], v[192:195], v[152:155], v[100:103]
	v_mfma_f32_16x16x32_bf16 v[84:87], v[192:195], v[160:163], v[84:87]
	v_mfma_f32_16x16x32_bf16 v[84:87], v[196:199], v[164:167], v[84:87]
	v_mfma_f32_16x16x32_bf16 v[80:83], v[212:215], v[164:167], v[80:83]
	v_mfma_f32_16x16x32_bf16 v[80:83], v[200:203], v[160:163], v[80:83]
	v_mfma_f32_16x16x32_bf16 v[64:67], v[200:203], v[168:171], v[64:67]
	v_mfma_f32_16x16x32_bf16 v[64:67], v[212:215], v[172:175], v[64:67]
	v_mfma_f32_16x16x32_bf16 v[68:71], v[196:199], v[172:175], v[68:71]
	v_mfma_f32_16x16x32_bf16 v[68:71], v[192:195], v[168:171], v[68:71]
	s_setprio 0
	s_mov_b32 m0, s54
	s_add_u32 s92, s44, 0x80
	s_addc_u32 s93, s45, 0
	s_barrier
	global_load_lds_dwordx4 v176, s[44:45]
	s_mov_b32 m0, s55
	s_nop 0
	global_load_lds_dwordx4 v180, s[44:45]
	ds_read_b128 v[144:147], v209 offset:16384
	ds_read_b128 v[148:151], v209 offset:17408
	ds_read_b128 v[152:155], v209 offset:18432
	ds_read_b128 v[156:159], v209 offset:19456
	ds_read_b128 v[160:163], v209 offset:20480
	ds_read_b128 v[164:167], v209 offset:21504
	ds_read_b128 v[168:171], v209 offset:22528
	ds_read_b128 v[172:175], v209 offset:23552
	s_barrier
	s_waitcnt lgkmcnt(0)
	s_setprio 1
	s_waitcnt lgkmcnt(0)
	v_mfma_f32_16x16x32_bf16 v[60:63], v[128:131], v[144:147], v[60:63]
	v_mfma_f32_16x16x32_bf16 v[60:63], v[132:135], v[148:151], v[60:63]
	v_mfma_f32_16x16x32_bf16 v[56:59], v[140:143], v[148:151], v[56:59]
	v_mfma_f32_16x16x32_bf16 v[56:59], v[136:139], v[144:147], v[56:59]
	v_mfma_f32_16x16x32_bf16 v[40:43], v[136:139], v[152:155], v[40:43]
	v_mfma_f32_16x16x32_bf16 v[40:43], v[140:143], v[156:159], v[40:43]
	v_mfma_f32_16x16x32_bf16 v[44:47], v[132:135], v[156:159], v[44:47]
	v_mfma_f32_16x16x32_bf16 v[44:47], v[128:131], v[152:155], v[44:47]
	v_mfma_f32_16x16x32_bf16 v[28:31], v[128:131], v[160:163], v[28:31]
	v_mfma_f32_16x16x32_bf16 v[28:31], v[132:135], v[164:167], v[28:31]
	v_mfma_f32_16x16x32_bf16 v[24:27], v[140:143], v[164:167], v[24:27]
	v_mfma_f32_16x16x32_bf16 v[24:27], v[136:139], v[160:163], v[24:27]
	v_mfma_f32_16x16x32_bf16 v[8:11], v[136:139], v[168:171], v[8:11]
	v_mfma_f32_16x16x32_bf16 v[8:11], v[140:143], v[172:175], v[8:11]
	v_mfma_f32_16x16x32_bf16 v[12:15], v[132:135], v[172:175], v[12:15]
	v_mfma_f32_16x16x32_bf16 v[12:15], v[128:131], v[168:171], v[12:15]
	s_setprio 0
	s_barrier
	s_add_u32 s70, s42, 0x40000
	s_addc_u32 s71, s43, 0
	s_add_i32 s69, s67, s51
	s_mov_b32 m0, s69
	s_nop 0
	global_load_lds_dwordx4 v178, s[70:71]
	s_add_i32 m0, s69, 0x2000
	s_nop 0
	global_load_lds_dwordx4 v182, s[70:71]
	s_waitcnt vmcnt(6)
	s_barrier
	s_setprio 1
	v_mfma_f32_16x16x32_bf16 v[52:55], v[192:195], v[144:147], v[52:55]
	v_mfma_f32_16x16x32_bf16 v[52:55], v[196:199], v[148:151], v[52:55]
	v_mfma_f32_16x16x32_bf16 v[48:51], v[212:215], v[148:151], v[48:51]
	v_mfma_f32_16x16x32_bf16 v[48:51], v[200:203], v[144:147], v[48:51]
	v_mfma_f32_16x16x32_bf16 v[32:35], v[200:203], v[152:155], v[32:35]
	v_mfma_f32_16x16x32_bf16 v[32:35], v[212:215], v[156:159], v[32:35]
	v_mfma_f32_16x16x32_bf16 v[36:39], v[196:199], v[156:159], v[36:39]
	v_mfma_f32_16x16x32_bf16 v[36:39], v[192:195], v[152:155], v[36:39]
	v_mfma_f32_16x16x32_bf16 v[20:23], v[192:195], v[160:163], v[20:23]
	v_mfma_f32_16x16x32_bf16 v[20:23], v[196:199], v[164:167], v[20:23]
	v_mfma_f32_16x16x32_bf16 v[16:19], v[212:215], v[164:167], v[16:19]
	v_mfma_f32_16x16x32_bf16 v[16:19], v[200:203], v[160:163], v[16:19]
	v_mfma_f32_16x16x32_bf16 v[0:3], v[200:203], v[168:171], v[0:3]
	v_mfma_f32_16x16x32_bf16 v[0:3], v[212:215], v[172:175], v[0:3]
	v_mfma_f32_16x16x32_bf16 v[4:7], v[196:199], v[172:175], v[4:7]
	v_mfma_f32_16x16x32_bf16 v[4:7], v[192:195], v[168:171], v[4:7]
	s_setprio 0
	s_add_i32 s69, 0, 0x18000
	s_barrier
	s_add_u32 s44, s44, 0x40000
	s_addc_u32 s45, s45, 0
	s_mov_b32 m0, s56
	s_nop 0
	global_load_lds_dwordx4 v176, s[44:45]
	s_mov_b32 m0, s57
	s_nop 0
	global_load_lds_dwordx4 v180, s[44:45]
	ds_read_b128 v[128:131], v252
	ds_read_b128 v[132:135], v252 offset:1024
	ds_read_b128 v[136:139], v252 offset:2048
	ds_read_b128 v[140:143], v252 offset:3072
	ds_read_b128 v[144:147], v209 offset:32768
	ds_read_b128 v[148:151], v209 offset:33792
	ds_read_b128 v[152:155], v209 offset:34816
	ds_read_b128 v[156:159], v209 offset:35840
	ds_read_b128 v[160:163], v209 offset:36864
	ds_read_b128 v[164:167], v209 offset:37888
	ds_read_b128 v[168:171], v209 offset:38912
	ds_read_b128 v[172:175], v209 offset:39936
	s_waitcnt lgkmcnt(8)
	s_barrier
; #define PG8_STAGE(bufoff, gbase, voff) do { _Pragma("unroll") for (int _i = 0; _i < 2; ++_i) \
;         __builtin_amdgcn_global_load_lds((const unsigned*)((const char*)(gbase) + (voff)[_i]), (LAS unsigned*)(lds + (bufoff) + ldsw + _i * 8192), 16, 0, 0); } while (0)
; #define PG8_LDA(dst, b, h) do { _Pragma("unroll") for (int m = 0; m < 4; ++m) _Pragma("unroll") for (int k = 0; k < 2; ++k) dst[m][k] = *(const LAS bf16x8*)(lds + PG8_SA(b, h) + aoff + m * 2048 + k * 1024); } while (0)
; #define PG8_LDB(dst, b, h) do { _Pragma("unroll") for (int n = 0; n < 2; ++n) _Pragma("unroll") for (int k = 0; k < 2; ++k) dst[n][k] = *(const LAS bf16x8*)(lds + PG8_SB(b, h) + boff + n * 2048 + k * 1024); } while (0)
; #define PG8_MMA(ai, bj, At, Bt) do { __builtin_amdgcn_s_setprio(1); _Pragma("unroll") for (int m = 0; m < 4; ++m) _Pragma("unroll") for (int n = 0; n < 2; ++n) _Pragma("unroll") for (int k = 0; k < 2; ++k) \
;         acc[ai][bj][m][n] = __builtin_amdgcn_mfma_f32_16x16x32_bf16(Bt[n][k], At[m][k], acc[ai][bj][m][n], 0, 0, 0); __builtin_amdgcn_s_setprio(0); } while (0)
; #define PG8_WAIT_V(n) asm volatile("s_waitcnt vmcnt(" #n ")" ::: "memory")
; #define PG8_WAIT_L(n) asm volatile("s_waitcnt lgkmcnt(" #n ")" ::: "memory")
; #define PG8_BAR __builtin_amdgcn_s_barrier()
; #define PG8_SCHED __builtin_amdgcn_sched_barrier(0)
; template <class Epi, class Ptrs>
; __device__ __forceinline__ void gemm_phase(LAS unsigned char* lds, const int K, const StaticOrder& S, const Ptrs& P, const Epi& E) {
;     ...
;             PG8_WAIT_L(8); PG8_BAR; PG8_WAIT_L(0); PG8_MMA(0, 0, At, B0); PG8_BAR; PG8_SCHED;
;             PG8_LDB(B1, 1, 1); PG8_STAGE(PG8_SB(1, 0), b3, voffB);
;             PG8_BAR; PG8_WAIT_L(0); PG8_MMA(0, 1, At, B1); PG8_BAR;
;             PG8_LDA(At, 1, 1); PG8_STAGE(PG8_SA(1, 0), a3, voffA);
;             PG8_BAR; PG8_WAIT_L(0); PG8_MMA(1, 0, At, B0); PG8_BAR; PG8_SCHED;
;             PG8_STAGE(PG8_SB(1, 1), b3 + hstep, voffB);
;             PG8_WAIT_V(6); PG8_BAR; PG8_MMA(1, 1, At, B1); PG8_BAR;
	s_waitcnt lgkmcnt(0)
	s_setprio 1
	s_waitcnt lgkmcnt(0)
	v_mfma_f32_16x16x32_bf16 v[124:127], v[128:131], v[144:147], v[124:127]
	v_mfma_f32_16x16x32_bf16 v[124:127], v[132:135], v[148:151], v[124:127]
	v_mfma_f32_16x16x32_bf16 v[120:123], v[140:143], v[148:151], v[120:123]
	v_mfma_f32_16x16x32_bf16 v[120:123], v[136:139], v[144:147], v[120:123]
	v_mfma_f32_16x16x32_bf16 v[104:107], v[136:139], v[152:155], v[104:107]
	v_mfma_f32_16x16x32_bf16 v[104:107], v[140:143], v[156:159], v[104:107]
	v_mfma_f32_16x16x32_bf16 v[108:111], v[132:135], v[156:159], v[108:111]
	v_mfma_f32_16x16x32_bf16 v[108:111], v[128:131], v[152:155], v[108:111]
	v_mfma_f32_16x16x32_bf16 v[92:95], v[128:131], v[160:163], v[92:95]
	v_mfma_f32_16x16x32_bf16 v[92:95], v[132:135], v[164:167], v[92:95]
	v_mfma_f32_16x16x32_bf16 v[88:91], v[140:143], v[164:167], v[88:91]
	v_mfma_f32_16x16x32_bf16 v[88:91], v[136:139], v[160:163], v[88:91]
	v_mfma_f32_16x16x32_bf16 v[72:75], v[136:139], v[168:171], v[72:75]
	v_mfma_f32_16x16x32_bf16 v[72:75], v[140:143], v[172:175], v[72:75]
	v_mfma_f32_16x16x32_bf16 v[76:79], v[132:135], v[172:175], v[76:79]
	v_mfma_f32_16x16x32_bf16 v[76:79], v[128:131], v[168:171], v[76:79]
	s_setprio 0
	s_barrier
	s_add_i32 s44, 0, 0x1c000
	s_add_i32 s45, s69, s51
	s_mov_b32 m0, s45
	s_nop 0
	global_load_lds_dwordx4 v178, s[90:91]
	s_add_i32 m0, s45, 0x2000
	s_nop 0
	global_load_lds_dwordx4 v182, s[90:91]
	ds_read_b128 v[192:195], v253
	ds_read_b128 v[196:199], v253 offset:1024
	ds_read_b128 v[200:203], v253 offset:2048
	ds_read_b128 v[212:215], v253 offset:3072
	s_barrier
	s_waitcnt lgkmcnt(0)
	s_setprio 1
	s_waitcnt lgkmcnt(0)
	v_mfma_f32_16x16x32_bf16 v[116:119], v[192:195], v[144:147], v[116:119]
	v_mfma_f32_16x16x32_bf16 v[116:119], v[196:199], v[148:151], v[116:119]
	v_mfma_f32_16x16x32_bf16 v[112:115], v[212:215], v[148:151], v[112:115]
	v_mfma_f32_16x16x32_bf16 v[112:115], v[200:203], v[144:147], v[112:115]
	v_mfma_f32_16x16x32_bf16 v[96:99], v[200:203], v[152:155], v[96:99]
	v_mfma_f32_16x16x32_bf16 v[96:99], v[212:215], v[156:159], v[96:99]
	v_mfma_f32_16x16x32_bf16 v[100:103], v[196:199], v[156:159], v[100:103]
	v_mfma_f32_16x16x32_bf16 v[100:103], v[192:195], v[152:155], v[100:103]
	v_mfma_f32_16x16x32_bf16 v[84:87], v[192:195], v[160:163], v[84:87]
	v_mfma_f32_16x16x32_bf16 v[84:87], v[196:199], v[164:167], v[84:87]
	v_mfma_f32_16x16x32_bf16 v[80:83], v[212:215], v[164:167], v[80:83]
	v_mfma_f32_16x16x32_bf16 v[80:83], v[200:203], v[160:163], v[80:83]
	v_mfma_f32_16x16x32_bf16 v[64:67], v[200:203], v[168:171], v[64:67]
	v_mfma_f32_16x16x32_bf16 v[64:67], v[212:215], v[172:175], v[64:67]
	v_mfma_f32_16x16x32_bf16 v[68:71], v[196:199], v[172:175], v[68:71]
	v_mfma_f32_16x16x32_bf16 v[68:71], v[192:195], v[168:171], v[68:71]
	s_setprio 0
	s_mov_b32 m0, s63
	s_barrier
	global_load_lds_dwordx4 v176, s[92:93]
	s_mov_b32 m0, s64
	s_nop 0
	global_load_lds_dwordx4 v180, s[92:93]
	ds_read_b128 v[144:147], v209 offset:49152
	ds_read_b128 v[148:151], v209 offset:50176
	ds_read_b128 v[152:155], v209 offset:51200
	ds_read_b128 v[156:159], v209 offset:52224
	ds_read_b128 v[160:163], v209 offset:53248
	ds_read_b128 v[164:167], v209 offset:54272
	ds_read_b128 v[168:171], v209 offset:55296
	ds_read_b128 v[172:175], v209 offset:56320
	s_barrier
	s_waitcnt lgkmcnt(0)
	s_setprio 1
	s_waitcnt lgkmcnt(0)
	v_mfma_f32_16x16x32_bf16 v[60:63], v[128:131], v[144:147], v[60:63]
	v_mfma_f32_16x16x32_bf16 v[60:63], v[132:135], v[148:151], v[60:63]
	v_mfma_f32_16x16x32_bf16 v[56:59], v[140:143], v[148:151], v[56:59]
	v_mfma_f32_16x16x32_bf16 v[56:59], v[136:139], v[144:147], v[56:59]
	v_mfma_f32_16x16x32_bf16 v[40:43], v[136:139], v[152:155], v[40:43]
	v_mfma_f32_16x16x32_bf16 v[40:43], v[140:143], v[156:159], v[40:43]
	v_mfma_f32_16x16x32_bf16 v[44:47], v[132:135], v[156:159], v[44:47]
	v_mfma_f32_16x16x32_bf16 v[44:47], v[128:131], v[152:155], v[44:47]
	v_mfma_f32_16x16x32_bf16 v[28:31], v[128:131], v[160:163], v[28:31]
	v_mfma_f32_16x16x32_bf16 v[28:31], v[132:135], v[164:167], v[28:31]
	v_mfma_f32_16x16x32_bf16 v[24:27], v[140:143], v[164:167], v[24:27]
	v_mfma_f32_16x16x32_bf16 v[24:27], v[136:139], v[160:163], v[24:27]
	v_mfma_f32_16x16x32_bf16 v[8:11], v[136:139], v[168:171], v[8:11]
	v_mfma_f32_16x16x32_bf16 v[8:11], v[140:143], v[172:175], v[8:11]
	v_mfma_f32_16x16x32_bf16 v[12:15], v[132:135], v[172:175], v[12:15]
	v_mfma_f32_16x16x32_bf16 v[12:15], v[128:131], v[168:171], v[12:15]
	s_setprio 0
	s_barrier
	s_add_u32 s42, s42, 0x40080
	s_addc_u32 s43, s43, 0
	s_add_i32 s44, s44, s51
	s_mov_b32 m0, s44
	s_nop 0
	global_load_lds_dwordx4 v178, s[42:43]
	s_add_i32 m0, s44, 0x2000
	s_nop 0
	global_load_lds_dwordx4 v182, s[42:43]
	s_waitcnt vmcnt(6)
	s_barrier
; __device__ __forceinline__ unsigned cvt_pk_bf16(float lo, float hi) { unsigned r; asm volatile("v_cvt_pk_bf16_f32 %0, %1, %2" : "=v"(r) : "v"(lo), "v"(hi)); return r; }
; __device__ __forceinline__ float x16_sum(float x) { auto s = __builtin_amdgcn_permlane16_swap(__float_as_uint(x), __float_as_uint(x), false, false); return __uint_as_float(s[0]) + __uint_as_float(s[1]); }
; __device__ __forceinline__ float x32_sum(float x) { auto s = __builtin_amdgcn_permlane32_swap(__float_as_uint(x), __float_as_uint(x), false, false); return __uint_as_float(s[0]) + __uint_as_float(s[1]); }
;     __device__ __forceinline__ void operator()(const f32x4 (&acc)[2][2][4][2], const Unit& u, int ui, int wr, int wc, int fr, int fq) const {
;         const int row0 = u.pm * 256 + wr * 64 + fr, col0 = u.pn * 256 + wc * 32 + 8 * fq;
;         const float* xb0 = (u.pm * 256 < MP) ? xp : xs - (size_t)MP * DM;
; #pragma unroll
;         for (int ai = 0; ai < 2; ++ai) {
;             f32x4 xv[4][2][2];
; #pragma unroll
;             for (int m = 0; m < 4; ++m)
; #pragma unroll
;                 for (int bj = 0; bj < 2; ++bj) { const float* p = xb0 + (size_t)(row0 + ai * 128 + m * 16) * DM + col0 + bj * 128; xv[m][bj][0] = *(const f32x4*)p; xv[m][bj][1] = *(const f32x4*)(p + 4); }
; #pragma unroll
;             for (int m = 0; m < 4; ++m) { const int row = row0 + ai * 128 + m * 16; const size_t off = (size_t)row * DM + col0; float ss = 0.f;
; #pragma unroll
;                 for (int bj = 0; bj < 2; ++bj) {
;                     const f32x4 v0 = acc[ai][bj][m][0] + xv[m][bj][0], v1 = acc[ai][bj][m][1] + xv[m][bj][1];
;                     u32x4 w; w.x = cvt_pk_bf16(v0[0], v0[1]); w.y = cvt_pk_bf16(v0[2], v0[3]); w.z = cvt_pk_bf16(v1[0], v1[1]); w.w = cvt_pk_bf16(v1[2], v1[3]);
;                     *(u32x4*)(xb + off + bj * 128) = w;
;                     ss += (v0[0] * v0[0] + v0[1] * v0[1]) + (v0[2] * v0[2] + v0[3] * v0[3]) + (v1[0] * v1[0] + v1[1] * v1[1]) + (v1[2] * v1[2] + v1[3] * v1[3]); }
;                 ss = x32_sum(x16_sum(ss));
;                 if (fq == 0) part[(size_t)row * 16 + u.pn * 4 + wc] = ss; }
	s_setprio 1
	v_mfma_f32_16x16x32_bf16 v[52:55], v[192:195], v[144:147], v[52:55]
	v_mfma_f32_16x16x32_bf16 v[52:55], v[196:199], v[148:151], v[52:55]
	v_mfma_f32_16x16x32_bf16 v[48:51], v[212:215], v[148:151], v[48:51]
	v_mfma_f32_16x16x32_bf16 v[48:51], v[200:203], v[144:147], v[48:51]
	v_mfma_f32_16x16x32_bf16 v[32:35], v[200:203], v[152:155], v[32:35]
	v_mfma_f32_16x16x32_bf16 v[32:35], v[212:215], v[156:159], v[32:35]
	v_mfma_f32_16x16x32_bf16 v[36:39], v[196:199], v[156:159], v[36:39]
	v_mfma_f32_16x16x32_bf16 v[36:39], v[192:195], v[152:155], v[36:39]
	v_mfma_f32_16x16x32_bf16 v[20:23], v[192:195], v[160:163], v[20:23]
	v_mfma_f32_16x16x32_bf16 v[20:23], v[196:199], v[164:167], v[20:23]
	v_mfma_f32_16x16x32_bf16 v[16:19], v[212:215], v[164:167], v[16:19]
	v_mfma_f32_16x16x32_bf16 v[16:19], v[200:203], v[160:163], v[16:19]
	v_mfma_f32_16x16x32_bf16 v[0:3], v[200:203], v[168:171], v[0:3]
	v_mfma_f32_16x16x32_bf16 v[0:3], v[212:215], v[172:175], v[0:3]
	v_mfma_f32_16x16x32_bf16 v[4:7], v[196:199], v[172:175], v[4:7]
	v_mfma_f32_16x16x32_bf16 v[4:7], v[192:195], v[168:171], v[4:7]
	s_setprio 0
	s_add_i32 s41, s41, 2
	s_add_u32 s38, s38, 0x100
	s_addc_u32 s39, s39, 0
	s_add_u32 s21, s21, 0x100
	s_addc_u32 s23, s23, 0
	s_cmp_gt_u32 s41, 13
	s_barrier
	s_cbranch_scc0 .LBB0_353
	s_nop 0
	s_nop 0
	s_nop 0
	s_nop 0
	s_nop 0
	s_nop 0
	s_nop 0
	s_nop 0
	s_nop 0
	s_nop 0
	s_nop 0
	s_nop 0
	s_nop 0
	s_nop 0
	s_nop 0
	s_nop 0
	s_nop 0
	s_nop 0
	s_nop 0
	s_nop 0
	s_nop 0
	s_nop 0
	s_nop 0
	s_nop 0
	s_cmpk_lt_i32 s40, 0x80
	v_lshl_add_u32 v194, s40, 8, v204
	v_lshl_or_b32 v192, s12, 8, v206
	s_cselect_b32 s21, s37, s61
	s_cselect_b32 s23, s36, s60
	v_mov_b32_e32 v128, s23
	v_mov_b32_e32 v129, s21
	v_ashrrev_i32_e32 v193, 31, v192
	v_ashrrev_i32_e32 v195, 31, v194
	v_lshl_add_u64 v[196:197], v[192:193], 2, v[128:129]
	v_lshlrev_b64 v[128:129], 12, v[194:195]
	v_or_b32_e32 v202, 16, v194
	v_or_b32_e32 v200, 32, v194
	v_or_b32_e32 v198, 48, v194
	v_lshl_add_u64 v[128:129], v[196:197], 0, v[128:129]
	v_ashrrev_i32_e32 v203, 31, v202
	v_ashrrev_i32_e32 v201, 31, v200
	v_ashrrev_i32_e32 v199, 31, v198
	global_load_dwordx4 v[212:215], v[128:129], off
	global_load_dwordx4 v[216:219], v[128:129], off offset:16
	global_load_dwordx4 v[220:223], v[128:129], off offset:512
	global_load_dwordx4 v[224:227], v[128:129], off offset:528
	v_lshlrev_b64 v[128:129], 12, v[202:203]
	v_lshlrev_b64 v[130:131], 12, v[200:201]
	v_lshlrev_b64 v[132:133], 12, v[198:199]
	v_lshl_add_u64 v[128:129], v[196:197], 0, v[128:129]
	v_lshl_add_u64 v[130:131], v[196:197], 0, v[130:131]
	v_lshl_add_u64 v[132:133], v[196:197], 0, v[132:133]
	global_load_dwordx4 v[168:171], v[128:129], off offset:16
	global_load_dwordx4 v[172:175], v[128:129], off
	global_load_dwordx4 v[160:163], v[128:129], off offset:528
	global_load_dwordx4 v[164:167], v[128:129], off offset:512
	global_load_dwordx4 v[152:155], v[130:131], off offset:16
	global_load_dwordx4 v[156:159], v[130:131], off
	global_load_dwordx4 v[144:147], v[130:131], off offset:528
	global_load_dwordx4 v[148:151], v[130:131], off offset:512
	global_load_dwordx4 v[136:139], v[132:133], off offset:16
	global_load_dwordx4 v[140:143], v[132:133], off
	s_nop 0
	global_load_dwordx4 v[128:131], v[132:133], off offset:528
	s_nop 0
	global_load_dwordx4 v[132:135], v[132:133], off offset:512
	v_lshlrev_b64 v[228:229], 11, v[194:195]
	v_lshl_add_u64 v[228:229], s[14:15], 0, v[228:229]
	v_lshl_add_u64 v[228:229], v[192:193], 1, v[228:229]
	s_lshl_b32 s38, s12, 2
	s_ashr_i32 s39, s38, 31
	s_waitcnt vmcnt(0)
	v_pk_add_f32 v[126:127], v[126:127], v[214:215]
	v_pk_add_f32 v[124:125], v[124:125], v[212:213]
	v_pk_add_f32 v[118:119], v[118:119], v[222:223]
	v_pk_add_f32 v[116:117], v[116:117], v[220:221]
	v_pk_add_f32 v[120:121], v[120:121], v[216:217]
	v_pk_add_f32 v[214:215], v[112:113], v[224:225]
	v_cvt_pk_bf16_f32 v112, v124, v125
	v_cvt_pk_bf16_f32 v113, v126, v127
	v_mul_f32_e32 v125, v125, v125
	v_mul_f32_e32 v127, v127, v127
	v_mul_f32_e32 v211, v117, v117
	v_mul_f32_e32 v216, v119, v119
	v_pk_add_f32 v[122:123], v[122:123], v[218:219]
	v_pk_add_f32 v[212:213], v[114:115], v[226:227]
	v_cvt_pk_bf16_f32 v114, v120, v121
	v_cvt_pk_bf16_f32 v115, v122, v123
	v_mul_f32_e32 v121, v121, v121
	v_mul_f32_e32 v217, v215, v215
	global_store_dwordx4 v[228:229], v[112:115], off
	v_fmac_f32_e32 v125, v124, v124
	v_fmac_f32_e32 v127, v126, v126
	v_cvt_pk_bf16_f32 v112, v116, v117
	v_fmac_f32_e32 v211, v116, v116
	v_fmac_f32_e32 v216, v118, v118
	v_mul_f32_e32 v123, v123, v123
	v_mul_f32_e32 v218, v213, v213
	v_fmac_f32_e32 v121, v120, v120
	v_cvt_pk_bf16_f32 v113, v118, v119
	v_cvt_pk_bf16_f32 v114, v214, v215
	v_cvt_pk_bf16_f32 v115, v212, v213
	v_fmac_f32_e32 v217, v214, v214
	v_add_f32_e32 v116, v125, v127
	global_store_dwordx4 v[228:229], v[112:115], off offset:256
	v_fmac_f32_e32 v123, v122, v122
	v_fmac_f32_e32 v218, v212, v212
	v_add_f32_e32 v112, v211, v216
	v_add_f32_e32 v113, v116, v121
	v_add_f32_e32 v112, v112, v217
	v_add_f32_e32 v113, v123, v113
	v_add_f32_e32 v112, v218, v112
	v_add_f32_e32 v112, v113, v112
	v_mov_b32_e32 v113, v112
	s_nop 1
	v_permlane16_swap_b32_e32 v112, v113
	v_add_f32_e32 v112, v112, v113
	v_mov_b32_e32 v113, v112
	s_nop 1
	v_permlane32_swap_b32_e32 v112, v113
	s_and_saveexec_b64 s[40:41], s[6:7]
	s_cbranch_execz .LBB0_356
	v_lshlrev_b64 v[114:115], 6, v[194:195]
	v_lshl_add_u64 v[114:115], s[16:17], 0, v[114:115]
	v_lshl_add_u64 v[114:115], s[38:39], 2, v[114:115]
	s_lshl_b32 s12, s62, 2
	v_lshl_add_u64 v[114:115], v[114:115], 0, s[12:13]
	v_add_f32_e32 v112, v112, v113
	global_store_dword v[114:115], v112, off

; #define PG8_STAGE(bufoff, gbase, voff) do { _Pragma("unroll") for (int _i = 0; _i < 2; ++_i) \
;         __builtin_amdgcn_global_load_lds((const unsigned*)((const char*)(gbase) + (voff)[_i]), (LAS unsigned*)(lds + (bufoff) + ldsw + _i * 8192), 16, 0, 0); } while (0)
; #define PG8_WAIT_V(n) asm volatile("s_waitcnt vmcnt(" #n ")" ::: "memory")
; #define PG8_BAR __builtin_amdgcn_s_barrier()
; template <class Epi, class Ptrs>
; __device__ __forceinline__ void gemm_phase(LAS unsigned char* lds, const int K, const StaticOrder& S, const Ptrs& P, const Epi& E) {
;     const int tid = threadIdx.x, wid = __builtin_amdgcn_readfirstlane(tid >> 6), lane = tid & 63, wr = wid >> 2, wc = wid & 3, fr = lane & 15, fq = lane >> 4;
;     const int nt = K / BK;
;     unsigned voffA[2], voffB[2];
; #pragma unroll
;     for (int i = 0; i < 2; ++i) { int R, C; stage_rc(tid * 16 + i * 8192, R, C); const int Rb = (R & ~31) + perm32(R & 31);
;         voffA[i] = (unsigned)(R * K + C) * 2u; voffB[i] = (unsigned)(Rb * K + C) * 2u; }
;     const size_t kstep = (size_t)(BK * 2);
;     const size_t hstep = (size_t)HALF * K * 2;
;     const unsigned ldsw = (unsigned)wid * 1024u;
;     const int aoff = lds_byte(wr * 64 + fr, fq * 8), boff = lds_byte(wc * 32 + fr, fq * 8);
;     ...
;     PG8_STAGE(PG8_SB(0, 0), cB, voffB); PG8_STAGE(PG8_SA(0, 0), cA, voffA); PG8_STAGE(PG8_SB(0, 1), cB + hstep, voffB); PG8_STAGE(PG8_SA(0, 1), cA + hstep, voffA);
;     if (wr == 1) PG8_BAR;
;     PG8_WAIT_V(4); PG8_BAR;
;     PG8_STAGE(PG8_SB(1, 0), cB + kstep, voffB); PG8_STAGE(PG8_SA(1, 0), cA + kstep, voffA); PG8_STAGE(PG8_SB(1, 1), cB + hstep + kstep, voffB);
;     PG8_WAIT_V(6); PG8_BAR;
.LBB0_427:
	s_nop 0
	s_nop 0
	s_nop 0
	s_nop 0
	s_nop 0
	s_nop 0
	s_nop 0
	s_nop 0
	s_nop 0
	s_nop 0
	s_nop 0
	s_nop 0
	s_nop 0
	s_nop 0
	s_nop 0
	s_nop 0
	s_nop 0
	s_nop 0
	s_nop 0
	s_nop 0
	s_nop 0
	s_nop 0
	s_nop 0
	s_nop 0
	s_nop 0
	s_nop 0
	s_nop 0
	s_nop 0
	s_nop 0
	s_nop 0
	s_nop 0
	s_nop 0
	s_nop 0
	s_nop 0
	s_nop 0
	s_nop 0
	s_nop 0
	s_nop 0
	s_nop 0
	s_nop 0
	s_nop 0
	s_nop 0
	s_nop 0
	s_nop 0
	s_nop 0
	s_nop 0
	s_nop 0
	s_nop 0
	s_nop 0
	s_nop 0
	s_nop 0
	s_nop 0
	s_nop 0
	s_add_u32 s10, s28, 0xe000000
	s_addc_u32 s11, s29, 0
	s_lshl_b32 s4, s4, 5
	s_mov_b64 s[12:13], 0x80
	s_and_b32 s15, s4, 0x60
	s_add_i32 m0, s39, 0x18000
	v_lshl_add_u64 v[6:7], v[6:7], 0, s[12:13]
	s_ashr_i32 s60, s3, 31
	s_lshl_b32 s14, s1, 13
	s_lshl_b32 s16, s15, 7
	s_waitcnt vmcnt(4)
	s_barrier
	global_load_lds_dwordx4 v[6:7], off
	v_lshl_add_u64 v[4:5], v[4:5], 0, s[12:13]
	s_add_i32 m0, s39, 0x1a000
	s_add_i32 s61, s39, 0x8000
	s_add_i32 s62, s39, 0xa000
	global_load_lds_dwordx4 v[4:5], off
	v_lshl_add_u64 v[2:3], v[2:3], 0, s[12:13]
	s_mov_b32 m0, s61
	s_add_u32 s4, s42, 0x40080
	global_load_lds_dwordx4 v[2:3], off
	v_lshl_add_u64 v[0:1], v[0:1], 0, s[12:13]
	s_mov_b32 m0, s62
	s_addc_u32 s5, s43, 0
	global_load_lds_dwordx4 v[0:1], off
	s_add_i32 m0, s39, 0x1c000
	v_lshl_add_u64 v[0:1], s[4:5], 0, v[130:131]
	global_load_lds_dwordx4 v[0:1], off
	v_lshl_add_u64 v[0:1], s[4:5], 0, v[134:135]
	s_add_i32 m0, s39, 0x1e000
	s_sext_i32_i8 s69, s0
	global_load_lds_dwordx4 v[0:1], off
	v_and_b32_e32 v0, 15, v208
	v_lshlrev_b32_e32 v1, 1, v11
	v_lshlrev_b32_e32 v2, 6, v208
	s_movk_i32 s0, 0x3c0
	v_lshlrev_b32_e32 v3, 2, v208
	v_and_or_b32 v2, v2, s0, v1
	v_and_b32_e32 v3, 32, v3
	v_lshl_or_b32 v146, s1, 6, v0
	v_lshl_or_b32 v0, v0, 6, v1
	v_lshlrev_b32_e32 v1, 8, v208
	v_bitop3_b32 v147, s16, v2, v3 bitop3:0xf6
	v_and_b32_e32 v1, 0x38000, v1
	v_lshlrev_b32_e32 v2, 11, v10
	v_or3_b32 v1, v8, v1, v2
	v_add_u32_e32 v136, v1, v9
	v_lshlrev_b32_e32 v1, 4, v12
	s_waitcnt vmcnt(6)
	v_and_b32_e32 v1, 0x78000, v1
	v_bitop3_b32 v0, v0, s14, v3 bitop3:0xde
	v_or3_b32 v1, v8, v1, v2
	s_add_i32 s63, 0, 0x10000
	s_add_i32 s64, 0, 0x14000
	v_or_b32_e32 v148, s15, v11
	v_mov_b32_e32 v137, v131
	v_add_u32_e32 v138, v1, v9
	v_mov_b32_e32 v139, v131
	v_mov_b64_e32 v[140:141], 0x1800
	v_mov_b64_e32 v[142:143], 0x17ff
	v_add_u32_e32 v149, s63, v147
	v_add_u32_e32 v150, 0, v0
	v_add_u32_e32 v151, s64, v147
	s_mov_b64 s[14:15], 0x100000
	s_mov_b32 s65, 0x100000
	s_mov_b64 s[16:17], 0x120000
	s_mov_b32 s66, 0x120000
	s_mov_b64 s[18:19], 0x140000
	s_mov_b32 s67, 0x140000
	s_mov_b64 s[20:21], 0x160000
	s_mov_b32 s68, 0x160000
	s_barrier

; #define PG8_STAGE(bufoff, gbase, voff) do { _Pragma("unroll") for (int _i = 0; _i < 2; ++_i) \
;         __builtin_amdgcn_global_load_lds((const unsigned*)((const char*)(gbase) + (voff)[_i]), (LAS unsigned*)(lds + (bufoff) + ldsw + _i * 8192), 16, 0, 0); } while (0)
; #define PG8_LDA(dst, b, h) do { _Pragma("unroll") for (int m = 0; m < 4; ++m) _Pragma("unroll") for (int k = 0; k < 2; ++k) dst[m][k] = *(const LAS bf16x8*)(lds + PG8_SA(b, h) + aoff + m * 2048 + k * 1024); } while (0)
; #define PG8_LDB(dst, b, h) do { _Pragma("unroll") for (int n = 0; n < 2; ++n) _Pragma("unroll") for (int k = 0; k < 2; ++k) dst[n][k] = *(const LAS bf16x8*)(lds + PG8_SB(b, h) + boff + n * 2048 + k * 1024); } while (0)
; #define PG8_MMA(ai, bj, At, Bt) do { __builtin_amdgcn_s_setprio(1); _Pragma("unroll") for (int m = 0; m < 4; ++m) _Pragma("unroll") for (int n = 0; n < 2; ++n) _Pragma("unroll") for (int k = 0; k < 2; ++k) \
;         acc[ai][bj][m][n] = __builtin_amdgcn_mfma_f32_16x16x32_bf16(Bt[n][k], At[m][k], acc[ai][bj][m][n], 0, 0, 0); __builtin_amdgcn_s_setprio(0); } while (0)
; #define PG8_WAIT_L(n) asm volatile("s_waitcnt lgkmcnt(" #n ")" ::: "memory")
; #define PG8_BAR __builtin_amdgcn_s_barrier()
; #define PG8_SCHED __builtin_amdgcn_sched_barrier(0)
; template <class Epi, class Ptrs>
; __device__ __forceinline__ void gemm_phase(LAS unsigned char* lds, const int K, const StaticOrder& S, const Ptrs& P, const Epi& E) {
;     ...
;         for (int t = 0; t < nt; t += 2) {
;             const bool last = (t == nt - 2);
;             const char* a1 = cA + (size_t)(t + 1) * kstep;
;             const char* a2 = last ? nA : cA + (size_t)(t + 2) * kstep; const char* b2 = last ? nB : cB + (size_t)(t + 2) * kstep;
;             const char* a3 = a2 + kstep; const char* b3 = b2 + kstep;
;             PG8_LDB(B0, 0, 0); PG8_SCHED; PG8_LDA(At, 0, 0); PG8_STAGE(PG8_SA(1, 1), a1 + hstep, voffA);
;             PG8_WAIT_L(8); PG8_BAR; PG8_WAIT_L(0); PG8_MMA(0, 0, At, B0); PG8_BAR; PG8_SCHED;
;     ...
; #pragma unroll
;         for (int a = 0; a < 2; ++a)
; #pragma unroll
;             for (int b = 0; b < 2; ++b)
; #pragma unroll
;                 for (int m = 0; m < 4; ++m)
; #pragma unroll
;                     for (int n = 0; n < 2; ++n) acc[a][b][m][n] = (f32x4){0.f, 0.f, 0.f, 0.f};
.LBB0_432:
	s_add_u32 s40, s40, 0x40080
	s_addc_u32 s41, s41, 0
	s_add_u32 s23, s42, 0x100
	v_mov_b32_e32 v0, 0
	s_addc_u32 s25, s43, 0
	s_mov_b32 s70, -2
	v_mov_b32_e32 v1, v0
	v_mov_b32_e32 v2, v0
	v_mov_b32_e32 v3, v0
	v_mov_b32_e32 v4, v0
	v_mov_b32_e32 v5, v0
	v_mov_b32_e32 v6, v0
	v_mov_b32_e32 v7, v0
	v_mov_b32_e32 v16, v0
	v_mov_b32_e32 v17, v0
	v_mov_b32_e32 v18, v0
	v_mov_b32_e32 v19, v0
	v_mov_b32_e32 v20, v0
	v_mov_b32_e32 v21, v0
	v_mov_b32_e32 v22, v0
	v_mov_b32_e32 v23, v0
	v_mov_b32_e32 v32, v0
	v_mov_b32_e32 v33, v0
	v_mov_b32_e32 v34, v0
	v_mov_b32_e32 v35, v0
	v_mov_b32_e32 v36, v0
	v_mov_b32_e32 v37, v0
	v_mov_b32_e32 v38, v0
	v_mov_b32_e32 v39, v0
	v_mov_b32_e32 v48, v0
	v_mov_b32_e32 v49, v0
	v_mov_b32_e32 v50, v0
	v_mov_b32_e32 v51, v0
	v_mov_b32_e32 v52, v0
	v_mov_b32_e32 v53, v0
	v_mov_b32_e32 v54, v0
	v_mov_b32_e32 v55, v0
	v_mov_b32_e32 v8, v0
	v_mov_b32_e32 v9, v0
	v_mov_b32_e32 v10, v0
	v_mov_b32_e32 v11, v0
	v_mov_b32_e32 v12, v0
	v_mov_b32_e32 v13, v0
	v_mov_b32_e32 v14, v0
	v_mov_b32_e32 v15, v0
	v_mov_b32_e32 v24, v0
	v_mov_b32_e32 v25, v0
	v_mov_b32_e32 v26, v0
	v_mov_b32_e32 v27, v0
	v_mov_b32_e32 v28, v0
	v_mov_b32_e32 v29, v0
	v_mov_b32_e32 v30, v0
	v_mov_b32_e32 v31, v0
	v_mov_b32_e32 v40, v0
	v_mov_b32_e32 v41, v0
	v_mov_b32_e32 v42, v0
	v_mov_b32_e32 v43, v0
	v_mov_b32_e32 v44, v0
	v_mov_b32_e32 v45, v0
	v_mov_b32_e32 v46, v0
	v_mov_b32_e32 v47, v0
	v_mov_b32_e32 v56, v0
	v_mov_b32_e32 v57, v0
	v_mov_b32_e32 v58, v0
	v_mov_b32_e32 v59, v0
	v_mov_b32_e32 v60, v0
	v_mov_b32_e32 v61, v0
	v_mov_b32_e32 v62, v0
	v_mov_b32_e32 v63, v0
	v_mov_b32_e32 v64, v0
	v_mov_b32_e32 v65, v0
	v_mov_b32_e32 v66, v0
	v_mov_b32_e32 v67, v0
	v_mov_b32_e32 v68, v0
	v_mov_b32_e32 v69, v0
	v_mov_b32_e32 v70, v0
	v_mov_b32_e32 v71, v0
	v_mov_b32_e32 v80, v0
	v_mov_b32_e32 v81, v0
	v_mov_b32_e32 v82, v0
	v_mov_b32_e32 v83, v0
	v_mov_b32_e32 v84, v0
	v_mov_b32_e32 v85, v0
	v_mov_b32_e32 v86, v0
	v_mov_b32_e32 v87, v0
	v_mov_b32_e32 v96, v0
	v_mov_b32_e32 v97, v0
	v_mov_b32_e32 v98, v0
	v_mov_b32_e32 v99, v0
	v_mov_b32_e32 v100, v0
	v_mov_b32_e32 v101, v0
	v_mov_b32_e32 v102, v0
	v_mov_b32_e32 v103, v0
	v_mov_b32_e32 v112, v0
	v_mov_b32_e32 v113, v0
	v_mov_b32_e32 v114, v0
	v_mov_b32_e32 v115, v0
	v_mov_b32_e32 v116, v0
	v_mov_b32_e32 v117, v0
	v_mov_b32_e32 v118, v0
	v_mov_b32_e32 v119, v0
	v_mov_b32_e32 v72, v0
	v_mov_b32_e32 v73, v0
	v_mov_b32_e32 v74, v0
	v_mov_b32_e32 v75, v0
	v_mov_b32_e32 v76, v0
	v_mov_b32_e32 v77, v0
	v_mov_b32_e32 v78, v0
	v_mov_b32_e32 v79, v0
	v_mov_b32_e32 v88, v0
	v_mov_b32_e32 v89, v0
	v_mov_b32_e32 v90, v0
	v_mov_b32_e32 v91, v0
	v_mov_b32_e32 v92, v0
	v_mov_b32_e32 v93, v0
	v_mov_b32_e32 v94, v0
	v_mov_b32_e32 v95, v0
	v_mov_b32_e32 v104, v0
	v_mov_b32_e32 v105, v0
	v_mov_b32_e32 v106, v0
	v_mov_b32_e32 v107, v0
	v_mov_b32_e32 v108, v0
	v_mov_b32_e32 v109, v0
	v_mov_b32_e32 v110, v0
	v_mov_b32_e32 v111, v0
	v_mov_b32_e32 v120, v0
	v_mov_b32_e32 v121, v0
	v_mov_b32_e32 v122, v0
	v_mov_b32_e32 v123, v0
	v_mov_b32_e32 v124, v0
	v_mov_b32_e32 v125, v0
	v_mov_b32_e32 v126, v0
	v_add_u32_e32 v252, 0x18000, v147
	v_add_u32_e32 v253, 0x1c000, v147
	v_mov_b32_e32 v127, v0
.LBB0_433:
	s_add_u32 s42, s40, 0xfffc0080
	s_addc_u32 s43, s41, -1
	s_cmp_eq_u32 s70, 12
	s_cselect_b32 s45, s1, s43
	s_cselect_b32 s44, s0, s42
	s_cselect_b32 s43, s37, s25
	s_cselect_b32 s42, s36, s23
	s_add_i32 m0, s39, 0xc000
	s_nop 0
	global_load_lds_dwordx4 v136, s[40:41]
	s_add_i32 m0, s39, 0xe000
	s_nop 0
	global_load_lds_dwordx4 v138, s[40:41]
	ds_read_b128 v[152:155], v149
	ds_read_b128 v[156:159], v149 offset:1024
	ds_read_b128 v[160:163], v149 offset:2048
	ds_read_b128 v[164:167], v149 offset:3072
	ds_read_b128 v[168:171], v150
	ds_read_b128 v[172:175], v150 offset:1024
	ds_read_b128 v[176:179], v150 offset:2048
	ds_read_b128 v[180:183], v150 offset:3072
	ds_read_b128 v[184:187], v150 offset:4096
	ds_read_b128 v[188:191], v150 offset:5120
	ds_read_b128 v[192:195], v150 offset:6144
	ds_read_b128 v[196:199], v150 offset:7168
	s_waitcnt lgkmcnt(8)
	s_barrier
	s_waitcnt lgkmcnt(0)
	s_setprio 1
	s_waitcnt lgkmcnt(0)
	v_mfma_f32_16x16x32_bf16 v[124:127], v[152:155], v[168:171], v[124:127]
	v_mfma_f32_16x16x32_bf16 v[124:127], v[156:159], v[172:175], v[124:127]
	v_mfma_f32_16x16x32_bf16 v[120:123], v[164:167], v[172:175], v[120:123]
	v_mfma_f32_16x16x32_bf16 v[120:123], v[160:163], v[168:171], v[120:123]
	v_mfma_f32_16x16x32_bf16 v[104:107], v[160:163], v[176:179], v[104:107]
	v_mfma_f32_16x16x32_bf16 v[104:107], v[164:167], v[180:183], v[104:107]
	v_mfma_f32_16x16x32_bf16 v[108:111], v[156:159], v[180:183], v[108:111]
	v_mfma_f32_16x16x32_bf16 v[108:111], v[152:155], v[176:179], v[108:111]
	v_mfma_f32_16x16x32_bf16 v[92:95], v[152:155], v[184:187], v[92:95]
	v_mfma_f32_16x16x32_bf16 v[92:95], v[156:159], v[188:191], v[92:95]
	v_mfma_f32_16x16x32_bf16 v[88:91], v[164:167], v[188:191], v[88:91]
	v_mfma_f32_16x16x32_bf16 v[88:91], v[160:163], v[184:187], v[88:91]
	v_mfma_f32_16x16x32_bf16 v[72:75], v[160:163], v[192:195], v[72:75]
	v_mfma_f32_16x16x32_bf16 v[72:75], v[164:167], v[196:199], v[72:75]
	v_mfma_f32_16x16x32_bf16 v[76:79], v[156:159], v[196:199], v[76:79]
	v_mfma_f32_16x16x32_bf16 v[76:79], v[152:155], v[192:195], v[76:79]
	s_setprio 0
	s_barrier
	s_add_i32 s71, s63, s51
	s_add_u32 s76, s42, 0x80
	s_addc_u32 s77, s43, 0
	s_mov_b32 m0, s71
	s_nop 0
	global_load_lds_dwordx4 v130, s[42:43]
	s_add_i32 m0, s71, 0x2000
	s_nop 0
	global_load_lds_dwordx4 v134, s[42:43]
	ds_read_b128 v[200:203], v151
	ds_read_b128 v[204:207], v151 offset:1024
	ds_read_b128 v[210:213], v151 offset:2048
	ds_read_b128 v[214:217], v151 offset:3072
	s_barrier
; #define PG8_STAGE(bufoff, gbase, voff) do { _Pragma("unroll") for (int _i = 0; _i < 2; ++_i) \
;         __builtin_amdgcn_global_load_lds((const unsigned*)((const char*)(gbase) + (voff)[_i]), (LAS unsigned*)(lds + (bufoff) + ldsw + _i * 8192), 16, 0, 0); } while (0)
; #define PG8_LDA(dst, b, h) do { _Pragma("unroll") for (int m = 0; m < 4; ++m) _Pragma("unroll") for (int k = 0; k < 2; ++k) dst[m][k] = *(const LAS bf16x8*)(lds + PG8_SA(b, h) + aoff + m * 2048 + k * 1024); } while (0)
; #define PG8_LDB(dst, b, h) do { _Pragma("unroll") for (int n = 0; n < 2; ++n) _Pragma("unroll") for (int k = 0; k < 2; ++k) dst[n][k] = *(const LAS bf16x8*)(lds + PG8_SB(b, h) + boff + n * 2048 + k * 1024); } while (0)
; #define PG8_MMA(ai, bj, At, Bt) do { __builtin_amdgcn_s_setprio(1); _Pragma("unroll") for (int m = 0; m < 4; ++m) _Pragma("unroll") for (int n = 0; n < 2; ++n) _Pragma("unroll") for (int k = 0; k < 2; ++k) \
;         acc[ai][bj][m][n] = __builtin_amdgcn_mfma_f32_16x16x32_bf16(Bt[n][k], At[m][k], acc[ai][bj][m][n], 0, 0, 0); __builtin_amdgcn_s_setprio(0); } while (0)
; #define PG8_WAIT_V(n) asm volatile("s_waitcnt vmcnt(" #n ")" ::: "memory")
; #define PG8_WAIT_L(n) asm volatile("s_waitcnt lgkmcnt(" #n ")" ::: "memory")
; #define PG8_BAR __builtin_amdgcn_s_barrier()
; #define PG8_SCHED __builtin_amdgcn_sched_barrier(0)
; template <class Epi, class Ptrs>
; __device__ __forceinline__ void gemm_phase(LAS unsigned char* lds, const int K, const StaticOrder& S, const Ptrs& P, const Epi& E) {
;     ...
;             PG8_BAR; PG8_WAIT_L(0); PG8_MMA(0, 1, At, B1); PG8_BAR;
;             PG8_LDA(At, 0, 1); PG8_STAGE(PG8_SA(0, 0), a2, voffA);
;             PG8_BAR; PG8_WAIT_L(0); PG8_MMA(1, 0, At, B0); PG8_BAR; PG8_SCHED;
;             PG8_STAGE(PG8_SB(0, 1), b2 + hstep, voffB);
;             PG8_WAIT_V(6); PG8_BAR; PG8_MMA(1, 1, At, B1); PG8_BAR;
;             PG8_LDB(B0, 1, 0); PG8_SCHED; PG8_LDA(At, 1, 0); PG8_STAGE(PG8_SA(0, 1), a2 + hstep, voffA);
	s_waitcnt lgkmcnt(0)
	s_setprio 1
	s_waitcnt lgkmcnt(0)
	v_mfma_f32_16x16x32_bf16 v[116:119], v[200:203], v[168:171], v[116:119]
	v_mfma_f32_16x16x32_bf16 v[116:119], v[204:207], v[172:175], v[116:119]
	v_mfma_f32_16x16x32_bf16 v[112:115], v[214:217], v[172:175], v[112:115]
	v_mfma_f32_16x16x32_bf16 v[112:115], v[210:213], v[168:171], v[112:115]
	v_mfma_f32_16x16x32_bf16 v[96:99], v[210:213], v[176:179], v[96:99]
	v_mfma_f32_16x16x32_bf16 v[96:99], v[214:217], v[180:183], v[96:99]
	v_mfma_f32_16x16x32_bf16 v[100:103], v[204:207], v[180:183], v[100:103]
	v_mfma_f32_16x16x32_bf16 v[100:103], v[200:203], v[176:179], v[100:103]
	v_mfma_f32_16x16x32_bf16 v[84:87], v[200:203], v[184:187], v[84:87]
	v_mfma_f32_16x16x32_bf16 v[84:87], v[204:207], v[188:191], v[84:87]
	v_mfma_f32_16x16x32_bf16 v[80:83], v[214:217], v[188:191], v[80:83]
	v_mfma_f32_16x16x32_bf16 v[80:83], v[210:213], v[184:187], v[80:83]
	v_mfma_f32_16x16x32_bf16 v[64:67], v[210:213], v[192:195], v[64:67]
	v_mfma_f32_16x16x32_bf16 v[64:67], v[214:217], v[196:199], v[64:67]
	v_mfma_f32_16x16x32_bf16 v[68:71], v[204:207], v[196:199], v[68:71]
	v_mfma_f32_16x16x32_bf16 v[68:71], v[200:203], v[192:195], v[68:71]
	s_setprio 0
	s_mov_b32 m0, s39
	s_add_u32 s78, s44, 0x80
	s_addc_u32 s79, s45, 0
	s_barrier
	global_load_lds_dwordx4 v128, s[44:45]
	s_mov_b32 m0, s56
	s_nop 0
	global_load_lds_dwordx4 v132, s[44:45]
	ds_read_b128 v[168:171], v150 offset:16384
	ds_read_b128 v[172:175], v150 offset:17408
	ds_read_b128 v[176:179], v150 offset:18432
	ds_read_b128 v[180:183], v150 offset:19456
	ds_read_b128 v[184:187], v150 offset:20480
	ds_read_b128 v[188:191], v150 offset:21504
	ds_read_b128 v[192:195], v150 offset:22528
	ds_read_b128 v[196:199], v150 offset:23552
	s_barrier
	s_waitcnt lgkmcnt(0)
	s_setprio 1
	s_waitcnt lgkmcnt(0)
	v_mfma_f32_16x16x32_bf16 v[60:63], v[152:155], v[168:171], v[60:63]
	v_mfma_f32_16x16x32_bf16 v[60:63], v[156:159], v[172:175], v[60:63]
	v_mfma_f32_16x16x32_bf16 v[56:59], v[164:167], v[172:175], v[56:59]
	v_mfma_f32_16x16x32_bf16 v[56:59], v[160:163], v[168:171], v[56:59]
	v_mfma_f32_16x16x32_bf16 v[40:43], v[160:163], v[176:179], v[40:43]
	v_mfma_f32_16x16x32_bf16 v[40:43], v[164:167], v[180:183], v[40:43]
	v_mfma_f32_16x16x32_bf16 v[44:47], v[156:159], v[180:183], v[44:47]
	v_mfma_f32_16x16x32_bf16 v[44:47], v[152:155], v[176:179], v[44:47]
	v_mfma_f32_16x16x32_bf16 v[28:31], v[152:155], v[184:187], v[28:31]
	v_mfma_f32_16x16x32_bf16 v[28:31], v[156:159], v[188:191], v[28:31]
	v_mfma_f32_16x16x32_bf16 v[24:27], v[164:167], v[188:191], v[24:27]
	v_mfma_f32_16x16x32_bf16 v[24:27], v[160:163], v[184:187], v[24:27]
	v_mfma_f32_16x16x32_bf16 v[8:11], v[160:163], v[192:195], v[8:11]
	v_mfma_f32_16x16x32_bf16 v[8:11], v[164:167], v[196:199], v[8:11]
	v_mfma_f32_16x16x32_bf16 v[12:15], v[156:159], v[196:199], v[12:15]
	v_mfma_f32_16x16x32_bf16 v[12:15], v[152:155], v[192:195], v[12:15]
	s_setprio 0
	s_barrier
	s_add_u32 s72, s42, 0x40000
	s_addc_u32 s73, s43, 0
	s_add_i32 s71, s64, s51
	s_mov_b32 m0, s71
	s_nop 0
	global_load_lds_dwordx4 v130, s[72:73]
	s_add_i32 m0, s71, 0x2000
	s_nop 0
	global_load_lds_dwordx4 v134, s[72:73]
	s_waitcnt vmcnt(6)
	s_barrier
	s_setprio 1
	v_mfma_f32_16x16x32_bf16 v[52:55], v[200:203], v[168:171], v[52:55]
	v_mfma_f32_16x16x32_bf16 v[52:55], v[204:207], v[172:175], v[52:55]
	v_mfma_f32_16x16x32_bf16 v[48:51], v[214:217], v[172:175], v[48:51]
	v_mfma_f32_16x16x32_bf16 v[48:51], v[210:213], v[168:171], v[48:51]
	v_mfma_f32_16x16x32_bf16 v[32:35], v[210:213], v[176:179], v[32:35]
	v_mfma_f32_16x16x32_bf16 v[32:35], v[214:217], v[180:183], v[32:35]
	v_mfma_f32_16x16x32_bf16 v[36:39], v[204:207], v[180:183], v[36:39]
	v_mfma_f32_16x16x32_bf16 v[36:39], v[200:203], v[176:179], v[36:39]
	v_mfma_f32_16x16x32_bf16 v[20:23], v[200:203], v[184:187], v[20:23]
	v_mfma_f32_16x16x32_bf16 v[20:23], v[204:207], v[188:191], v[20:23]
	v_mfma_f32_16x16x32_bf16 v[16:19], v[214:217], v[188:191], v[16:19]
	v_mfma_f32_16x16x32_bf16 v[16:19], v[210:213], v[184:187], v[16:19]
	v_mfma_f32_16x16x32_bf16 v[0:3], v[210:213], v[192:195], v[0:3]
	v_mfma_f32_16x16x32_bf16 v[0:3], v[214:217], v[196:199], v[0:3]
	v_mfma_f32_16x16x32_bf16 v[4:7], v[204:207], v[196:199], v[4:7]
	v_mfma_f32_16x16x32_bf16 v[4:7], v[200:203], v[192:195], v[4:7]
	s_setprio 0
	s_add_i32 s71, 0, 0x18000
	s_barrier
	s_add_u32 s44, s44, 0x40000
	s_addc_u32 s45, s45, 0
	s_mov_b32 m0, s57
	s_nop 0
	global_load_lds_dwordx4 v128, s[44:45]
	s_mov_b32 m0, s58
	s_nop 0
	global_load_lds_dwordx4 v132, s[44:45]
	ds_read_b128 v[152:155], v252
	ds_read_b128 v[156:159], v252 offset:1024
	ds_read_b128 v[160:163], v252 offset:2048
	ds_read_b128 v[164:167], v252 offset:3072
	ds_read_b128 v[168:171], v150 offset:32768
	ds_read_b128 v[172:175], v150 offset:33792
	ds_read_b128 v[176:179], v150 offset:34816
	ds_read_b128 v[180:183], v150 offset:35840
	ds_read_b128 v[184:187], v150 offset:36864
	ds_read_b128 v[188:191], v150 offset:37888
	ds_read_b128 v[192:195], v150 offset:38912
	ds_read_b128 v[196:199], v150 offset:39936
	s_waitcnt lgkmcnt(8)
	s_barrier
; #define PG8_STAGE(bufoff, gbase, voff) do { _Pragma("unroll") for (int _i = 0; _i < 2; ++_i) \
;         __builtin_amdgcn_global_load_lds((const unsigned*)((const char*)(gbase) + (voff)[_i]), (LAS unsigned*)(lds + (bufoff) + ldsw + _i * 8192), 16, 0, 0); } while (0)
; #define PG8_LDA(dst, b, h) do { _Pragma("unroll") for (int m = 0; m < 4; ++m) _Pragma("unroll") for (int k = 0; k < 2; ++k) dst[m][k] = *(const LAS bf16x8*)(lds + PG8_SA(b, h) + aoff + m * 2048 + k * 1024); } while (0)
; #define PG8_LDB(dst, b, h) do { _Pragma("unroll") for (int n = 0; n < 2; ++n) _Pragma("unroll") for (int k = 0; k < 2; ++k) dst[n][k] = *(const LAS bf16x8*)(lds + PG8_SB(b, h) + boff + n * 2048 + k * 1024); } while (0)
; #define PG8_MMA(ai, bj, At, Bt) do { __builtin_amdgcn_s_setprio(1); _Pragma("unroll") for (int m = 0; m < 4; ++m) _Pragma("unroll") for (int n = 0; n < 2; ++n) _Pragma("unroll") for (int k = 0; k < 2; ++k) \
;         acc[ai][bj][m][n] = __builtin_amdgcn_mfma_f32_16x16x32_bf16(Bt[n][k], At[m][k], acc[ai][bj][m][n], 0, 0, 0); __builtin_amdgcn_s_setprio(0); } while (0)
; #define PG8_WAIT_V(n) asm volatile("s_waitcnt vmcnt(" #n ")" ::: "memory")
; #define PG8_WAIT_L(n) asm volatile("s_waitcnt lgkmcnt(" #n ")" ::: "memory")
; #define PG8_BAR __builtin_amdgcn_s_barrier()
; #define PG8_SCHED __builtin_amdgcn_sched_barrier(0)
; template <class Epi, class Ptrs>
; __device__ __forceinline__ void gemm_phase(LAS unsigned char* lds, const int K, const StaticOrder& S, const Ptrs& P, const Epi& E) {
;     ...
;             PG8_WAIT_L(8); PG8_BAR; PG8_WAIT_L(0); PG8_MMA(0, 0, At, B0); PG8_BAR; PG8_SCHED;
;             PG8_LDB(B1, 1, 1); PG8_STAGE(PG8_SB(1, 0), b3, voffB);
;             PG8_BAR; PG8_WAIT_L(0); PG8_MMA(0, 1, At, B1); PG8_BAR;
;             PG8_LDA(At, 1, 1); PG8_STAGE(PG8_SA(1, 0), a3, voffA);
;             PG8_BAR; PG8_WAIT_L(0); PG8_MMA(1, 0, At, B0); PG8_BAR; PG8_SCHED;
;             PG8_STAGE(PG8_SB(1, 1), b3 + hstep, voffB);
;             PG8_WAIT_V(6); PG8_BAR; PG8_MMA(1, 1, At, B1); PG8_BAR;
	s_waitcnt lgkmcnt(0)
	s_setprio 1
	s_waitcnt lgkmcnt(0)
	v_mfma_f32_16x16x32_bf16 v[124:127], v[152:155], v[168:171], v[124:127]
	v_mfma_f32_16x16x32_bf16 v[124:127], v[156:159], v[172:175], v[124:127]
	v_mfma_f32_16x16x32_bf16 v[120:123], v[164:167], v[172:175], v[120:123]
	v_mfma_f32_16x16x32_bf16 v[120:123], v[160:163], v[168:171], v[120:123]
	v_mfma_f32_16x16x32_bf16 v[104:107], v[160:163], v[176:179], v[104:107]
	v_mfma_f32_16x16x32_bf16 v[104:107], v[164:167], v[180:183], v[104:107]
	v_mfma_f32_16x16x32_bf16 v[108:111], v[156:159], v[180:183], v[108:111]
	v_mfma_f32_16x16x32_bf16 v[108:111], v[152:155], v[176:179], v[108:111]
	v_mfma_f32_16x16x32_bf16 v[92:95], v[152:155], v[184:187], v[92:95]
	v_mfma_f32_16x16x32_bf16 v[92:95], v[156:159], v[188:191], v[92:95]
	v_mfma_f32_16x16x32_bf16 v[88:91], v[164:167], v[188:191], v[88:91]
	v_mfma_f32_16x16x32_bf16 v[88:91], v[160:163], v[184:187], v[88:91]
	v_mfma_f32_16x16x32_bf16 v[72:75], v[160:163], v[192:195], v[72:75]
	v_mfma_f32_16x16x32_bf16 v[72:75], v[164:167], v[196:199], v[72:75]
	v_mfma_f32_16x16x32_bf16 v[76:79], v[156:159], v[196:199], v[76:79]
	v_mfma_f32_16x16x32_bf16 v[76:79], v[152:155], v[192:195], v[76:79]
	s_setprio 0
	s_barrier
	s_add_i32 s44, 0, 0x1c000
	s_add_i32 s45, s71, s51
	s_mov_b32 m0, s45
	s_nop 0
	global_load_lds_dwordx4 v130, s[76:77]
	s_add_i32 m0, s45, 0x2000
	s_nop 0
	global_load_lds_dwordx4 v134, s[76:77]
	ds_read_b128 v[200:203], v253
	ds_read_b128 v[204:207], v253 offset:1024
	ds_read_b128 v[210:213], v253 offset:2048
	ds_read_b128 v[214:217], v253 offset:3072
	s_barrier
	s_waitcnt lgkmcnt(0)
	s_setprio 1
	s_waitcnt lgkmcnt(0)
	v_mfma_f32_16x16x32_bf16 v[116:119], v[200:203], v[168:171], v[116:119]
	v_mfma_f32_16x16x32_bf16 v[116:119], v[204:207], v[172:175], v[116:119]
	v_mfma_f32_16x16x32_bf16 v[112:115], v[214:217], v[172:175], v[112:115]
	v_mfma_f32_16x16x32_bf16 v[112:115], v[210:213], v[168:171], v[112:115]
	v_mfma_f32_16x16x32_bf16 v[96:99], v[210:213], v[176:179], v[96:99]
	v_mfma_f32_16x16x32_bf16 v[96:99], v[214:217], v[180:183], v[96:99]
	v_mfma_f32_16x16x32_bf16 v[100:103], v[204:207], v[180:183], v[100:103]
	v_mfma_f32_16x16x32_bf16 v[100:103], v[200:203], v[176:179], v[100:103]
	v_mfma_f32_16x16x32_bf16 v[84:87], v[200:203], v[184:187], v[84:87]
	v_mfma_f32_16x16x32_bf16 v[84:87], v[204:207], v[188:191], v[84:87]
	v_mfma_f32_16x16x32_bf16 v[80:83], v[214:217], v[188:191], v[80:83]
	v_mfma_f32_16x16x32_bf16 v[80:83], v[210:213], v[184:187], v[80:83]
	v_mfma_f32_16x16x32_bf16 v[64:67], v[210:213], v[192:195], v[64:67]
	v_mfma_f32_16x16x32_bf16 v[64:67], v[214:217], v[196:199], v[64:67]
	v_mfma_f32_16x16x32_bf16 v[68:71], v[204:207], v[196:199], v[68:71]
	v_mfma_f32_16x16x32_bf16 v[68:71], v[200:203], v[192:195], v[68:71]
	s_setprio 0
	s_mov_b32 m0, s61
	s_barrier
	global_load_lds_dwordx4 v128, s[78:79]
	s_mov_b32 m0, s62
	s_nop 0
	global_load_lds_dwordx4 v132, s[78:79]
	ds_read_b128 v[168:171], v150 offset:49152
	ds_read_b128 v[172:175], v150 offset:50176
	ds_read_b128 v[176:179], v150 offset:51200
	ds_read_b128 v[180:183], v150 offset:52224
	ds_read_b128 v[184:187], v150 offset:53248
	ds_read_b128 v[188:191], v150 offset:54272
	ds_read_b128 v[192:195], v150 offset:55296
	ds_read_b128 v[196:199], v150 offset:56320
	s_barrier
	s_waitcnt lgkmcnt(0)
	s_setprio 1
	s_waitcnt lgkmcnt(0)
	v_mfma_f32_16x16x32_bf16 v[60:63], v[152:155], v[168:171], v[60:63]
	v_mfma_f32_16x16x32_bf16 v[60:63], v[156:159], v[172:175], v[60:63]
	v_mfma_f32_16x16x32_bf16 v[56:59], v[164:167], v[172:175], v[56:59]
	v_mfma_f32_16x16x32_bf16 v[56:59], v[160:163], v[168:171], v[56:59]
	v_mfma_f32_16x16x32_bf16 v[40:43], v[160:163], v[176:179], v[40:43]
	v_mfma_f32_16x16x32_bf16 v[40:43], v[164:167], v[180:183], v[40:43]
	v_mfma_f32_16x16x32_bf16 v[44:47], v[156:159], v[180:183], v[44:47]
	v_mfma_f32_16x16x32_bf16 v[44:47], v[152:155], v[176:179], v[44:47]
	v_mfma_f32_16x16x32_bf16 v[28:31], v[152:155], v[184:187], v[28:31]
	v_mfma_f32_16x16x32_bf16 v[28:31], v[156:159], v[188:191], v[28:31]
	v_mfma_f32_16x16x32_bf16 v[24:27], v[164:167], v[188:191], v[24:27]
	v_mfma_f32_16x16x32_bf16 v[24:27], v[160:163], v[184:187], v[24:27]
	v_mfma_f32_16x16x32_bf16 v[8:11], v[160:163], v[192:195], v[8:11]
	v_mfma_f32_16x16x32_bf16 v[8:11], v[164:167], v[196:199], v[8:11]
	v_mfma_f32_16x16x32_bf16 v[12:15], v[156:159], v[196:199], v[12:15]
	v_mfma_f32_16x16x32_bf16 v[12:15], v[152:155], v[192:195], v[12:15]
	s_setprio 0
	s_barrier
	s_add_u32 s42, s42, 0x40080
	s_addc_u32 s43, s43, 0
	s_add_i32 s44, s44, s51
	s_mov_b32 m0, s44
	s_nop 0
	global_load_lds_dwordx4 v130, s[42:43]
	s_add_i32 m0, s44, 0x2000
	s_nop 0
	global_load_lds_dwordx4 v134, s[42:43]
	s_waitcnt vmcnt(6)
	s_barrier
	s_setprio 1
	v_mfma_f32_16x16x32_bf16 v[52:55], v[200:203], v[168:171], v[52:55]
	v_mfma_f32_16x16x32_bf16 v[52:55], v[204:207], v[172:175], v[52:55]
	v_mfma_f32_16x16x32_bf16 v[48:51], v[214:217], v[172:175], v[48:51]
	v_mfma_f32_16x16x32_bf16 v[48:51], v[210:213], v[168:171], v[48:51]
	v_mfma_f32_16x16x32_bf16 v[32:35], v[210:213], v[176:179], v[32:35]
	v_mfma_f32_16x16x32_bf16 v[32:35], v[214:217], v[180:183], v[32:35]
	v_mfma_f32_16x16x32_bf16 v[36:39], v[204:207], v[180:183], v[36:39]
	v_mfma_f32_16x16x32_bf16 v[36:39], v[200:203], v[176:179], v[36:39]
	v_mfma_f32_16x16x32_bf16 v[20:23], v[200:203], v[184:187], v[20:23]
	v_mfma_f32_16x16x32_bf16 v[20:23], v[204:207], v[188:191], v[20:23]
	v_mfma_f32_16x16x32_bf16 v[16:19], v[214:217], v[188:191], v[16:19]
	v_mfma_f32_16x16x32_bf16 v[16:19], v[210:213], v[184:187], v[16:19]
	v_mfma_f32_16x16x32_bf16 v[0:3], v[210:213], v[192:195], v[0:3]
	v_mfma_f32_16x16x32_bf16 v[0:3], v[214:217], v[196:199], v[0:3]
	v_mfma_f32_16x16x32_bf16 v[4:7], v[204:207], v[196:199], v[4:7]
	v_mfma_f32_16x16x32_bf16 v[4:7], v[200:203], v[192:195], v[4:7]
	s_setprio 0
	s_add_i32 s70, s70, 2
	s_add_u32 s40, s40, 0x100
	s_addc_u32 s41, s41, 0
	s_add_u32 s23, s23, 0x100
	s_addc_u32 s25, s25, 0
	s_cmp_gt_u32 s70, 13
	s_barrier
; __device__ __forceinline__ unsigned cvt_pk_bf16(float lo, float hi) { unsigned r; asm volatile("v_cvt_pk_bf16_f32 %0, %1, %2" : "=v"(r) : "v"(lo), "v"(hi)); return r; }
;     __device__ __forceinline__ void operator()(const f32x4 (&acc)[2][2][4][2], const Unit& u, int ui, int wr, int wc, int fr, int fq) const {
;         const int row0 = u.pm * 256 + wr * 64 + fr, col0 = u.pn * 256 + wc * 32 + 8 * fq;
; #pragma unroll
;         for (int ai = 0; ai < 2; ++ai)
; #pragma unroll
;             for (int m = 0; m < 4; ++m) { bf16_t* rowp = hid + (size_t)(row0 + ai * 128 + m * 16) * DFF + col0;
; #pragma unroll
;                 for (int bj = 0; bj < 2; ++bj) { f32x4 v0 = acc[ai][bj][m][0], v1 = acc[ai][bj][m][1];
; #pragma unroll
;                     for (int j = 0; j < 4; ++j) { const float a = fmaxf(v0[j], 0.f), b = fmaxf(v1[j], 0.f); v0[j] = a * a; v1[j] = b * b; }
;                     u32x4 w; w.x = cvt_pk_bf16(v0[0], v0[1]); w.y = cvt_pk_bf16(v0[2], v0[3]); w.z = cvt_pk_bf16(v1[0], v1[1]); w.w = cvt_pk_bf16(v1[2], v1[3]);
;                     *(u32x4*)(rowp + bj * 128) = w; } }
	s_cbranch_scc0 .LBB0_433
	s_nop 0
	s_nop 0
	s_nop 0
	s_nop 0
	s_nop 0
	s_nop 0
	s_nop 0
	s_nop 0
	s_nop 0
	s_nop 0
	s_nop 0
	s_nop 0
	s_nop 0
	s_nop 0
	s_nop 0
	s_nop 0
	s_nop 0
	s_nop 0
	s_nop 0
	s_nop 0
	s_nop 0
	s_nop 0
	s_nop 0
	s_nop 0
	v_lshl_add_u32 v152, s38, 8, v146
	v_max_f32_e32 v120, 0, v120
	v_ashrrev_i32_e32 v153, 31, v152
	v_max_f32_e32 v121, 0, v121
	v_max_f32_e32 v122, 0, v122
	v_lshl_or_b32 v144, s69, 8, v148
	v_lshlrev_b64 v[154:155], 13, v[152:153]
	v_mul_f32_e32 v153, v120, v120
	v_max_f32_e32 v120, 0, v125
	v_ashrrev_i32_e32 v145, 31, v144
	v_max_f32_e32 v124, 0, v124
	v_mul_f32_e32 v125, v121, v121
	v_max_f32_e32 v121, 0, v126
	v_mul_f32_e32 v126, v122, v122
	v_max_f32_e32 v122, 0, v127
	v_max_f32_e32 v123, 0, v123
	v_lshl_add_u64 v[154:155], s[10:11], 0, v[154:155]
	v_lshlrev_b64 v[156:157], 1, v[144:145]
	v_mul_f32_e32 v120, v120, v120
	v_max_f32_e32 v112, 0, v112
	v_lshl_add_u64 v[144:145], v[154:155], 0, v[156:157]
	v_mul_f32_e32 v124, v124, v124
	v_mul_f32_e32 v121, v121, v121
	v_mul_f32_e32 v122, v122, v122
	v_mul_f32_e32 v123, v123, v123
	v_cvt_pk_bf16_f32 v120, v124, v120
	v_max_f32_e32 v113, 0, v113
	v_max_f32_e32 v114, 0, v114
	v_cvt_pk_bf16_f32 v121, v121, v122
	v_cvt_pk_bf16_f32 v122, v153, v125
	v_cvt_pk_bf16_f32 v123, v126, v123
	global_store_dwordx4 v[144:145], v[120:123], off
	s_nop 1
	v_mul_f32_e32 v120, v112, v112
	v_max_f32_e32 v112, 0, v117
	v_max_f32_e32 v116, 0, v116
	v_mul_f32_e32 v117, v113, v113
	v_max_f32_e32 v113, 0, v118
	v_mul_f32_e32 v118, v114, v114
	v_max_f32_e32 v114, 0, v119
	v_max_f32_e32 v115, 0, v115
	v_mul_f32_e32 v112, v112, v112
	v_mul_f32_e32 v116, v116, v116
	v_mul_f32_e32 v113, v113, v113
	v_mul_f32_e32 v114, v114, v114
	v_mul_f32_e32 v115, v115, v115
	v_cvt_pk_bf16_f32 v112, v116, v112
	v_max_f32_e32 v104, 0, v104
	v_cvt_pk_bf16_f32 v113, v113, v114
	v_cvt_pk_bf16_f32 v114, v120, v117
	v_cvt_pk_bf16_f32 v115, v118, v115
	global_store_dwordx4 v[144:145], v[112:115], off offset:256
	s_nop 0
	v_max_f32_e32 v105, 0, v105
	v_or_b32_e32 v112, 16, v152
	v_max_f32_e32 v106, 0, v106
	v_ashrrev_i32_e32 v113, 31, v112
	v_mul_f32_e32 v114, v104, v104
	v_max_f32_e32 v104, 0, v109
	v_lshlrev_b64 v[112:113], 13, v[112:113]
	v_max_f32_e32 v108, 0, v108
	v_mul_f32_e32 v109, v105, v105
	v_max_f32_e32 v105, 0, v110
	v_mul_f32_e32 v110, v106, v106
	v_max_f32_e32 v106, 0, v111
	v_max_f32_e32 v107, 0, v107
	v_lshl_add_u64 v[112:113], s[10:11], 0, v[112:113]
	v_mul_f32_e32 v104, v104, v104
	v_max_f32_e32 v96, 0, v96
	v_lshl_add_u64 v[112:113], v[112:113], 0, v[156:157]
	v_mul_f32_e32 v108, v108, v108
	v_mul_f32_e32 v105, v105, v105
	v_mul_f32_e32 v106, v106, v106
	v_mul_f32_e32 v107, v107, v107
	v_cvt_pk_bf16_f32 v104, v108, v104
	v_max_f32_e32 v97, 0, v97
	v_max_f32_e32 v98, 0, v98
	v_cvt_pk_bf16_f32 v105, v105, v106
	v_cvt_pk_bf16_f32 v106, v114, v109
	v_cvt_pk_bf16_f32 v107, v110, v107
	global_store_dwordx4 v[112:113], v[104:107], off
	s_nop 1
	v_mul_f32_e32 v104, v96, v96
	v_max_f32_e32 v96, 0, v101
	v_max_f32_e32 v100, 0, v100
	v_mul_f32_e32 v101, v97, v97
	v_max_f32_e32 v97, 0, v102
	v_mul_f32_e32 v102, v98, v98
	v_max_f32_e32 v98, 0, v103
	v_max_f32_e32 v99, 0, v99
	v_mul_f32_e32 v96, v96, v96
	v_mul_f32_e32 v100, v100, v100
	v_mul_f32_e32 v97, v97, v97
	v_mul_f32_e32 v98, v98, v98
	v_mul_f32_e32 v99, v99, v99
	v_cvt_pk_bf16_f32 v96, v100, v96
	v_max_f32_e32 v88, 0, v88
	v_cvt_pk_bf16_f32 v97, v97, v98
	v_cvt_pk_bf16_f32 v98, v104, v101
	v_cvt_pk_bf16_f32 v99, v102, v99
	global_store_dwordx4 v[112:113], v[96:99], off offset:256
	s_nop 0
	v_max_f32_e32 v89, 0, v89
	v_or_b32_e32 v96, 32, v152
	v_max_f32_e32 v90, 0, v90
	v_ashrrev_i32_e32 v97, 31, v96
	v_mul_f32_e32 v98, v88, v88
	v_max_f32_e32 v88, 0, v93
	v_lshlrev_b64 v[96:97], 13, v[96:97]
	v_max_f32_e32 v92, 0, v92
	v_mul_f32_e32 v93, v89, v89
	v_max_f32_e32 v89, 0, v94
	v_mul_f32_e32 v94, v90, v90
	v_max_f32_e32 v90, 0, v95
	v_max_f32_e32 v91, 0, v91
	v_lshl_add_u64 v[96:97], s[10:11], 0, v[96:97]
	v_mul_f32_e32 v88, v88, v88
	v_max_f32_e32 v80, 0, v80
	v_lshl_add_u64 v[96:97], v[96:97], 0, v[156:157]
	v_mul_f32_e32 v92, v92, v92
	v_mul_f32_e32 v89, v89, v89
	v_mul_f32_e32 v90, v90, v90
	v_mul_f32_e32 v91, v91, v91
	v_cvt_pk_bf16_f32 v88, v92, v88
	v_max_f32_e32 v81, 0, v81
	v_max_f32_e32 v82, 0, v82
	v_cvt_pk_bf16_f32 v89, v89, v90
	v_cvt_pk_bf16_f32 v90, v98, v93
	v_cvt_pk_bf16_f32 v91, v94, v91
	global_store_dwordx4 v[96:97], v[88:91], off
	s_nop 1
	v_mul_f32_e32 v88, v80, v80
	v_max_f32_e32 v80, 0, v85
	v_max_f32_e32 v84, 0, v84
	v_mul_f32_e32 v85, v81, v81
	v_max_f32_e32 v81, 0, v86
	v_mul_f32_e32 v86, v82, v82
	v_max_f32_e32 v82, 0, v87
	v_max_f32_e32 v83, 0, v83
	v_mul_f32_e32 v80, v80, v80
	v_mul_f32_e32 v84, v84, v84
	v_mul_f32_e32 v81, v81, v81
	v_mul_f32_e32 v82, v82, v82
	v_mul_f32_e32 v83, v83, v83
	v_cvt_pk_bf16_f32 v80, v84, v80
	v_max_f32_e32 v72, 0, v72
	v_cvt_pk_bf16_f32 v81, v81, v82
	v_cvt_pk_bf16_f32 v82, v88, v85
	v_cvt_pk_bf16_f32 v83, v86, v83
	global_store_dwordx4 v[96:97], v[80:83], off offset:256
	s_nop 0
	v_max_f32_e32 v73, 0, v73
	v_or_b32_e32 v80, 48, v152
	v_max_f32_e32 v74, 0, v74
	v_ashrrev_i32_e32 v81, 31, v80
	v_mul_f32_e32 v82, v72, v72
	v_max_f32_e32 v72, 0, v77
	v_lshlrev_b64 v[80:81], 13, v[80:81]
	v_max_f32_e32 v76, 0, v76
	v_mul_f32_e32 v77, v73, v73
	v_max_f32_e32 v73, 0, v78
	v_mul_f32_e32 v78, v74, v74
	v_max_f32_e32 v74, 0, v79
	v_max_f32_e32 v75, 0, v75
	v_lshl_add_u64 v[80:81], s[10:11], 0, v[80:81]
	v_mul_f32_e32 v72, v72, v72
	v_max_f32_e32 v64, 0, v64
	v_max_f32_e32 v65, 0, v65
	v_max_f32_e32 v66, 0, v66
	v_lshl_add_u64 v[80:81], v[80:81], 0, v[156:157]
	v_mul_f32_e32 v76, v76, v76
; __device__ __forceinline__ unsigned cvt_pk_bf16(float lo, float hi) { unsigned r; asm volatile("v_cvt_pk_bf16_f32 %0, %1, %2" : "=v"(r) : "v"(lo), "v"(hi)); return r; }
;     __device__ __forceinline__ void operator()(const f32x4 (&acc)[2][2][4][2], const Unit& u, int ui, int wr, int wc, int fr, int fq) const {
;     ...
;         for (int ai = 0; ai < 2; ++ai)
; #pragma unroll
;             for (int m = 0; m < 4; ++m) { bf16_t* rowp = hid + (size_t)(row0 + ai * 128 + m * 16) * DFF + col0;
; #pragma unroll
;                 for (int bj = 0; bj < 2; ++bj) { f32x4 v0 = acc[ai][bj][m][0], v1 = acc[ai][bj][m][1];
; #pragma unroll
;                     for (int j = 0; j < 4; ++j) { const float a = fmaxf(v0[j], 0.f), b = fmaxf(v1[j], 0.f); v0[j] = a * a; v1[j] = b * b; }
;                     u32x4 w; w.x = cvt_pk_bf16(v0[0], v0[1]); w.y = cvt_pk_bf16(v0[2], v0[3]); w.z = cvt_pk_bf16(v1[0], v1[1]); w.w = cvt_pk_bf16(v1[2], v1[3]);
;                     *(u32x4*)(rowp + bj * 128) = w; } }
	v_mul_f32_e32 v73, v73, v73
	v_mul_f32_e32 v74, v74, v74
	v_mul_f32_e32 v75, v75, v75
	v_cvt_pk_bf16_f32 v72, v76, v72
	v_cvt_pk_bf16_f32 v73, v73, v74
	v_cvt_pk_bf16_f32 v74, v82, v77
	v_cvt_pk_bf16_f32 v75, v78, v75
	global_store_dwordx4 v[80:81], v[72:75], off
	v_max_f32_e32 v68, 0, v68
	v_max_f32_e32 v67, 0, v67
	v_mul_f32_e32 v72, v64, v64
	v_max_f32_e32 v64, 0, v69
	v_mul_f32_e32 v69, v65, v65
	v_max_f32_e32 v65, 0, v70
	v_mul_f32_e32 v70, v66, v66
	v_max_f32_e32 v66, 0, v71
	v_mul_f32_e32 v64, v64, v64
	v_mul_f32_e32 v65, v65, v65
	v_mul_f32_e32 v66, v66, v66
	v_max_f32_e32 v56, 0, v56
	v_mul_f32_e32 v68, v68, v68
	v_mul_f32_e32 v67, v67, v67
	v_cvt_pk_bf16_f32 v64, v68, v64
	v_cvt_pk_bf16_f32 v65, v65, v66
	v_cvt_pk_bf16_f32 v66, v72, v69
	v_max_f32_e32 v57, 0, v57
	v_max_f32_e32 v58, 0, v58
	v_cvt_pk_bf16_f32 v67, v70, v67
	global_store_dwordx4 v[80:81], v[64:67], off offset:256
	s_nop 0
	v_max_f32_e32 v60, 0, v60
	v_mul_f32_e32 v66, v56, v56
	v_max_f32_e32 v56, 0, v61
	v_mul_f32_e32 v61, v57, v57
	v_max_f32_e32 v57, 0, v62
	v_mul_f32_e32 v62, v58, v58
	v_max_f32_e32 v58, 0, v63
	v_mul_f32_e32 v60, v60, v60
	v_mul_f32_e32 v56, v56, v56
	v_max_f32_e32 v59, 0, v59
	v_mul_f32_e32 v57, v57, v57
	v_mul_f32_e32 v58, v58, v58
	v_cvt_pk_bf16_f32 v56, v60, v56
	v_add_co_u32_e32 v60, vcc, s65, v144
	v_max_f32_e32 v48, 0, v48
	v_max_f32_e32 v49, 0, v49
	v_max_f32_e32 v50, 0, v50
	v_mul_f32_e32 v59, v59, v59
	v_cvt_pk_bf16_f32 v57, v57, v58
	v_cvt_pk_bf16_f32 v58, v66, v61
	v_addc_co_u32_e32 v61, vcc, 0, v145, vcc
	v_cvt_pk_bf16_f32 v59, v62, v59
	global_store_dwordx4 v[60:61], v[56:59], off
	v_max_f32_e32 v52, 0, v52
	v_max_f32_e32 v51, 0, v51
	v_mul_f32_e32 v56, v48, v48
	v_max_f32_e32 v48, 0, v53
	v_mul_f32_e32 v53, v49, v49
	v_max_f32_e32 v49, 0, v54
	v_mul_f32_e32 v54, v50, v50
	v_max_f32_e32 v50, 0, v55
	v_mul_f32_e32 v48, v48, v48
	v_mul_f32_e32 v49, v49, v49
	v_mul_f32_e32 v50, v50, v50
	v_max_f32_e32 v40, 0, v40
	v_lshl_add_u64 v[64:65], v[144:145], 0, s[14:15]
	v_mul_f32_e32 v52, v52, v52
	v_mul_f32_e32 v51, v51, v51
	v_cvt_pk_bf16_f32 v48, v52, v48
	v_cvt_pk_bf16_f32 v49, v49, v50
	v_cvt_pk_bf16_f32 v50, v56, v53
	v_max_f32_e32 v41, 0, v41
	v_max_f32_e32 v42, 0, v42
	v_cvt_pk_bf16_f32 v51, v54, v51
	global_store_dwordx4 v[64:65], v[48:51], off offset:256
	s_nop 0
	v_max_f32_e32 v44, 0, v44
	v_mul_f32_e32 v50, v40, v40
	v_max_f32_e32 v40, 0, v45
	v_mul_f32_e32 v45, v41, v41
	v_max_f32_e32 v41, 0, v46
	v_mul_f32_e32 v46, v42, v42
	v_max_f32_e32 v42, 0, v47
	v_mul_f32_e32 v44, v44, v44
	v_mul_f32_e32 v40, v40, v40
	v_max_f32_e32 v43, 0, v43
	v_mul_f32_e32 v41, v41, v41
	v_mul_f32_e32 v42, v42, v42
	v_cvt_pk_bf16_f32 v40, v44, v40
	v_add_co_u32_e32 v44, vcc, s66, v144
	v_max_f32_e32 v32, 0, v32
	v_max_f32_e32 v33, 0, v33
	v_max_f32_e32 v34, 0, v34
	v_mul_f32_e32 v43, v43, v43
	v_cvt_pk_bf16_f32 v41, v41, v42
	v_cvt_pk_bf16_f32 v42, v50, v45
	v_addc_co_u32_e32 v45, vcc, 0, v145, vcc
	v_cvt_pk_bf16_f32 v43, v46, v43
	global_store_dwordx4 v[44:45], v[40:43], off
	v_max_f32_e32 v36, 0, v36
	v_max_f32_e32 v35, 0, v35
	v_mul_f32_e32 v40, v32, v32
	v_max_f32_e32 v32, 0, v37
	v_mul_f32_e32 v37, v33, v33
	v_max_f32_e32 v33, 0, v38
	v_mul_f32_e32 v38, v34, v34
	v_max_f32_e32 v34, 0, v39
	v_mul_f32_e32 v32, v32, v32
	v_mul_f32_e32 v33, v33, v33
	v_mul_f32_e32 v34, v34, v34
	v_max_f32_e32 v24, 0, v24
	v_lshl_add_u64 v[48:49], v[144:145], 0, s[16:17]
	v_mul_f32_e32 v36, v36, v36
	v_mul_f32_e32 v35, v35, v35
	v_cvt_pk_bf16_f32 v32, v36, v32
	v_cvt_pk_bf16_f32 v33, v33, v34
	v_cvt_pk_bf16_f32 v34, v40, v37
	v_max_f32_e32 v25, 0, v25
	v_max_f32_e32 v26, 0, v26
	v_cvt_pk_bf16_f32 v35, v38, v35
	global_store_dwordx4 v[48:49], v[32:35], off offset:256
	s_nop 0
	v_max_f32_e32 v28, 0, v28
	v_mul_f32_e32 v34, v24, v24
	v_max_f32_e32 v24, 0, v29
	v_mul_f32_e32 v29, v25, v25
	v_max_f32_e32 v25, 0, v30
	v_mul_f32_e32 v30, v26, v26
	v_max_f32_e32 v26, 0, v31
	v_mul_f32_e32 v28, v28, v28
	v_mul_f32_e32 v24, v24, v24
	v_max_f32_e32 v27, 0, v27
	v_mul_f32_e32 v25, v25, v25
	v_mul_f32_e32 v26, v26, v26
	v_cvt_pk_bf16_f32 v24, v28, v24
	v_add_co_u32_e32 v28, vcc, s67, v144
	v_max_f32_e32 v16, 0, v16
	v_max_f32_e32 v17, 0, v17
	v_max_f32_e32 v18, 0, v18
	v_mul_f32_e32 v27, v27, v27
	v_cvt_pk_bf16_f32 v25, v25, v26
	v_cvt_pk_bf16_f32 v26, v34, v29
	v_addc_co_u32_e32 v29, vcc, 0, v145, vcc
	v_cvt_pk_bf16_f32 v27, v30, v27
	global_store_dwordx4 v[28:29], v[24:27], off
	v_max_f32_e32 v20, 0, v20
	v_max_f32_e32 v19, 0, v19
	v_mul_f32_e32 v24, v16, v16
	v_max_f32_e32 v16, 0, v21
	v_mul_f32_e32 v21, v17, v17
	v_max_f32_e32 v17, 0, v22
	v_mul_f32_e32 v22, v18, v18
	v_max_f32_e32 v18, 0, v23
	v_mul_f32_e32 v16, v16, v16
	v_mul_f32_e32 v17, v17, v17
	v_mul_f32_e32 v18, v18, v18
	v_max_f32_e32 v8, 0, v8
	v_lshl_add_u64 v[32:33], v[144:145], 0, s[18:19]
	v_mul_f32_e32 v20, v20, v20
	v_mul_f32_e32 v19, v19, v19
	v_cvt_pk_bf16_f32 v16, v20, v16
	v_cvt_pk_bf16_f32 v17, v17, v18
	v_cvt_pk_bf16_f32 v18, v24, v21
	v_max_f32_e32 v9, 0, v9
	v_max_f32_e32 v10, 0, v10
	v_cvt_pk_bf16_f32 v19, v22, v19
	global_store_dwordx4 v[32:33], v[16:19], off offset:256
	s_nop 0
	v_max_f32_e32 v12, 0, v12
	v_mul_f32_e32 v18, v8, v8
	v_max_f32_e32 v8, 0, v13
	v_mul_f32_e32 v13, v9, v9
	v_max_f32_e32 v9, 0, v14
	v_mul_f32_e32 v14, v10, v10
	v_max_f32_e32 v10, 0, v15
	v_mul_f32_e32 v12, v12, v12
	v_mul_f32_e32 v8, v8, v8
	v_max_f32_e32 v11, 0, v11
	v_mul_f32_e32 v9, v9, v9
	v_mul_f32_e32 v10, v10, v10
	v_cvt_pk_bf16_f32 v8, v12, v8
	v_add_co_u32_e32 v12, vcc, s68, v144
	v_max_f32_e32 v0, 0, v0
	v_max_f32_e32 v1, 0, v1
	v_max_f32_e32 v2, 0, v2
	v_mul_f32_e32 v11, v11, v11
	v_cvt_pk_bf16_f32 v9, v9, v10
	v_cvt_pk_bf16_f32 v10, v18, v13
	v_addc_co_u32_e32 v13, vcc, 0, v145, vcc
	v_cvt_pk_bf16_f32 v11, v14, v11
	global_store_dwordx4 v[12:13], v[8:11], off
	v_max_f32_e32 v3, 0, v3
	v_max_f32_e32 v4, 0, v4
	v_mul_f32_e32 v8, v0, v0
	v_max_f32_e32 v0, 0, v5
	v_mul_f32_e32 v5, v1, v1
	v_max_f32_e32 v1, 0, v6
	v_mul_f32_e32 v6, v2, v2
	v_max_f32_e32 v2, 0, v7
	v_lshl_add_u64 v[16:17], v[144:145], 0, s[20:21]
	v_mul_f32_e32 v0, v0, v0
	v_mul_f32_e32 v1, v1, v1
	v_mul_f32_e32 v2, v2, v2
	v_mul_f32_e32 v3, v3, v3
	s_and_b64 vcc, exec, s[4:5]
	s_mov_b32 s69, s22
	s_mov_b32 s38, s24
	s_mov_b64 s[40:41], s[0:1]
	s_mov_b64 s[42:43], s[36:37]
	v_mul_f32_e32 v4, v4, v4
	v_cvt_pk_bf16_f32 v0, v4, v0
	v_cvt_pk_bf16_f32 v1, v1, v2
	v_cvt_pk_bf16_f32 v2, v8, v5
	v_cvt_pk_bf16_f32 v3, v6, v3
	global_store_dwordx4 v[16:17], v[0:3], off offset:256
	s_cbranch_vccz .LBB0_428
	s_waitcnt vmcnt(0)
	s_cmpk_gt_u32 s46, 0xff
	s_cbranch_scc1 .LBB0_437
	s_barrier

; #define PG8_STAGE(bufoff, gbase, voff) do { _Pragma("unroll") for (int _i = 0; _i < 2; ++_i) \
;         __builtin_amdgcn_global_load_lds((const unsigned*)((const char*)(gbase) + (voff)[_i]), (LAS unsigned*)(lds + (bufoff) + ldsw + _i * 8192), 16, 0, 0); } while (0)
; #define PG8_LDA(dst, b, h) do { _Pragma("unroll") for (int m = 0; m < 4; ++m) _Pragma("unroll") for (int k = 0; k < 2; ++k) dst[m][k] = *(const LAS bf16x8*)(lds + PG8_SA(b, h) + aoff + m * 2048 + k * 1024); } while (0)
; #define PG8_LDB(dst, b, h) do { _Pragma("unroll") for (int n = 0; n < 2; ++n) _Pragma("unroll") for (int k = 0; k < 2; ++k) dst[n][k] = *(const LAS bf16x8*)(lds + PG8_SB(b, h) + boff + n * 2048 + k * 1024); } while (0)
; #define PG8_MMA(ai, bj, At, Bt) do { __builtin_amdgcn_s_setprio(1); _Pragma("unroll") for (int m = 0; m < 4; ++m) _Pragma("unroll") for (int n = 0; n < 2; ++n) _Pragma("unroll") for (int k = 0; k < 2; ++k) \
;         acc[ai][bj][m][n] = __builtin_amdgcn_mfma_f32_16x16x32_bf16(Bt[n][k], At[m][k], acc[ai][bj][m][n], 0, 0, 0); __builtin_amdgcn_s_setprio(0); } while (0)
; #define PG8_WAIT_L(n) asm volatile("s_waitcnt lgkmcnt(" #n ")" ::: "memory")
; #define PG8_BAR __builtin_amdgcn_s_barrier()
; #define PG8_SCHED __builtin_amdgcn_sched_barrier(0)
; template <class Epi, class Ptrs>
; __device__ __forceinline__ void gemm_phase(LAS unsigned char* lds, const int K, const StaticOrder& S, const Ptrs& P, const Epi& E) {
;     ...
;         for (int t = 0; t < nt; t += 2) {
;             const bool last = (t == nt - 2);
;             const char* a1 = cA + (size_t)(t + 1) * kstep;
;             const char* a2 = last ? nA : cA + (size_t)(t + 2) * kstep; const char* b2 = last ? nB : cB + (size_t)(t + 2) * kstep;
;             const char* a3 = a2 + kstep; const char* b3 = b2 + kstep;
;             PG8_LDB(B0, 0, 0); PG8_SCHED; PG8_LDA(At, 0, 0); PG8_STAGE(PG8_SA(1, 1), a1 + hstep, voffA);
;             PG8_WAIT_L(8); PG8_BAR; PG8_WAIT_L(0); PG8_MMA(0, 0, At, B0); PG8_BAR; PG8_SCHED;
;     ...
;         for (int a = 0; a < 2; ++a)
; #pragma unroll
;             for (int b = 0; b < 2; ++b)
; #pragma unroll
;                 for (int m = 0; m < 4; ++m)
; #pragma unroll
;                     for (int n = 0; n < 2; ++n) acc[a][b][m][n] = (f32x4){0.f, 0.f, 0.f, 0.f};
;         cur = nxt; cA = nA; cB = nB; ++ui;
.LBB0_521:
	s_add_u32 s20, s20, 0x100080
	s_nop 0
	s_nop 0
	s_nop 0
	s_nop 0
	s_nop 0
	s_nop 0
	s_nop 0
	s_nop 0
	s_nop 0
	s_nop 0
	s_nop 0
	s_nop 0
	s_nop 0
	s_nop 0
	s_nop 0
	s_nop 0
	s_nop 0
	s_nop 0
	s_nop 0
	s_nop 0
	s_nop 0
	s_nop 0
	s_nop 0
	s_nop 0
	s_nop 0
	s_nop 0
	s_nop 0
	s_nop 0
	s_nop 0
	s_nop 0
	s_nop 0
	s_nop 0
	s_nop 0
	s_nop 0
	s_nop 0
	s_nop 0
	s_nop 0
	s_nop 0
	s_nop 0
	s_nop 0
	s_nop 0
	s_nop 0
	s_nop 0
	s_nop 0
	s_nop 0
	s_nop 0
	s_nop 0
	s_nop 0
	s_nop 0
	s_nop 0
	s_nop 0
	s_nop 0
	s_nop 0
	s_nop 0
	s_nop 0
	s_nop 0
	s_nop 0
	s_nop 0
	s_nop 0
	s_nop 0
	s_addc_u32 s21, s21, 0
	s_add_u32 s11, s22, 0x100
	v_mov_b32_e32 v0, 0
	s_addc_u32 s13, s23, 0
	s_mov_b32 s46, -2
	v_mov_b32_e32 v1, v0
	v_mov_b32_e32 v2, v0
	v_mov_b32_e32 v3, v0
	v_mov_b32_e32 v4, v0
	v_mov_b32_e32 v5, v0
	v_mov_b32_e32 v6, v0
	v_mov_b32_e32 v7, v0
	v_mov_b32_e32 v12, v0
	v_mov_b32_e32 v13, v0
	v_mov_b32_e32 v14, v0
	v_mov_b32_e32 v15, v0
	v_mov_b32_e32 v20, v0
	v_mov_b32_e32 v21, v0
	v_mov_b32_e32 v22, v0
	v_mov_b32_e32 v23, v0
	v_mov_b32_e32 v28, v0
	v_mov_b32_e32 v29, v0
	v_mov_b32_e32 v30, v0
	v_mov_b32_e32 v31, v0
	v_mov_b32_e32 v36, v0
	v_mov_b32_e32 v37, v0
	v_mov_b32_e32 v38, v0
	v_mov_b32_e32 v39, v0
	v_mov_b32_e32 v44, v0
	v_mov_b32_e32 v45, v0
	v_mov_b32_e32 v46, v0
	v_mov_b32_e32 v47, v0
	v_mov_b32_e32 v52, v0
	v_mov_b32_e32 v53, v0
	v_mov_b32_e32 v54, v0
	v_mov_b32_e32 v55, v0
	v_mov_b32_e32 v8, v0
	v_mov_b32_e32 v9, v0
	v_mov_b32_e32 v10, v0
	v_mov_b32_e32 v11, v0
	v_mov_b32_e32 v16, v0
	v_mov_b32_e32 v17, v0
	v_mov_b32_e32 v18, v0
	v_mov_b32_e32 v19, v0
	v_mov_b32_e32 v24, v0
	v_mov_b32_e32 v25, v0
	v_mov_b32_e32 v26, v0
	v_mov_b32_e32 v27, v0
	v_mov_b32_e32 v32, v0
	v_mov_b32_e32 v33, v0
	v_mov_b32_e32 v34, v0
	v_mov_b32_e32 v35, v0
	v_mov_b32_e32 v40, v0
	v_mov_b32_e32 v41, v0
	v_mov_b32_e32 v42, v0
	v_mov_b32_e32 v43, v0
	v_mov_b32_e32 v48, v0
	v_mov_b32_e32 v49, v0
	v_mov_b32_e32 v50, v0
	v_mov_b32_e32 v51, v0
	v_mov_b32_e32 v56, v0
	v_mov_b32_e32 v57, v0
	v_mov_b32_e32 v58, v0
	v_mov_b32_e32 v59, v0
	v_mov_b32_e32 v60, v0
	v_mov_b32_e32 v61, v0
	v_mov_b32_e32 v62, v0
	v_mov_b32_e32 v63, v0
	v_mov_b32_e32 v64, v0
	v_mov_b32_e32 v65, v0
	v_mov_b32_e32 v66, v0
	v_mov_b32_e32 v67, v0
	v_mov_b32_e32 v68, v0
	v_mov_b32_e32 v69, v0
	v_mov_b32_e32 v70, v0
	v_mov_b32_e32 v71, v0
	v_mov_b32_e32 v80, v0
	v_mov_b32_e32 v81, v0
	v_mov_b32_e32 v82, v0
	v_mov_b32_e32 v83, v0
	v_mov_b32_e32 v84, v0
	v_mov_b32_e32 v85, v0
	v_mov_b32_e32 v86, v0
	v_mov_b32_e32 v87, v0
	v_mov_b32_e32 v96, v0
	v_mov_b32_e32 v97, v0
	v_mov_b32_e32 v98, v0
	v_mov_b32_e32 v99, v0
	v_mov_b32_e32 v100, v0
	v_mov_b32_e32 v101, v0
	v_mov_b32_e32 v102, v0
	v_mov_b32_e32 v103, v0
	v_mov_b32_e32 v108, v0
	v_mov_b32_e32 v109, v0
	v_mov_b32_e32 v110, v0
	v_mov_b32_e32 v111, v0
	v_mov_b32_e32 v116, v0
	v_mov_b32_e32 v117, v0
	v_mov_b32_e32 v118, v0
	v_mov_b32_e32 v119, v0
	v_mov_b32_e32 v72, v0
	v_mov_b32_e32 v73, v0
	v_mov_b32_e32 v74, v0
	v_mov_b32_e32 v75, v0
	v_mov_b32_e32 v76, v0
	v_mov_b32_e32 v77, v0
	v_mov_b32_e32 v78, v0
	v_mov_b32_e32 v79, v0
	v_mov_b32_e32 v88, v0
	v_mov_b32_e32 v89, v0
	v_mov_b32_e32 v90, v0
	v_mov_b32_e32 v91, v0
	v_mov_b32_e32 v92, v0
	v_mov_b32_e32 v93, v0
	v_mov_b32_e32 v94, v0
	v_mov_b32_e32 v95, v0
	v_mov_b32_e32 v104, v0
	v_mov_b32_e32 v105, v0
	v_mov_b32_e32 v106, v0
	v_mov_b32_e32 v107, v0
	v_mov_b32_e32 v112, v0
	v_mov_b32_e32 v113, v0
	v_mov_b32_e32 v114, v0
	v_mov_b32_e32 v115, v0
	v_mov_b32_e32 v120, v0
	v_mov_b32_e32 v121, v0
	v_mov_b32_e32 v122, v0
	v_mov_b32_e32 v123, v0
	v_mov_b32_e32 v124, v0
	v_mov_b32_e32 v125, v0
	v_mov_b32_e32 v126, v0
	v_add_u32_e32 v252, 0x18000, v187
	v_add_u32_e32 v253, 0x1c000, v187
	v_mov_b32_e32 v127, v0
.LBB0_522:
	s_add_u32 s22, s20, 0xfff00080
	s_addc_u32 s23, s21, -1
	s_cmp_eq_u32 s46, 60
	s_cselect_b32 s25, s5, s23
	s_cselect_b32 s24, s4, s22
	s_cselect_b32 s23, s15, s13
	s_cselect_b32 s22, s14, s11
	s_add_i32 m0, s17, 0xc000
	s_nop 0
	global_load_lds_dwordx4 v168, s[20:21]
	s_add_i32 m0, s17, 0xe000
	s_nop 0
	global_load_lds_dwordx4 v170, s[20:21]
	ds_read_b128 v[128:131], v193
	ds_read_b128 v[132:135], v193 offset:1024
	ds_read_b128 v[136:139], v193 offset:2048
	ds_read_b128 v[140:143], v193 offset:3072
	ds_read_b128 v[144:147], v194
	ds_read_b128 v[148:151], v194 offset:1024
	ds_read_b128 v[152:155], v194 offset:2048
	ds_read_b128 v[156:159], v194 offset:3072
	ds_read_b128 v[176:179], v194 offset:4096
	ds_read_b128 v[180:183], v194 offset:5120
	ds_read_b128 v[196:199], v194 offset:6144
	ds_read_b128 v[200:203], v194 offset:7168
	s_waitcnt lgkmcnt(8)
	s_barrier
	s_waitcnt lgkmcnt(0)
	s_setprio 1
	s_waitcnt lgkmcnt(0)
	v_mfma_f32_16x16x32_bf16 v[124:127], v[128:131], v[144:147], v[124:127]
	v_mfma_f32_16x16x32_bf16 v[124:127], v[132:135], v[148:151], v[124:127]
	v_mfma_f32_16x16x32_bf16 v[120:123], v[140:143], v[148:151], v[120:123]
	v_mfma_f32_16x16x32_bf16 v[120:123], v[136:139], v[144:147], v[120:123]
	v_mfma_f32_16x16x32_bf16 v[104:107], v[136:139], v[152:155], v[104:107]
	v_mfma_f32_16x16x32_bf16 v[104:107], v[140:143], v[156:159], v[104:107]
	v_mfma_f32_16x16x32_bf16 v[112:115], v[132:135], v[156:159], v[112:115]
	v_mfma_f32_16x16x32_bf16 v[112:115], v[128:131], v[152:155], v[112:115]
	v_mfma_f32_16x16x32_bf16 v[92:95], v[128:131], v[176:179], v[92:95]
	v_mfma_f32_16x16x32_bf16 v[92:95], v[132:135], v[180:183], v[92:95]
	v_mfma_f32_16x16x32_bf16 v[88:91], v[140:143], v[180:183], v[88:91]
	v_mfma_f32_16x16x32_bf16 v[88:91], v[136:139], v[176:179], v[88:91]
	v_mfma_f32_16x16x32_bf16 v[72:75], v[136:139], v[196:199], v[72:75]
	v_mfma_f32_16x16x32_bf16 v[72:75], v[140:143], v[200:203], v[72:75]
	v_mfma_f32_16x16x32_bf16 v[76:79], v[132:135], v[200:203], v[76:79]
	v_mfma_f32_16x16x32_bf16 v[76:79], v[128:131], v[196:199], v[76:79]
	s_setprio 0
	s_barrier
; #define PG8_STAGE(bufoff, gbase, voff) do { _Pragma("unroll") for (int _i = 0; _i < 2; ++_i) \
;         __builtin_amdgcn_global_load_lds((const unsigned*)((const char*)(gbase) + (voff)[_i]), (LAS unsigned*)(lds + (bufoff) + ldsw + _i * 8192), 16, 0, 0); } while (0)
; #define PG8_LDA(dst, b, h) do { _Pragma("unroll") for (int m = 0; m < 4; ++m) _Pragma("unroll") for (int k = 0; k < 2; ++k) dst[m][k] = *(const LAS bf16x8*)(lds + PG8_SA(b, h) + aoff + m * 2048 + k * 1024); } while (0)
; #define PG8_LDB(dst, b, h) do { _Pragma("unroll") for (int n = 0; n < 2; ++n) _Pragma("unroll") for (int k = 0; k < 2; ++k) dst[n][k] = *(const LAS bf16x8*)(lds + PG8_SB(b, h) + boff + n * 2048 + k * 1024); } while (0)
; #define PG8_MMA(ai, bj, At, Bt) do { __builtin_amdgcn_s_setprio(1); _Pragma("unroll") for (int m = 0; m < 4; ++m) _Pragma("unroll") for (int n = 0; n < 2; ++n) _Pragma("unroll") for (int k = 0; k < 2; ++k) \
;         acc[ai][bj][m][n] = __builtin_amdgcn_mfma_f32_16x16x32_bf16(Bt[n][k], At[m][k], acc[ai][bj][m][n], 0, 0, 0); __builtin_amdgcn_s_setprio(0); } while (0)
; #define PG8_WAIT_V(n) asm volatile("s_waitcnt vmcnt(" #n ")" ::: "memory")
; #define PG8_WAIT_L(n) asm volatile("s_waitcnt lgkmcnt(" #n ")" ::: "memory")
; #define PG8_BAR __builtin_amdgcn_s_barrier()
; #define PG8_SCHED __builtin_amdgcn_sched_barrier(0)
; template <class Epi, class Ptrs>
; __device__ __forceinline__ void gemm_phase(LAS unsigned char* lds, const int K, const StaticOrder& S, const Ptrs& P, const Epi& E) {
;     ...
;             PG8_LDB(B1, 0, 1); PG8_STAGE(PG8_SB(0, 0), b2, voffB);
;             PG8_BAR; PG8_WAIT_L(0); PG8_MMA(0, 1, At, B1); PG8_BAR;
;             PG8_LDA(At, 0, 1); PG8_STAGE(PG8_SA(0, 0), a2, voffA);
;             PG8_BAR; PG8_WAIT_L(0); PG8_MMA(1, 0, At, B0); PG8_BAR; PG8_SCHED;
;             PG8_STAGE(PG8_SB(0, 1), b2 + hstep, voffB);
;             PG8_WAIT_V(6); PG8_BAR; PG8_MMA(1, 1, At, B1); PG8_BAR;
;             PG8_LDB(B0, 1, 0); PG8_SCHED; PG8_LDA(At, 1, 0); PG8_STAGE(PG8_SA(0, 1), a2 + hstep, voffA);
;             PG8_WAIT_L(8); PG8_BAR; PG8_WAIT_L(0); PG8_MMA(0, 0, At, B0); PG8_BAR; PG8_SCHED;
	s_add_i32 s47, s42, s34
	s_add_u32 s90, s22, 0x80
	s_addc_u32 s91, s23, 0
	s_mov_b32 m0, s47
	s_nop 0
	global_load_lds_dwordx4 v162, s[22:23]
	s_add_i32 m0, s47, 0x2000
	s_nop 0
	global_load_lds_dwordx4 v166, s[22:23]
	ds_read_b128 v[204:207], v195
	ds_read_b128 v[208:211], v195 offset:1024
	ds_read_b128 v[212:215], v195 offset:2048
	ds_read_b128 v[216:219], v195 offset:3072
	s_barrier
	s_waitcnt lgkmcnt(0)
	s_setprio 1
	s_waitcnt lgkmcnt(0)
	v_mfma_f32_16x16x32_bf16 v[116:119], v[204:207], v[144:147], v[116:119]
	v_mfma_f32_16x16x32_bf16 v[116:119], v[208:211], v[148:151], v[116:119]
	v_mfma_f32_16x16x32_bf16 v[108:111], v[216:219], v[148:151], v[108:111]
	v_mfma_f32_16x16x32_bf16 v[108:111], v[212:215], v[144:147], v[108:111]
	v_mfma_f32_16x16x32_bf16 v[96:99], v[212:215], v[152:155], v[96:99]
	v_mfma_f32_16x16x32_bf16 v[96:99], v[216:219], v[156:159], v[96:99]
	v_mfma_f32_16x16x32_bf16 v[100:103], v[208:211], v[156:159], v[100:103]
	v_mfma_f32_16x16x32_bf16 v[100:103], v[204:207], v[152:155], v[100:103]
	v_mfma_f32_16x16x32_bf16 v[84:87], v[204:207], v[176:179], v[84:87]
	v_mfma_f32_16x16x32_bf16 v[84:87], v[208:211], v[180:183], v[84:87]
	v_mfma_f32_16x16x32_bf16 v[80:83], v[216:219], v[180:183], v[80:83]
	v_mfma_f32_16x16x32_bf16 v[80:83], v[212:215], v[176:179], v[80:83]
	v_mfma_f32_16x16x32_bf16 v[64:67], v[212:215], v[196:199], v[64:67]
	v_mfma_f32_16x16x32_bf16 v[64:67], v[216:219], v[200:203], v[64:67]
	v_mfma_f32_16x16x32_bf16 v[68:71], v[208:211], v[200:203], v[68:71]
	v_mfma_f32_16x16x32_bf16 v[68:71], v[204:207], v[196:199], v[68:71]
	s_setprio 0
	s_mov_b32 m0, s17
	s_add_u32 s92, s24, 0x80
	s_addc_u32 s93, s25, 0
	s_barrier
	global_load_lds_dwordx4 v160, s[24:25]
	s_mov_b32 m0, s19
	s_nop 0
	global_load_lds_dwordx4 v164, s[24:25]
	ds_read_b128 v[144:147], v194 offset:16384
	ds_read_b128 v[148:151], v194 offset:17408
	ds_read_b128 v[152:155], v194 offset:18432
	ds_read_b128 v[156:159], v194 offset:19456
	ds_read_b128 v[176:179], v194 offset:20480
	ds_read_b128 v[180:183], v194 offset:21504
	ds_read_b128 v[196:199], v194 offset:22528
	ds_read_b128 v[200:203], v194 offset:23552
	s_barrier
	s_waitcnt lgkmcnt(0)
	s_setprio 1
	s_waitcnt lgkmcnt(0)
	v_mfma_f32_16x16x32_bf16 v[60:63], v[128:131], v[144:147], v[60:63]
	v_mfma_f32_16x16x32_bf16 v[60:63], v[132:135], v[148:151], v[60:63]
	v_mfma_f32_16x16x32_bf16 v[56:59], v[140:143], v[148:151], v[56:59]
	v_mfma_f32_16x16x32_bf16 v[56:59], v[136:139], v[144:147], v[56:59]
	v_mfma_f32_16x16x32_bf16 v[40:43], v[136:139], v[152:155], v[40:43]
	v_mfma_f32_16x16x32_bf16 v[40:43], v[140:143], v[156:159], v[40:43]
	v_mfma_f32_16x16x32_bf16 v[48:51], v[132:135], v[156:159], v[48:51]
	v_mfma_f32_16x16x32_bf16 v[48:51], v[128:131], v[152:155], v[48:51]
	v_mfma_f32_16x16x32_bf16 v[32:35], v[128:131], v[176:179], v[32:35]
	v_mfma_f32_16x16x32_bf16 v[32:35], v[132:135], v[180:183], v[32:35]
	v_mfma_f32_16x16x32_bf16 v[24:27], v[140:143], v[180:183], v[24:27]
	v_mfma_f32_16x16x32_bf16 v[24:27], v[136:139], v[176:179], v[24:27]
	v_mfma_f32_16x16x32_bf16 v[8:11], v[136:139], v[196:199], v[8:11]
	v_mfma_f32_16x16x32_bf16 v[8:11], v[140:143], v[200:203], v[8:11]
	v_mfma_f32_16x16x32_bf16 v[16:19], v[132:135], v[200:203], v[16:19]
	v_mfma_f32_16x16x32_bf16 v[16:19], v[128:131], v[196:199], v[16:19]
	s_setprio 0
	s_barrier
	s_add_u32 s48, s22, 0x100000
	s_addc_u32 s49, s23, 0
	s_add_i32 s47, s43, s34
	s_mov_b32 m0, s47
	s_nop 0
	global_load_lds_dwordx4 v162, s[48:49]
	s_add_i32 m0, s47, 0x2000
	s_nop 0
	global_load_lds_dwordx4 v166, s[48:49]
	s_waitcnt vmcnt(6)
	s_barrier
	s_setprio 1
	v_mfma_f32_16x16x32_bf16 v[52:55], v[204:207], v[144:147], v[52:55]
	v_mfma_f32_16x16x32_bf16 v[52:55], v[208:211], v[148:151], v[52:55]
	v_mfma_f32_16x16x32_bf16 v[44:47], v[216:219], v[148:151], v[44:47]
	v_mfma_f32_16x16x32_bf16 v[44:47], v[212:215], v[144:147], v[44:47]
	v_mfma_f32_16x16x32_bf16 v[28:31], v[212:215], v[152:155], v[28:31]
	v_mfma_f32_16x16x32_bf16 v[28:31], v[216:219], v[156:159], v[28:31]
	v_mfma_f32_16x16x32_bf16 v[36:39], v[208:211], v[156:159], v[36:39]
	v_mfma_f32_16x16x32_bf16 v[36:39], v[204:207], v[152:155], v[36:39]
	v_mfma_f32_16x16x32_bf16 v[20:23], v[204:207], v[176:179], v[20:23]
	v_mfma_f32_16x16x32_bf16 v[20:23], v[208:211], v[180:183], v[20:23]
	v_mfma_f32_16x16x32_bf16 v[12:15], v[216:219], v[180:183], v[12:15]
	v_mfma_f32_16x16x32_bf16 v[12:15], v[212:215], v[176:179], v[12:15]
	v_mfma_f32_16x16x32_bf16 v[0:3], v[212:215], v[196:199], v[0:3]
	v_mfma_f32_16x16x32_bf16 v[0:3], v[216:219], v[200:203], v[0:3]
	v_mfma_f32_16x16x32_bf16 v[4:7], v[208:211], v[200:203], v[4:7]
	v_mfma_f32_16x16x32_bf16 v[4:7], v[204:207], v[196:199], v[4:7]
	s_setprio 0
	s_add_i32 s47, 0, 0x18000
	s_barrier
	s_add_u32 s24, s24, 0x100000
	s_addc_u32 s25, s25, 0
	s_mov_b32 m0, s40
	s_nop 0
	global_load_lds_dwordx4 v160, s[24:25]
	s_mov_b32 m0, s41
	s_nop 0
	global_load_lds_dwordx4 v164, s[24:25]
	ds_read_b128 v[128:131], v252
	ds_read_b128 v[132:135], v252 offset:1024
	ds_read_b128 v[136:139], v252 offset:2048
	ds_read_b128 v[140:143], v252 offset:3072
	ds_read_b128 v[144:147], v194 offset:32768
	ds_read_b128 v[148:151], v194 offset:33792
	ds_read_b128 v[152:155], v194 offset:34816
	ds_read_b128 v[156:159], v194 offset:35840
	ds_read_b128 v[176:179], v194 offset:36864
	ds_read_b128 v[180:183], v194 offset:37888
	ds_read_b128 v[196:199], v194 offset:38912
	ds_read_b128 v[200:203], v194 offset:39936
	s_waitcnt lgkmcnt(8)
	s_barrier
; #define PG8_STAGE(bufoff, gbase, voff) do { _Pragma("unroll") for (int _i = 0; _i < 2; ++_i) \
;         __builtin_amdgcn_global_load_lds((const unsigned*)((const char*)(gbase) + (voff)[_i]), (LAS unsigned*)(lds + (bufoff) + ldsw + _i * 8192), 16, 0, 0); } while (0)
; #define PG8_LDA(dst, b, h) do { _Pragma("unroll") for (int m = 0; m < 4; ++m) _Pragma("unroll") for (int k = 0; k < 2; ++k) dst[m][k] = *(const LAS bf16x8*)(lds + PG8_SA(b, h) + aoff + m * 2048 + k * 1024); } while (0)
; #define PG8_LDB(dst, b, h) do { _Pragma("unroll") for (int n = 0; n < 2; ++n) _Pragma("unroll") for (int k = 0; k < 2; ++k) dst[n][k] = *(const LAS bf16x8*)(lds + PG8_SB(b, h) + boff + n * 2048 + k * 1024); } while (0)
; #define PG8_MMA(ai, bj, At, Bt) do { __builtin_amdgcn_s_setprio(1); _Pragma("unroll") for (int m = 0; m < 4; ++m) _Pragma("unroll") for (int n = 0; n < 2; ++n) _Pragma("unroll") for (int k = 0; k < 2; ++k) \
;         acc[ai][bj][m][n] = __builtin_amdgcn_mfma_f32_16x16x32_bf16(Bt[n][k], At[m][k], acc[ai][bj][m][n], 0, 0, 0); __builtin_amdgcn_s_setprio(0); } while (0)
; #define PG8_WAIT_V(n) asm volatile("s_waitcnt vmcnt(" #n ")" ::: "memory")
; #define PG8_WAIT_L(n) asm volatile("s_waitcnt lgkmcnt(" #n ")" ::: "memory")
; #define PG8_BAR __builtin_amdgcn_s_barrier()
; #define PG8_SCHED __builtin_amdgcn_sched_barrier(0)
; template <class Epi, class Ptrs>
; __device__ __forceinline__ void gemm_phase(LAS unsigned char* lds, const int K, const StaticOrder& S, const Ptrs& P, const Epi& E) {
;     ...
;             PG8_WAIT_L(8); PG8_BAR; PG8_WAIT_L(0); PG8_MMA(0, 0, At, B0); PG8_BAR; PG8_SCHED;
;             PG8_LDB(B1, 1, 1); PG8_STAGE(PG8_SB(1, 0), b3, voffB);
;             PG8_BAR; PG8_WAIT_L(0); PG8_MMA(0, 1, At, B1); PG8_BAR;
;             PG8_LDA(At, 1, 1); PG8_STAGE(PG8_SA(1, 0), a3, voffA);
;             PG8_BAR; PG8_WAIT_L(0); PG8_MMA(1, 0, At, B0); PG8_BAR; PG8_SCHED;
;             PG8_STAGE(PG8_SB(1, 1), b3 + hstep, voffB);
;             PG8_WAIT_V(6); PG8_BAR; PG8_MMA(1, 1, At, B1); PG8_BAR;
	s_waitcnt lgkmcnt(0)
	s_setprio 1
	s_waitcnt lgkmcnt(0)
	v_mfma_f32_16x16x32_bf16 v[124:127], v[128:131], v[144:147], v[124:127]
	v_mfma_f32_16x16x32_bf16 v[124:127], v[132:135], v[148:151], v[124:127]
	v_mfma_f32_16x16x32_bf16 v[120:123], v[140:143], v[148:151], v[120:123]
	v_mfma_f32_16x16x32_bf16 v[120:123], v[136:139], v[144:147], v[120:123]
	v_mfma_f32_16x16x32_bf16 v[104:107], v[136:139], v[152:155], v[104:107]
	v_mfma_f32_16x16x32_bf16 v[104:107], v[140:143], v[156:159], v[104:107]
	v_mfma_f32_16x16x32_bf16 v[112:115], v[132:135], v[156:159], v[112:115]
	v_mfma_f32_16x16x32_bf16 v[112:115], v[128:131], v[152:155], v[112:115]
	v_mfma_f32_16x16x32_bf16 v[92:95], v[128:131], v[176:179], v[92:95]
	v_mfma_f32_16x16x32_bf16 v[92:95], v[132:135], v[180:183], v[92:95]
	v_mfma_f32_16x16x32_bf16 v[88:91], v[140:143], v[180:183], v[88:91]
	v_mfma_f32_16x16x32_bf16 v[88:91], v[136:139], v[176:179], v[88:91]
	v_mfma_f32_16x16x32_bf16 v[72:75], v[136:139], v[196:199], v[72:75]
	v_mfma_f32_16x16x32_bf16 v[72:75], v[140:143], v[200:203], v[72:75]
	v_mfma_f32_16x16x32_bf16 v[76:79], v[132:135], v[200:203], v[76:79]
	v_mfma_f32_16x16x32_bf16 v[76:79], v[128:131], v[196:199], v[76:79]
	s_setprio 0
	s_barrier
	s_add_i32 s24, 0, 0x1c000
	s_add_i32 s25, s47, s34
	s_mov_b32 m0, s25
	s_nop 0
	global_load_lds_dwordx4 v162, s[90:91]
	s_add_i32 m0, s25, 0x2000
	s_nop 0
	global_load_lds_dwordx4 v166, s[90:91]
	ds_read_b128 v[204:207], v253
	ds_read_b128 v[208:211], v253 offset:1024
	ds_read_b128 v[212:215], v253 offset:2048
	ds_read_b128 v[216:219], v253 offset:3072
	s_barrier
	s_waitcnt lgkmcnt(0)
	s_setprio 1
	s_waitcnt lgkmcnt(0)
	v_mfma_f32_16x16x32_bf16 v[116:119], v[204:207], v[144:147], v[116:119]
	v_mfma_f32_16x16x32_bf16 v[116:119], v[208:211], v[148:151], v[116:119]
	v_mfma_f32_16x16x32_bf16 v[108:111], v[216:219], v[148:151], v[108:111]
	v_mfma_f32_16x16x32_bf16 v[108:111], v[212:215], v[144:147], v[108:111]
	v_mfma_f32_16x16x32_bf16 v[96:99], v[212:215], v[152:155], v[96:99]
	v_mfma_f32_16x16x32_bf16 v[96:99], v[216:219], v[156:159], v[96:99]
	v_mfma_f32_16x16x32_bf16 v[100:103], v[208:211], v[156:159], v[100:103]
	v_mfma_f32_16x16x32_bf16 v[100:103], v[204:207], v[152:155], v[100:103]
	v_mfma_f32_16x16x32_bf16 v[84:87], v[204:207], v[176:179], v[84:87]
	v_mfma_f32_16x16x32_bf16 v[84:87], v[208:211], v[180:183], v[84:87]
	v_mfma_f32_16x16x32_bf16 v[80:83], v[216:219], v[180:183], v[80:83]
	v_mfma_f32_16x16x32_bf16 v[80:83], v[212:215], v[176:179], v[80:83]
	v_mfma_f32_16x16x32_bf16 v[64:67], v[212:215], v[196:199], v[64:67]
	v_mfma_f32_16x16x32_bf16 v[64:67], v[216:219], v[200:203], v[64:67]
	v_mfma_f32_16x16x32_bf16 v[68:71], v[208:211], v[200:203], v[68:71]
	v_mfma_f32_16x16x32_bf16 v[68:71], v[204:207], v[196:199], v[68:71]
	s_setprio 0
	s_mov_b32 m0, s28
	s_barrier
	global_load_lds_dwordx4 v160, s[92:93]
	s_mov_b32 m0, s29
	s_nop 0
	global_load_lds_dwordx4 v164, s[92:93]
	ds_read_b128 v[144:147], v194 offset:49152
	ds_read_b128 v[148:151], v194 offset:50176
	ds_read_b128 v[152:155], v194 offset:51200
	ds_read_b128 v[156:159], v194 offset:52224
	ds_read_b128 v[176:179], v194 offset:53248
	ds_read_b128 v[180:183], v194 offset:54272
	ds_read_b128 v[196:199], v194 offset:55296
	ds_read_b128 v[200:203], v194 offset:56320
	s_barrier
	s_waitcnt lgkmcnt(0)
	s_setprio 1
	s_waitcnt lgkmcnt(0)
	v_mfma_f32_16x16x32_bf16 v[60:63], v[128:131], v[144:147], v[60:63]
	v_mfma_f32_16x16x32_bf16 v[60:63], v[132:135], v[148:151], v[60:63]
	v_mfma_f32_16x16x32_bf16 v[56:59], v[140:143], v[148:151], v[56:59]
	v_mfma_f32_16x16x32_bf16 v[56:59], v[136:139], v[144:147], v[56:59]
	v_mfma_f32_16x16x32_bf16 v[40:43], v[136:139], v[152:155], v[40:43]
	v_mfma_f32_16x16x32_bf16 v[40:43], v[140:143], v[156:159], v[40:43]
	v_mfma_f32_16x16x32_bf16 v[48:51], v[132:135], v[156:159], v[48:51]
	v_mfma_f32_16x16x32_bf16 v[48:51], v[128:131], v[152:155], v[48:51]
	v_mfma_f32_16x16x32_bf16 v[32:35], v[128:131], v[176:179], v[32:35]
	v_mfma_f32_16x16x32_bf16 v[32:35], v[132:135], v[180:183], v[32:35]
	v_mfma_f32_16x16x32_bf16 v[24:27], v[140:143], v[180:183], v[24:27]
	v_mfma_f32_16x16x32_bf16 v[24:27], v[136:139], v[176:179], v[24:27]
	v_mfma_f32_16x16x32_bf16 v[8:11], v[136:139], v[196:199], v[8:11]
	v_mfma_f32_16x16x32_bf16 v[8:11], v[140:143], v[200:203], v[8:11]
	v_mfma_f32_16x16x32_bf16 v[16:19], v[132:135], v[200:203], v[16:19]
	v_mfma_f32_16x16x32_bf16 v[16:19], v[128:131], v[196:199], v[16:19]
	s_setprio 0
	s_barrier
	s_add_u32 s22, s22, 0x100080
	s_addc_u32 s23, s23, 0
	s_add_i32 s24, s24, s34
	s_mov_b32 m0, s24
	s_nop 0
	global_load_lds_dwordx4 v162, s[22:23]
	s_add_i32 m0, s24, 0x2000
	s_nop 0
	global_load_lds_dwordx4 v166, s[22:23]
	s_waitcnt vmcnt(6)
	s_barrier
	s_setprio 1
	v_mfma_f32_16x16x32_bf16 v[52:55], v[204:207], v[144:147], v[52:55]
	v_mfma_f32_16x16x32_bf16 v[52:55], v[208:211], v[148:151], v[52:55]
	v_mfma_f32_16x16x32_bf16 v[44:47], v[216:219], v[148:151], v[44:47]
	v_mfma_f32_16x16x32_bf16 v[44:47], v[212:215], v[144:147], v[44:47]
	v_mfma_f32_16x16x32_bf16 v[28:31], v[212:215], v[152:155], v[28:31]
	v_mfma_f32_16x16x32_bf16 v[28:31], v[216:219], v[156:159], v[28:31]
	v_mfma_f32_16x16x32_bf16 v[36:39], v[208:211], v[156:159], v[36:39]
	v_mfma_f32_16x16x32_bf16 v[36:39], v[204:207], v[152:155], v[36:39]
	v_mfma_f32_16x16x32_bf16 v[20:23], v[204:207], v[176:179], v[20:23]
	v_mfma_f32_16x16x32_bf16 v[20:23], v[208:211], v[180:183], v[20:23]
	v_mfma_f32_16x16x32_bf16 v[12:15], v[216:219], v[180:183], v[12:15]
	v_mfma_f32_16x16x32_bf16 v[12:15], v[212:215], v[176:179], v[12:15]
	v_mfma_f32_16x16x32_bf16 v[0:3], v[212:215], v[196:199], v[0:3]
	v_mfma_f32_16x16x32_bf16 v[0:3], v[216:219], v[200:203], v[0:3]
	v_mfma_f32_16x16x32_bf16 v[4:7], v[208:211], v[200:203], v[4:7]
	v_mfma_f32_16x16x32_bf16 v[4:7], v[204:207], v[196:199], v[4:7]
	s_setprio 0
	s_add_i32 s46, s46, 2
	s_add_u32 s20, s20, 0x100
	s_addc_u32 s21, s21, 0
	s_add_u32 s11, s11, 0x100
	s_addc_u32 s13, s13, 0
	s_cmp_gt_u32 s46, 61
	s_barrier
; __device__ __forceinline__ float bf_lo(unsigned w) { return __uint_as_float(w << 16); }
; __device__ __forceinline__ float bf_hi(unsigned w) { return __uint_as_float(w & 0xffff0000u); }
;     __device__ __forceinline__ void operator()(const f32x4 (&acc)[2][2][4][2], const Unit& u, int ui, int wr, int wc, int fr, int fq) const {
;         const int rl0 = wr * 64 + fr, col0 = u.pn * 256 + wc * 32 + 8 * fq;
;         u32x4 xv[2][4][2];
; #pragma unroll
;         for (int ai = 0; ai < 2; ++ai)
; #pragma unroll
;             for (int m = 0; m < 4; ++m)
; #pragma unroll
;                 for (int bj = 0; bj < 2; ++bj) xv[ai][m][bj] = *(const u32x4*)(xb + (size_t)(u.pm * 256 + rl0 + ai * 128 + m * 16) * DM + col0 + bj * 128);
; #pragma unroll
;         for (int ai = 0; ai < 2; ++ai)
; #pragma unroll
;             for (int m = 0; m < 4; ++m) { const int rl = rl0 + ai * 128 + m * 16; float* rowp = out + (size_t)(u.pm * 256 + rl) * DM + col0;
;                 const float r2 = tab[ui * 256 + rl];
; #pragma unroll
;                 for (int bj = 0; bj < 2; ++bj) { const u32x4 x = xv[ai][m][bj];
;                     const f32x4 x0 = {bf_lo(x.x), bf_hi(x.x), bf_lo(x.y), bf_hi(x.y)}, x1 = {bf_lo(x.z), bf_hi(x.z), bf_lo(x.w), bf_hi(x.w)};
;                     *(f32x4*)(rowp + bj * 128) = acc[ai][bj][m][0] * r2 + x0; *(f32x4*)(rowp + bj * 128 + 4) = acc[ai][bj][m][1] * r2 + x1; } }
	s_cbranch_scc0 .LBB0_522
	s_nop 0
	s_nop 0
	s_nop 0
	s_nop 0
	s_nop 0
	s_nop 0
	s_nop 0
	s_nop 0
	s_nop 0
	s_nop 0
	s_nop 0
	s_nop 0
	s_nop 0
	s_nop 0
	s_nop 0
	s_nop 0
	s_nop 0
	s_nop 0
	s_nop 0
	s_nop 0
	s_nop 0
	s_nop 0
	s_nop 0
	s_nop 0
	s_lshl_b32 s11, s18, 8
	v_lshl_or_b32 v128, s16, 8, v191
	v_add_u32_e32 v130, s11, v186
	v_ashrrev_i32_e32 v129, 31, v128
	v_ashrrev_i32_e32 v131, 31, v130
	v_lshl_add_u64 v[132:133], v[128:129], 1, s[6:7]
	v_lshlrev_b64 v[134:135], 11, v[130:131]
	v_lshl_add_u64 v[134:135], v[132:133], 0, v[134:135]
	global_load_dwordx4 v[198:201], v[134:135], off
	global_load_dwordx4 v[202:205], v[134:135], off offset:256
	v_or_b32_e32 v134, 16, v130
	v_ashrrev_i32_e32 v135, 31, v134
	v_lshlrev_b64 v[134:135], 11, v[134:135]
	v_lshl_add_u64 v[134:135], v[132:133], 0, v[134:135]
	global_load_dwordx4 v[206:209], v[134:135], off
	global_load_dwordx4 v[210:213], v[134:135], off offset:256
	v_or_b32_e32 v136, 32, v130
	v_ashrrev_i32_e32 v137, 31, v136
	v_or_b32_e32 v138, 48, v130
	v_add_u32_e32 v184, 0x80, v130
	v_add_u32_e32 v182, 0x90, v130
	v_add_u32_e32 v180, 0xa0, v130
	v_add_u32_e32 v178, 0xb0, v130
	v_lshlrev_b64 v[176:177], 2, v[128:129]
	v_lshlrev_b64 v[128:129], 12, v[130:131]
	v_lshlrev_b64 v[130:131], 11, v[136:137]
	v_lshl_add_u64 v[130:131], v[132:133], 0, v[130:131]
	global_load_dwordx4 v[214:217], v[130:131], off
	v_ashrrev_i32_e32 v139, 31, v138
	v_ashrrev_i32_e32 v185, 31, v184
	v_ashrrev_i32_e32 v183, 31, v182
	v_ashrrev_i32_e32 v181, 31, v180
	v_ashrrev_i32_e32 v179, 31, v178
	v_lshlrev_b64 v[134:135], 11, v[138:139]
	v_lshlrev_b64 v[136:137], 11, v[184:185]
	v_lshlrev_b64 v[138:139], 11, v[182:183]
	v_lshl_add_u32 v196, s45, 10, v192
	v_lshlrev_b64 v[140:141], 11, v[180:181]
	v_lshlrev_b64 v[142:143], 11, v[178:179]
	v_lshl_add_u64 v[128:129], s[26:27], 0, v[128:129]
	v_lshl_add_u64 v[134:135], v[132:133], 0, v[134:135]
	v_lshl_add_u64 v[136:137], v[132:133], 0, v[136:137]
	v_lshl_add_u64 v[138:139], v[132:133], 0, v[138:139]
	ds_read2_b32 v[230:231], v196 offset1:16
	v_lshl_add_u64 v[234:235], v[132:133], 0, v[140:141]
	v_lshl_add_u64 v[236:237], v[132:133], 0, v[142:143]
	v_lshl_add_u64 v[238:239], v[128:129], 0, v[176:177]
	global_load_dwordx4 v[218:221], v[130:131], off offset:256
	global_load_dwordx4 v[222:225], v[134:135], off
	global_load_dwordx4 v[226:229], v[134:135], off offset:256
	global_load_dwordx4 v[156:159], v[136:137], off
	global_load_dwordx4 v[152:155], v[136:137], off offset:256
	global_load_dwordx4 v[148:151], v[138:139], off
	global_load_dwordx4 v[144:147], v[138:139], off offset:256
	global_load_dwordx4 v[140:143], v[234:235], off
	s_nop 0
	global_load_dwordx4 v[136:139], v[234:235], off offset:256
	global_load_dwordx4 v[132:135], v[236:237], off
	global_load_dwordx4 v[128:131], v[236:237], off offset:256
	v_add_u32_e32 v232, s11, v188
	v_ashrrev_i32_e32 v233, 31, v232
	s_and_b64 vcc, exec, s[0:1]
	s_mov_b32 s16, s10
	s_mov_b32 s18, s12
	s_mov_b64 s[20:21], s[4:5]
	s_mov_b64 s[22:23], s[14:15]
	s_mov_b32 s45, s44
	s_waitcnt vmcnt(0)
	v_lshlrev_b32_e32 v234, 16, v198
	v_and_b32_e32 v235, 0xffff0000, v198
	v_lshlrev_b32_e32 v198, 16, v199
	v_and_b32_e32 v199, 0xffff0000, v199
	v_lshlrev_b32_e32 v242, 16, v204
	v_and_b32_e32 v243, 0xffff0000, v204
	v_lshlrev_b32_e32 v236, 16, v200
	v_and_b32_e32 v237, 0xffff0000, v200
	v_lshlrev_b32_e32 v200, 16, v201
	v_and_b32_e32 v201, 0xffff0000, v201
	v_lshlrev_b32_e32 v240, 16, v202
	v_and_b32_e32 v241, 0xffff0000, v202
	v_lshlrev_b32_e32 v202, 16, v203
	v_and_b32_e32 v203, 0xffff0000, v203
	v_lshlrev_b32_e32 v204, 16, v205
	v_and_b32_e32 v205, 0xffff0000, v205
	s_waitcnt lgkmcnt(0)
	v_pk_fma_f32 v[126:127], v[126:127], v[230:231], v[198:199] op_sel_hi:[1,0,1]
	v_pk_fma_f32 v[124:125], v[124:125], v[230:231], v[234:235] op_sel_hi:[1,0,1]
	v_pk_fma_f32 v[108:109], v[108:109], v[230:231], v[242:243] op_sel_hi:[1,0,1]
	v_pk_fma_f32 v[122:123], v[122:123], v[230:231], v[200:201] op_sel_hi:[1,0,1]
	v_pk_fma_f32 v[120:121], v[120:121], v[230:231], v[236:237] op_sel_hi:[1,0,1]
	v_pk_fma_f32 v[118:119], v[118:119], v[230:231], v[202:203] op_sel_hi:[1,0,1]
	v_pk_fma_f32 v[116:117], v[116:117], v[230:231], v[240:241] op_sel_hi:[1,0,1]
	v_pk_fma_f32 v[110:111], v[110:111], v[230:231], v[204:205] op_sel_hi:[1,0,1]
	global_store_dwordx4 v[238:239], v[124:127], off
	global_store_dwordx4 v[238:239], v[120:123], off offset:16
	global_store_dwordx4 v[238:239], v[116:119], off offset:512
	global_store_dwordx4 v[238:239], v[108:111], off offset:528
	v_mov_b32_e32 v122, v231
	v_lshlrev_b32_e32 v118, 16, v208
	v_lshlrev_b64 v[108:109], 12, v[232:233]
	v_lshl_add_u64 v[108:109], s[26:27], 0, v[108:109]
	v_lshl_add_u64 v[116:117], v[108:109], 0, v[176:177]
	v_lshlrev_b32_e32 v108, 16, v206
	v_and_b32_e32 v109, 0xffff0000, v206
	v_lshlrev_b32_e32 v110, 16, v207
	v_and_b32_e32 v111, 0xffff0000, v207
	v_pk_fma_f32 v[110:111], v[114:115], v[122:123], v[110:111] op_sel_hi:[1,0,1]
	v_pk_fma_f32 v[108:109], v[112:113], v[122:123], v[108:109] op_sel_hi:[1,0,1]
	global_store_dwordx4 v[116:117], v[108:111], off
	v_and_b32_e32 v119, 0xffff0000, v208
	v_lshlrev_b32_e32 v120, 16, v209
	v_lshlrev_b32_e32 v108, 16, v212
	v_and_b32_e32 v109, 0xffff0000, v212
	v_lshlrev_b32_e32 v110, 16, v213
	v_and_b32_e32 v111, 0xffff0000, v213
	v_pk_fma_f32 v[98:99], v[98:99], v[122:123], v[110:111] op_sel_hi:[1,0,1]
	v_pk_fma_f32 v[96:97], v[96:97], v[122:123], v[108:109] op_sel_hi:[1,0,1]
	v_and_b32_e32 v121, 0xffff0000, v209
	global_store_dwordx4 v[116:117], v[96:99], off offset:528
	ds_read2_b32 v[98:99], v196 offset0:32 offset1:48
	v_pk_fma_f32 v[106:107], v[106:107], v[122:123], v[120:121] op_sel_hi:[1,0,1]
	v_pk_fma_f32 v[104:105], v[104:105], v[122:123], v[118:119] op_sel_hi:[1,0,1]
	v_add_u32_e32 v96, s11, v189
	global_store_dwordx4 v[116:117], v[104:107], off offset:16
	v_ashrrev_i32_e32 v97, 31, v96
	v_lshlrev_b64 v[96:97], 12, v[96:97]
	v_lshlrev_b32_e32 v104, 16, v210
	v_and_b32_e32 v105, 0xffff0000, v210
	v_lshlrev_b32_e32 v106, 16, v211
	v_and_b32_e32 v107, 0xffff0000, v211
	v_pk_fma_f32 v[102:103], v[102:103], v[122:123], v[106:107] op_sel_hi:[1,0,1]
	v_pk_fma_f32 v[100:101], v[100:101], v[122:123], v[104:105] op_sel_hi:[1,0,1]
	global_store_dwordx4 v[116:117], v[100:103], off offset:512
	v_lshl_add_u64 v[96:97], s[26:27], 0, v[96:97]
	v_lshl_add_u64 v[96:97], v[96:97], 0, v[176:177]
	v_lshlrev_b32_e32 v100, 16, v214
	v_and_b32_e32 v101, 0xffff0000, v214
	v_lshlrev_b32_e32 v102, 16, v215
	v_and_b32_e32 v103, 0xffff0000, v215
	s_waitcnt lgkmcnt(0)
; __device__ __forceinline__ float bf_lo(unsigned w) { return __uint_as_float(w << 16); }
; __device__ __forceinline__ float bf_hi(unsigned w) { return __uint_as_float(w & 0xffff0000u); }
;     __device__ __forceinline__ void operator()(const f32x4 (&acc)[2][2][4][2], const Unit& u, int ui, int wr, int wc, int fr, int fq) const {
;     ...
;         for (int ai = 0; ai < 2; ++ai)
; #pragma unroll
;             for (int m = 0; m < 4; ++m) { const int rl = rl0 + ai * 128 + m * 16; float* rowp = out + (size_t)(u.pm * 256 + rl) * DM + col0;
;                 const float r2 = tab[ui * 256 + rl];
; #pragma unroll
;                 for (int bj = 0; bj < 2; ++bj) { const u32x4 x = xv[ai][m][bj];
;                     const f32x4 x0 = {bf_lo(x.x), bf_hi(x.x), bf_lo(x.y), bf_hi(x.y)}, x1 = {bf_lo(x.z), bf_hi(x.z), bf_lo(x.w), bf_hi(x.w)};
;                     *(f32x4*)(rowp + bj * 128) = acc[ai][bj][m][0] * r2 + x0; *(f32x4*)(rowp + bj * 128 + 4) = acc[ai][bj][m][1] * r2 + x1; } }
	v_pk_fma_f32 v[94:95], v[94:95], v[98:99], v[102:103] op_sel_hi:[1,0,1]
	v_pk_fma_f32 v[92:93], v[92:93], v[98:99], v[100:101] op_sel_hi:[1,0,1]
	global_store_dwordx4 v[96:97], v[92:95], off
	v_lshlrev_b32_e32 v104, 16, v216
	v_and_b32_e32 v105, 0xffff0000, v216
	v_lshlrev_b32_e32 v92, 16, v220
	v_and_b32_e32 v93, 0xffff0000, v220
	v_lshlrev_b32_e32 v94, 16, v221
	v_and_b32_e32 v95, 0xffff0000, v221
	v_lshlrev_b32_e32 v106, 16, v217
	v_and_b32_e32 v107, 0xffff0000, v217
	v_pk_fma_f32 v[82:83], v[82:83], v[98:99], v[94:95] op_sel_hi:[1,0,1]
	v_pk_fma_f32 v[80:81], v[80:81], v[98:99], v[92:93] op_sel_hi:[1,0,1]
	v_pk_fma_f32 v[90:91], v[90:91], v[98:99], v[106:107] op_sel_hi:[1,0,1]
	v_pk_fma_f32 v[88:89], v[88:89], v[98:99], v[104:105] op_sel_hi:[1,0,1]
	global_store_dwordx4 v[96:97], v[80:83], off offset:528
	global_store_dwordx4 v[96:97], v[88:91], off offset:16
	s_nop 0
	v_add_u32_e32 v80, s11, v190
	v_lshlrev_b32_e32 v88, 16, v218
	v_and_b32_e32 v89, 0xffff0000, v218
	v_lshlrev_b32_e32 v90, 16, v219
	v_and_b32_e32 v91, 0xffff0000, v219
	v_ashrrev_i32_e32 v81, 31, v80
	v_pk_fma_f32 v[86:87], v[86:87], v[98:99], v[90:91] op_sel_hi:[1,0,1]
	v_pk_fma_f32 v[84:85], v[84:85], v[98:99], v[88:89] op_sel_hi:[1,0,1]
	v_lshlrev_b64 v[80:81], 12, v[80:81]
	global_store_dwordx4 v[96:97], v[84:87], off offset:512
	v_lshl_add_u64 v[80:81], s[26:27], 0, v[80:81]
	v_lshlrev_b32_e32 v82, 16, v222
	v_and_b32_e32 v83, 0xffff0000, v222
	v_lshlrev_b32_e32 v84, 16, v223
	v_and_b32_e32 v85, 0xffff0000, v223
	v_mov_b32_e32 v90, v99
	v_lshl_add_u64 v[80:81], v[80:81], 0, v[176:177]
	v_pk_fma_f32 v[78:79], v[78:79], v[90:91], v[84:85] op_sel_hi:[1,0,1]
	v_pk_fma_f32 v[76:77], v[76:77], v[90:91], v[82:83] op_sel_hi:[1,0,1]
	global_store_dwordx4 v[80:81], v[76:79], off
	v_lshlrev_b32_e32 v86, 16, v224
	v_and_b32_e32 v87, 0xffff0000, v224
	v_lshlrev_b32_e32 v76, 16, v228
	v_and_b32_e32 v77, 0xffff0000, v228
	v_lshlrev_b32_e32 v78, 16, v229
	v_and_b32_e32 v79, 0xffff0000, v229
	v_pk_fma_f32 v[66:67], v[66:67], v[90:91], v[78:79] op_sel_hi:[1,0,1]
	v_pk_fma_f32 v[64:65], v[64:65], v[90:91], v[76:77] op_sel_hi:[1,0,1]
	v_lshlrev_b32_e32 v88, 16, v225
	v_and_b32_e32 v89, 0xffff0000, v225
	global_store_dwordx4 v[80:81], v[64:67], off offset:528
	ds_read2_b32 v[66:67], v196 offset0:128 offset1:144
	v_pk_fma_f32 v[74:75], v[74:75], v[90:91], v[88:89] op_sel_hi:[1,0,1]
	v_pk_fma_f32 v[72:73], v[72:73], v[90:91], v[86:87] op_sel_hi:[1,0,1]
	global_store_dwordx4 v[80:81], v[72:75], off offset:16
	v_lshlrev_b64 v[64:65], 12, v[184:185]
	v_lshl_add_u64 v[64:65], s[26:27], 0, v[64:65]
	v_lshlrev_b32_e32 v72, 16, v226
	v_and_b32_e32 v73, 0xffff0000, v226
	v_lshlrev_b32_e32 v74, 16, v227
	v_and_b32_e32 v75, 0xffff0000, v227
	v_pk_fma_f32 v[70:71], v[70:71], v[90:91], v[74:75] op_sel_hi:[1,0,1]
	v_pk_fma_f32 v[68:69], v[68:69], v[90:91], v[72:73] op_sel_hi:[1,0,1]
	global_store_dwordx4 v[80:81], v[68:71], off offset:512
	v_lshl_add_u64 v[64:65], v[64:65], 0, v[176:177]
	v_lshlrev_b32_e32 v72, 16, v158
	v_lshlrev_b32_e32 v68, 16, v156
	v_and_b32_e32 v69, 0xffff0000, v156
	v_lshlrev_b32_e32 v70, 16, v157
	v_and_b32_e32 v71, 0xffff0000, v157
	v_and_b32_e32 v73, 0xffff0000, v158
	v_lshlrev_b32_e32 v74, 16, v159
	v_and_b32_e32 v75, 0xffff0000, v159
	s_waitcnt lgkmcnt(0)
; __device__ __forceinline__ float bf_lo(unsigned w) { return __uint_as_float(w << 16); }
; __device__ __forceinline__ float bf_hi(unsigned w) { return __uint_as_float(w & 0xffff0000u); }
; #define PG8_WAIT_V(n) asm volatile("s_waitcnt vmcnt(" #n ")" ::: "memory")
; #define PG8_BAR __builtin_amdgcn_s_barrier()
; template <class Epi, class Ptrs>
; __device__ __forceinline__ void gemm_phase(LAS unsigned char* lds, const int K, const StaticOrder& S, const Ptrs& P, const Epi& E) {
;     ...
;     PG8_WAIT_V(0);
;     if (wr == 0) PG8_BAR;
;     PG8_BAR;
;     __device__ __forceinline__ void operator()(const f32x4 (&acc)[2][2][4][2], const Unit& u, int ui, int wr, int wc, int fr, int fq) const {
;     ...
;         for (int ai = 0; ai < 2; ++ai)
; #pragma unroll
;             for (int m = 0; m < 4; ++m) { const int rl = rl0 + ai * 128 + m * 16; float* rowp = out + (size_t)(u.pm * 256 + rl) * DM + col0;
;                 const float r2 = tab[ui * 256 + rl];
; #pragma unroll
;                 for (int bj = 0; bj < 2; ++bj) { const u32x4 x = xv[ai][m][bj];
;                     const f32x4 x0 = {bf_lo(x.x), bf_hi(x.x), bf_lo(x.y), bf_hi(x.y)}, x1 = {bf_lo(x.z), bf_hi(x.z), bf_lo(x.w), bf_hi(x.w)};
;                     *(f32x4*)(rowp + bj * 128) = acc[ai][bj][m][0] * r2 + x0; *(f32x4*)(rowp + bj * 128 + 4) = acc[ai][bj][m][1] * r2 + x1; } }
	v_pk_fma_f32 v[62:63], v[62:63], v[66:67], v[70:71] op_sel_hi:[1,0,1]
	v_pk_fma_f32 v[60:61], v[60:61], v[66:67], v[68:69] op_sel_hi:[1,0,1]
	global_store_dwordx4 v[64:65], v[60:63], off
	v_pk_fma_f32 v[58:59], v[58:59], v[66:67], v[74:75] op_sel_hi:[1,0,1]
	v_pk_fma_f32 v[56:57], v[56:57], v[66:67], v[72:73] op_sel_hi:[1,0,1]
	v_lshlrev_b32_e32 v60, 16, v154
	v_and_b32_e32 v61, 0xffff0000, v154
	v_lshlrev_b32_e32 v62, 16, v155
	v_and_b32_e32 v63, 0xffff0000, v155
	global_store_dwordx4 v[64:65], v[56:59], off offset:16
	v_pk_fma_f32 v[46:47], v[46:47], v[66:67], v[62:63] op_sel_hi:[1,0,1]
	v_pk_fma_f32 v[44:45], v[44:45], v[66:67], v[60:61] op_sel_hi:[1,0,1]
	v_lshlrev_b32_e32 v56, 16, v152
	v_and_b32_e32 v57, 0xffff0000, v152
	v_lshlrev_b32_e32 v58, 16, v153
	v_and_b32_e32 v59, 0xffff0000, v153
	v_pk_fma_f32 v[54:55], v[54:55], v[66:67], v[58:59] op_sel_hi:[1,0,1]
	v_pk_fma_f32 v[52:53], v[52:53], v[66:67], v[56:57] op_sel_hi:[1,0,1]
	global_store_dwordx4 v[64:65], v[44:47], off offset:528
	global_store_dwordx4 v[64:65], v[52:55], off offset:512
	v_lshlrev_b32_e32 v56, 16, v151
	v_lshlrev_b64 v[44:45], 12, v[182:183]
	v_lshl_add_u64 v[44:45], s[26:27], 0, v[44:45]
	v_lshlrev_b32_e32 v54, 16, v150
	v_and_b32_e32 v55, 0xffff0000, v150
	v_and_b32_e32 v57, 0xffff0000, v151
	v_mov_b32_e32 v58, v67
	v_lshl_add_u64 v[52:53], v[44:45], 0, v[176:177]
	v_pk_fma_f32 v[42:43], v[42:43], v[58:59], v[56:57] op_sel_hi:[1,0,1]
	v_pk_fma_f32 v[40:41], v[40:41], v[58:59], v[54:55] op_sel_hi:[1,0,1]
	v_lshlrev_b32_e32 v44, 16, v148
	v_and_b32_e32 v45, 0xffff0000, v148
	v_lshlrev_b32_e32 v46, 16, v149
	v_and_b32_e32 v47, 0xffff0000, v149
	global_store_dwordx4 v[52:53], v[40:43], off offset:16
	v_pk_fma_f32 v[46:47], v[50:51], v[58:59], v[46:47] op_sel_hi:[1,0,1]
	v_pk_fma_f32 v[44:45], v[48:49], v[58:59], v[44:45] op_sel_hi:[1,0,1]
	v_lshlrev_b32_e32 v40, 16, v144
	v_and_b32_e32 v41, 0xffff0000, v144
	v_lshlrev_b32_e32 v42, 16, v145
	v_and_b32_e32 v43, 0xffff0000, v145
	v_pk_fma_f32 v[38:39], v[38:39], v[58:59], v[42:43] op_sel_hi:[1,0,1]
	v_pk_fma_f32 v[36:37], v[36:37], v[58:59], v[40:41] op_sel_hi:[1,0,1]
	global_store_dwordx4 v[52:53], v[44:47], off
	global_store_dwordx4 v[52:53], v[36:39], off offset:512
	ds_read2_b32 v[38:39], v196 offset0:160 offset1:176
	v_lshlrev_b32_e32 v44, 16, v146
	v_and_b32_e32 v45, 0xffff0000, v146
	v_lshlrev_b32_e32 v46, 16, v147
	v_and_b32_e32 v47, 0xffff0000, v147
	v_pk_fma_f32 v[30:31], v[30:31], v[58:59], v[46:47] op_sel_hi:[1,0,1]
	v_pk_fma_f32 v[28:29], v[28:29], v[58:59], v[44:45] op_sel_hi:[1,0,1]
	global_store_dwordx4 v[52:53], v[28:31], off offset:528
	v_lshlrev_b32_e32 v40, 16, v142
	v_and_b32_e32 v41, 0xffff0000, v142
	v_lshlrev_b64 v[28:29], 12, v[180:181]
	v_lshl_add_u64 v[28:29], s[26:27], 0, v[28:29]
	v_lshl_add_u64 v[36:37], v[28:29], 0, v[176:177]
	v_lshlrev_b32_e32 v28, 16, v140
	v_and_b32_e32 v29, 0xffff0000, v140
	v_lshlrev_b32_e32 v30, 16, v141
	v_and_b32_e32 v31, 0xffff0000, v141
	s_waitcnt lgkmcnt(0)
	v_pk_fma_f32 v[30:31], v[34:35], v[38:39], v[30:31] op_sel_hi:[1,0,1]
	v_pk_fma_f32 v[28:29], v[32:33], v[38:39], v[28:29] op_sel_hi:[1,0,1]
	v_lshlrev_b32_e32 v42, 16, v143
	v_and_b32_e32 v43, 0xffff0000, v143
	global_store_dwordx4 v[36:37], v[28:31], off
	v_pk_fma_f32 v[26:27], v[26:27], v[38:39], v[42:43] op_sel_hi:[1,0,1]
	v_pk_fma_f32 v[24:25], v[24:25], v[38:39], v[40:41] op_sel_hi:[1,0,1]
	v_lshlrev_b32_e32 v28, 16, v138
	v_and_b32_e32 v29, 0xffff0000, v138
	v_lshlrev_b32_e32 v30, 16, v139
	v_and_b32_e32 v31, 0xffff0000, v139
	v_pk_fma_f32 v[14:15], v[14:15], v[38:39], v[30:31] op_sel_hi:[1,0,1]
	v_pk_fma_f32 v[12:13], v[12:13], v[38:39], v[28:29] op_sel_hi:[1,0,1]
	global_store_dwordx4 v[36:37], v[24:27], off offset:16
	global_store_dwordx4 v[36:37], v[12:15], off offset:528
	s_nop 0
	v_lshlrev_b32_e32 v24, 16, v136
	v_and_b32_e32 v25, 0xffff0000, v136
	v_lshlrev_b32_e32 v26, 16, v137
	v_and_b32_e32 v27, 0xffff0000, v137
	v_lshlrev_b64 v[12:13], 12, v[178:179]
	v_pk_fma_f32 v[22:23], v[22:23], v[38:39], v[26:27] op_sel_hi:[1,0,1]
	v_pk_fma_f32 v[20:21], v[20:21], v[38:39], v[24:25] op_sel_hi:[1,0,1]
	v_lshl_add_u64 v[12:13], s[26:27], 0, v[12:13]
	global_store_dwordx4 v[36:37], v[20:23], off offset:512
	v_lshlrev_b32_e32 v14, 16, v133
	v_and_b32_e32 v15, 0xffff0000, v133
	v_lshl_add_u64 v[20:21], v[12:13], 0, v[176:177]
	v_lshlrev_b32_e32 v12, 16, v132
	v_and_b32_e32 v13, 0xffff0000, v132
	v_lshlrev_b32_e32 v22, 16, v134
	v_and_b32_e32 v23, 0xffff0000, v134
	v_lshlrev_b32_e32 v24, 16, v135
	v_and_b32_e32 v25, 0xffff0000, v135
	v_mov_b32_e32 v26, v39
	v_pk_fma_f32 v[14:15], v[18:19], v[26:27], v[14:15] op_sel_hi:[1,0,1]
	v_pk_fma_f32 v[12:13], v[16:17], v[26:27], v[12:13] op_sel_hi:[1,0,1]
	v_pk_fma_f32 v[10:11], v[10:11], v[26:27], v[24:25] op_sel_hi:[1,0,1]
	v_pk_fma_f32 v[8:9], v[8:9], v[26:27], v[22:23] op_sel_hi:[1,0,1]
	global_store_dwordx4 v[20:21], v[12:15], off
	global_store_dwordx4 v[20:21], v[8:11], off offset:16
	s_nop 0
	v_lshlrev_b32_e32 v12, 16, v130
	v_lshlrev_b32_e32 v8, 16, v128
	v_and_b32_e32 v9, 0xffff0000, v128
	v_lshlrev_b32_e32 v10, 16, v129
	v_and_b32_e32 v11, 0xffff0000, v129
	v_and_b32_e32 v13, 0xffff0000, v130
	v_lshlrev_b32_e32 v14, 16, v131
	v_and_b32_e32 v15, 0xffff0000, v131
	v_pk_fma_f32 v[6:7], v[6:7], v[26:27], v[10:11] op_sel_hi:[1,0,1]
	v_pk_fma_f32 v[4:5], v[4:5], v[26:27], v[8:9] op_sel_hi:[1,0,1]
	v_pk_fma_f32 v[2:3], v[2:3], v[26:27], v[14:15] op_sel_hi:[1,0,1]
	v_pk_fma_f32 v[0:1], v[0:1], v[26:27], v[12:13] op_sel_hi:[1,0,1]
	global_store_dwordx4 v[20:21], v[4:7], off offset:512
	global_store_dwordx4 v[20:21], v[0:3], off offset:528
	s_cbranch_vccz .LBB0_517
	s_waitcnt vmcnt(0)
	s_cmpk_gt_u32 s33, 0xff
	s_cbranch_scc1 .LBB0_526
	s_barrier
